# attention output epilogues (FoX, SWA, MLA): lane^1/lane^2 exchanges via DPP quad_perm instead of ds_bpermute; plus v22 epilogue rsq/preload
# speedup vs baseline: 1.0162x; 1.0019x over previous
; #define SBAR() __builtin_amdgcn_sched_barrier(0)
; __device__ __forceinline__ int crow(int r, int hi) { return (r & 3) + 8 * (r >> 2) + 4 * hi; }
; #define SEAM_K0() do { VMWN(NQR); if constexpr (C::F8QK) { const int nb_ = ((NT & 1) == 0) ? NX3(bq) : bq; char* kb_ = KB3(nb_);     \
;                            *(bf16x8*)(kb_ + kr * K8P + kc * 16) = S.st_k0; if (kr < 32) *(bf16x8*)(kb_ + (2 * kr + (kc >> 2)) * K8P + 128 + (kc & 3) * 16) = S.st_kp; S.b0 = nb_; }  \
;                        else SWRITE_HK(0); SBAR(); } while (0)
; template <int MODE>
; __device__ __forceinline__ void attn_block(const AttnArgs& a, const BlockRef& cur, const BlockRef& nxt, char* lds, Seam<MODE>& S, const int tid) {
;     ...
;     SBAR(); SEAM_K0();
;     if constexpr (NQR < NQ) {
; #pragma unroll
;         for (int d0 = NQR; d0 < NQ; ++d0) S.qr[d0] = load8(a.Q + (size_t)(nq_ + wid * QBLK + r32) * C::DK + d0 * 16 + hi * 8);
;         SBAR(); }
;     if (hi == 0) li_l[r32] = l_reg; asm volatile("s_waitcnt lgkmcnt(0)" ::: "memory");
;     float rli[16];
; #pragma unroll
;     for (int r = 0; r < 16; ++r) rli[r] = __builtin_amdgcn_rcpf(li_l[crow(r, hi)]) * (C::F8PV ? 0.125f : 1.0f);
;     int orow_ = cur.orow, hcol_ = cur.hcol; asm volatile("" : "+s"(orow_), "+s"(hcol_));
;     if (a.o8 != 0.f) {
;         unsigned char* Ob = (unsigned char*)a.O + (size_t)(orow_ + wid * QBLK) * ldo + hcol_; const float os = a.o8;
; #pragma unroll
;         for (int r = 0; r < 16; ++r) { const int orow = crow(r, hi);
; #pragma unroll
;             for (int d0 = 0; d0 < 4; ++d0) { const float v = __builtin_amdgcn_fmed3f(o[d0][r] * rli[r] * os, -448.f, 448.f);
;                 const float vn = __shfl_xor(v, 1);
;                 const int pk = __builtin_amdgcn_cvt_pk_fp8_f32(v, vn, 0, false) & 0xffff; const int pk2 = __shfl_xor(pk, 2);
;                 if ((r32 & 3) == 0) *(unsigned*)(Ob + (size_t)orow * ldo + d0 * 32 + r32) = (unsigned)pk | ((unsigned)pk2 << 16); } }
.LBB0_3283:
	v_lshlrev_b32_e32 v3, 8, v3
	v_bitop3_b32 v0, v0, v2, s68 bitop3:0x78
	s_waitcnt vmcnt(8)
	v_add3_u32 v0, 0, v3, v0
	s_waitcnt vmcnt(9)
	ds_write_b128 v0, v[112:115] offset:32768
	s_waitcnt vmcnt(8)
	ds_write_b128 v0, v[116:119] offset:40960
	v_cmp_gt_u32_e32 vcc, 32, v178
	s_and_saveexec_b64 s[6:7], vcc
	v_lshl_add_u32 v0, v128, 2, s60
	ds_write_b32 v0, v4
	s_or_b64 exec, exec, s[6:7]
	s_waitcnt lgkmcnt(0)
	v_lshl_add_u32 v0, v14, 2, s60
	ds_read_b128 v[80:83], v0
	ds_read_b128 v[10:13], v0 offset:32
	ds_read_b128 v[6:9], v0 offset:64
	ds_read_b128 v[2:5], v0 offset:96
	v_mov_b32_e32 v84, v1
	s_waitcnt lgkmcnt(3)
	v_rcp_f32_e32 v0, v80
	s_add_i32 s6, s79, s80
	s_ashr_i32 s7, s6, 31
	v_mul_f32_e32 v15, v64, v0
	v_mul_f32_e32 v15, 0x41800000, v15
	v_med3_f32 v64, v15, s72, v224
	s_nop 1
	v_mov_b32_dpp v80, v64 quad_perm:[1,0,3,2] row_mask:0xf bank_mask:0xf
	s_lshl_b64 s[6:7], s[6:7], 11
	s_ashr_i32 s50, s78, 31
	s_add_u32 s6, s64, s6
	s_addc_u32 s7, s65, s7
	s_waitcnt lgkmcnt(0)
	v_cvt_pk_fp8_f32 v84, v64, v80
	s_add_u32 s6, s6, s78
	v_mov_b32_e32 v129, v1
	v_ashrrev_i32_e32 v15, 31, v14
	v_and_b32_e32 v64, 0xffff, v84
	s_nop 1
	v_mov_b32_dpp v80, v64 quad_perm:[2,3,0,1] row_mask:0xf bank_mask:0xf
	s_addc_u32 s7, s7, s50
	v_and_b32_e32 v84, 3, v178
	v_lshlrev_b64 v[86:87], 11, v[14:15]
	v_cmp_eq_u32_e32 vcc, 0, v84
	v_lshl_add_u64 v[84:85], s[6:7], 0, v[128:129]
	v_lshl_add_u64 v[86:87], v[84:85], 0, v[86:87]
	s_and_saveexec_b64 s[6:7], vcc
	s_cbranch_execz .LBB0_3287
	s_waitcnt lgkmcnt(0)
	v_lshl_or_b32 v64, v80, 16, v64
	global_store_dword v[86:87], v64, off
.LBB0_3287:
	s_or_b64 exec, exec, s[6:7]
	v_mul_f32_e32 v48, v48, v0
	v_mul_f32_e32 v48, 0x41800000, v48
	v_med3_f32 v48, v48, s72, v224
	s_nop 1
	v_mov_b32_dpp v64, v48 quad_perm:[1,0,3,2] row_mask:0xf bank_mask:0xf
	s_waitcnt lgkmcnt(1)
	v_mov_b32_e32 v80, v1
	s_waitcnt lgkmcnt(0)
	v_cvt_pk_fp8_f32 v80, v48, v64
	v_and_b32_e32 v48, 0xffff, v80
	s_nop 1
	v_mov_b32_dpp v64, v48 quad_perm:[2,3,0,1] row_mask:0xf bank_mask:0xf
	s_and_saveexec_b64 s[6:7], vcc
	s_cbranch_execz .LBB0_3289
	s_waitcnt lgkmcnt(0)
	v_lshl_or_b32 v48, v64, 16, v48
	global_store_dword v[86:87], v48, off offset:32
.LBB0_3289:
	s_or_b64 exec, exec, s[6:7]
	v_mul_f32_e32 v32, v32, v0
	v_mul_f32_e32 v32, 0x41800000, v32
	v_med3_f32 v32, v32, s72, v224
	s_nop 1
	v_mov_b32_dpp v48, v32 quad_perm:[1,0,3,2] row_mask:0xf bank_mask:0xf
	s_waitcnt lgkmcnt(1)
	v_mov_b32_e32 v64, v1
	s_waitcnt lgkmcnt(0)
	v_cvt_pk_fp8_f32 v64, v32, v48
	v_and_b32_e32 v32, 0xffff, v64
	s_nop 1
	v_mov_b32_dpp v48, v32 quad_perm:[2,3,0,1] row_mask:0xf bank_mask:0xf
	s_and_saveexec_b64 s[6:7], vcc
	s_cbranch_execz .LBB0_3291
	s_waitcnt lgkmcnt(0)
	v_lshl_or_b32 v32, v48, 16, v32
	global_store_dword v[86:87], v32, off offset:64
.LBB0_3291:
	s_or_b64 exec, exec, s[6:7]
	v_mul_f32_e32 v0, v16, v0
	v_mul_f32_e32 v0, 0x41800000, v0
	v_med3_f32 v0, v0, s72, v224
	s_nop 1
	v_mov_b32_dpp v16, v0 quad_perm:[1,0,3,2] row_mask:0xf bank_mask:0xf
	v_mov_b32_e32 v32, v1
	s_waitcnt lgkmcnt(0)
	v_cvt_pk_fp8_f32 v32, v0, v16
	v_and_b32_e32 v0, 0xffff, v32
	s_nop 1
	v_mov_b32_dpp v16, v0 quad_perm:[2,3,0,1] row_mask:0xf bank_mask:0xf
	s_and_saveexec_b64 s[6:7], vcc
	s_cbranch_execz .LBB0_3293
	s_waitcnt lgkmcnt(0)
	v_lshl_or_b32 v0, v16, 16, v0
	global_store_dword v[86:87], v0, off offset:96
.LBB0_3293:
	s_or_b64 exec, exec, s[6:7]
	v_rcp_f32_e32 v0, v81
	v_mov_b32_e32 v48, v1
	v_or_b32_e32 v64, 1, v14
	s_waitcnt lgkmcnt(0)
	v_mul_f32_e32 v16, v65, v0
	v_mul_f32_e32 v16, 0x41800000, v16
	v_med3_f32 v16, v16, s72, v224
	s_nop 1
	v_mov_b32_dpp v32, v16 quad_perm:[1,0,3,2] row_mask:0xf bank_mask:0xf
	v_ashrrev_i32_e32 v65, 31, v64
	v_lshlrev_b64 v[64:65], 11, v[64:65]
	v_lshl_add_u64 v[64:65], v[84:85], 0, v[64:65]
	s_waitcnt lgkmcnt(0)
	v_cvt_pk_fp8_f32 v48, v16, v32
	v_and_b32_e32 v16, 0xffff, v48
	s_nop 1
	v_mov_b32_dpp v32, v16 quad_perm:[2,3,0,1] row_mask:0xf bank_mask:0xf
	s_and_saveexec_b64 s[6:7], vcc
	s_cbranch_execz .LBB0_3295
	s_waitcnt lgkmcnt(0)
	v_lshl_or_b32 v16, v32, 16, v16
	global_store_dword v[64:65], v16, off
.LBB0_3295:
	s_or_b64 exec, exec, s[6:7]
	v_mul_f32_e32 v16, v49, v0
	v_mul_f32_e32 v16, 0x41800000, v16
	v_med3_f32 v16, v16, s72, v224
	s_waitcnt lgkmcnt(0)
	s_nop 1
	v_mov_b32_dpp v32, v16 quad_perm:[1,0,3,2] row_mask:0xf bank_mask:0xf
	v_mov_b32_e32 v48, v1
	s_waitcnt lgkmcnt(0)
	v_cvt_pk_fp8_f32 v48, v16, v32
	v_and_b32_e32 v16, 0xffff, v48
	s_nop 1
	v_mov_b32_dpp v32, v16 quad_perm:[2,3,0,1] row_mask:0xf bank_mask:0xf
	s_and_saveexec_b64 s[6:7], vcc
	s_cbranch_execz .LBB0_3297
	s_waitcnt lgkmcnt(0)
	v_lshl_or_b32 v16, v32, 16, v16
	global_store_dword v[64:65], v16, off offset:32
.LBB0_3297:
	s_or_b64 exec, exec, s[6:7]
	v_mul_f32_e32 v16, v33, v0
	v_mul_f32_e32 v16, 0x41800000, v16
	v_med3_f32 v16, v16, s72, v224
	s_waitcnt lgkmcnt(0)
	s_nop 1
	v_mov_b32_dpp v32, v16 quad_perm:[1,0,3,2] row_mask:0xf bank_mask:0xf
	v_mov_b32_e32 v33, v1
	s_waitcnt lgkmcnt(0)
	v_cvt_pk_fp8_f32 v33, v16, v32
	v_and_b32_e32 v16, 0xffff, v33
	s_nop 1
	v_mov_b32_dpp v32, v16 quad_perm:[2,3,0,1] row_mask:0xf bank_mask:0xf
	s_and_saveexec_b64 s[6:7], vcc
	s_cbranch_execz .LBB0_3299
	s_waitcnt lgkmcnt(0)
	v_lshl_or_b32 v16, v32, 16, v16
	global_store_dword v[64:65], v16, off offset:64
.LBB0_3299:
	s_or_b64 exec, exec, s[6:7]
	v_mul_f32_e32 v0, v17, v0
	v_mul_f32_e32 v0, 0x41800000, v0
	v_med3_f32 v0, v0, s72, v224
	s_nop 1
	v_mov_b32_dpp v16, v0 quad_perm:[1,0,3,2] row_mask:0xf bank_mask:0xf
	v_mov_b32_e32 v17, v1
	s_waitcnt lgkmcnt(0)
	v_cvt_pk_fp8_f32 v17, v0, v16
	v_and_b32_e32 v0, 0xffff, v17
	s_nop 1
	v_mov_b32_dpp v16, v0 quad_perm:[2,3,0,1] row_mask:0xf bank_mask:0xf
	s_and_saveexec_b64 s[6:7], vcc
	s_cbranch_execz .LBB0_3301
	s_waitcnt lgkmcnt(0)
	v_lshl_or_b32 v0, v16, 16, v0
	global_store_dword v[64:65], v0, off offset:96
; __device__ __forceinline__ int crow(int r, int hi) { return (r & 3) + 8 * (r >> 2) + 4 * hi; }
; template <int MODE>
; __device__ __forceinline__ void attn_block(const AttnArgs& a, const BlockRef& cur, const BlockRef& nxt, char* lds, Seam<MODE>& S, const int tid) {
;     ...
;     if (a.o8 != 0.f) {
;         unsigned char* Ob = (unsigned char*)a.O + (size_t)(orow_ + wid * QBLK) * ldo + hcol_; const float os = a.o8;
; #pragma unroll
;         for (int r = 0; r < 16; ++r) { const int orow = crow(r, hi);
; #pragma unroll
;             for (int d0 = 0; d0 < 4; ++d0) { const float v = __builtin_amdgcn_fmed3f(o[d0][r] * rli[r] * os, -448.f, 448.f);
;                 const float vn = __shfl_xor(v, 1);
;                 const int pk = __builtin_amdgcn_cvt_pk_fp8_f32(v, vn, 0, false) & 0xffff; const int pk2 = __shfl_xor(pk, 2);
;                 if ((r32 & 3) == 0) *(unsigned*)(Ob + (size_t)orow * ldo + d0 * 32 + r32) = (unsigned)pk | ((unsigned)pk2 << 16); } }
.LBB0_3301:
	s_or_b64 exec, exec, s[6:7]
	v_rcp_f32_e32 v0, v82
	v_mov_b32_e32 v32, v1
	s_waitcnt lgkmcnt(0)
	v_mul_f32_e32 v16, v66, v0
	v_mul_f32_e32 v16, 0x41800000, v16
	v_med3_f32 v16, v16, s72, v224
	s_nop 1
	v_mov_b32_dpp v17, v16 quad_perm:[1,0,3,2] row_mask:0xf bank_mask:0xf
	s_waitcnt lgkmcnt(0)
	v_cvt_pk_fp8_f32 v32, v16, v17
	v_or_b32_e32 v16, 2, v14
	v_ashrrev_i32_e32 v17, 31, v16
	v_lshlrev_b64 v[16:17], 11, v[16:17]
	v_and_b32_e32 v32, 0xffff, v32
	s_nop 1
	v_mov_b32_dpp v33, v32 quad_perm:[2,3,0,1] row_mask:0xf bank_mask:0xf
	v_lshl_add_u64 v[16:17], v[84:85], 0, v[16:17]
	s_and_saveexec_b64 s[6:7], vcc
	s_cbranch_execz .LBB0_3303
	s_waitcnt lgkmcnt(0)
	v_lshl_or_b32 v32, v33, 16, v32
	global_store_dword v[16:17], v32, off
.LBB0_3303:
	s_or_b64 exec, exec, s[6:7]
	v_mul_f32_e32 v32, v50, v0
	v_mul_f32_e32 v32, 0x41800000, v32
	v_med3_f32 v32, v32, s72, v224
	s_waitcnt lgkmcnt(0)
	s_nop 1
	v_mov_b32_dpp v33, v32 quad_perm:[1,0,3,2] row_mask:0xf bank_mask:0xf
	v_mov_b32_e32 v48, v1
	s_waitcnt lgkmcnt(0)
	v_cvt_pk_fp8_f32 v48, v32, v33
	v_and_b32_e32 v32, 0xffff, v48
	s_nop 1
	v_mov_b32_dpp v33, v32 quad_perm:[2,3,0,1] row_mask:0xf bank_mask:0xf
	s_and_saveexec_b64 s[6:7], vcc
	s_cbranch_execz .LBB0_3305
	s_waitcnt lgkmcnt(0)
	v_lshl_or_b32 v32, v33, 16, v32
	global_store_dword v[16:17], v32, off offset:32
.LBB0_3305:
	s_or_b64 exec, exec, s[6:7]
	v_mul_f32_e32 v32, v34, v0
	v_mul_f32_e32 v32, 0x41800000, v32
	v_med3_f32 v32, v32, s72, v224
	s_waitcnt lgkmcnt(0)
	s_nop 1
	v_mov_b32_dpp v33, v32 quad_perm:[1,0,3,2] row_mask:0xf bank_mask:0xf
	v_mov_b32_e32 v34, v1
	s_waitcnt lgkmcnt(0)
	v_cvt_pk_fp8_f32 v34, v32, v33
	v_and_b32_e32 v32, 0xffff, v34
	s_nop 1
	v_mov_b32_dpp v33, v32 quad_perm:[2,3,0,1] row_mask:0xf bank_mask:0xf
	s_and_saveexec_b64 s[6:7], vcc
	s_cbranch_execz .LBB0_3307
	s_waitcnt lgkmcnt(0)
	v_lshl_or_b32 v32, v33, 16, v32
	global_store_dword v[16:17], v32, off offset:64
.LBB0_3307:
	s_or_b64 exec, exec, s[6:7]
	v_mul_f32_e32 v0, v18, v0
	v_mul_f32_e32 v0, 0x41800000, v0
	v_med3_f32 v0, v0, s72, v224
	s_nop 1
	v_mov_b32_dpp v18, v0 quad_perm:[1,0,3,2] row_mask:0xf bank_mask:0xf
	v_mov_b32_e32 v32, v1
	s_waitcnt lgkmcnt(0)
	v_cvt_pk_fp8_f32 v32, v0, v18
	v_and_b32_e32 v0, 0xffff, v32
	s_nop 1
	v_mov_b32_dpp v18, v0 quad_perm:[2,3,0,1] row_mask:0xf bank_mask:0xf
	s_and_saveexec_b64 s[6:7], vcc
	s_cbranch_execz .LBB0_3309
	s_waitcnt lgkmcnt(0)
	v_lshl_or_b32 v0, v18, 16, v0
	global_store_dword v[16:17], v0, off offset:96
.LBB0_3309:
	s_or_b64 exec, exec, s[6:7]
	v_rcp_f32_e32 v0, v83
	s_waitcnt lgkmcnt(0)
	v_mov_b32_e32 v18, v1
	v_mul_f32_e32 v16, v67, v0
	v_mul_f32_e32 v16, 0x41800000, v16
	v_med3_f32 v16, v16, s72, v224
	s_nop 1
	v_mov_b32_dpp v17, v16 quad_perm:[1,0,3,2] row_mask:0xf bank_mask:0xf
	s_waitcnt lgkmcnt(0)
	v_cvt_pk_fp8_f32 v18, v16, v17
	v_or_b32_e32 v16, 3, v14
	v_ashrrev_i32_e32 v17, 31, v16
	v_lshlrev_b64 v[16:17], 11, v[16:17]
	v_and_b32_e32 v18, 0xffff, v18
	s_nop 1
	v_mov_b32_dpp v32, v18 quad_perm:[2,3,0,1] row_mask:0xf bank_mask:0xf
	v_lshl_add_u64 v[16:17], v[84:85], 0, v[16:17]
	s_and_saveexec_b64 s[6:7], vcc
	s_cbranch_execz .LBB0_3311
	s_waitcnt lgkmcnt(0)
	v_lshl_or_b32 v18, v32, 16, v18
	global_store_dword v[16:17], v18, off
.LBB0_3311:
	s_or_b64 exec, exec, s[6:7]
	v_mul_f32_e32 v18, v51, v0
	v_mul_f32_e32 v18, 0x41800000, v18
	v_med3_f32 v18, v18, s72, v224
	s_waitcnt lgkmcnt(0)
	s_nop 1
	v_mov_b32_dpp v32, v18 quad_perm:[1,0,3,2] row_mask:0xf bank_mask:0xf
	v_mov_b32_e32 v33, v1
	s_waitcnt lgkmcnt(0)
	v_cvt_pk_fp8_f32 v33, v18, v32
	v_and_b32_e32 v18, 0xffff, v33
	s_nop 1
	v_mov_b32_dpp v32, v18 quad_perm:[2,3,0,1] row_mask:0xf bank_mask:0xf
	s_and_saveexec_b64 s[6:7], vcc
	s_cbranch_execz .LBB0_3313
	s_waitcnt lgkmcnt(0)
	v_lshl_or_b32 v18, v32, 16, v18
	global_store_dword v[16:17], v18, off offset:32
.LBB0_3313:
	s_or_b64 exec, exec, s[6:7]
	v_mul_f32_e32 v18, v35, v0
	v_mul_f32_e32 v18, 0x41800000, v18
	v_med3_f32 v18, v18, s72, v224
	s_waitcnt lgkmcnt(0)
	s_nop 1
	v_mov_b32_dpp v32, v18 quad_perm:[1,0,3,2] row_mask:0xf bank_mask:0xf
	v_mov_b32_e32 v33, v1
	s_waitcnt lgkmcnt(0)
	v_cvt_pk_fp8_f32 v33, v18, v32
	v_and_b32_e32 v18, 0xffff, v33
	s_nop 1
	v_mov_b32_dpp v32, v18 quad_perm:[2,3,0,1] row_mask:0xf bank_mask:0xf
	s_and_saveexec_b64 s[6:7], vcc
	s_cbranch_execz .LBB0_3315
	s_waitcnt lgkmcnt(0)
	v_lshl_or_b32 v18, v32, 16, v18
	global_store_dword v[16:17], v18, off offset:64
.LBB0_3315:
	s_or_b64 exec, exec, s[6:7]
	v_mul_f32_e32 v0, v19, v0
	v_mul_f32_e32 v0, 0x41800000, v0
	v_med3_f32 v0, v0, s72, v224
	s_nop 1
	v_mov_b32_dpp v18, v0 quad_perm:[1,0,3,2] row_mask:0xf bank_mask:0xf
	v_mov_b32_e32 v19, v1
	s_waitcnt lgkmcnt(0)
	v_cvt_pk_fp8_f32 v19, v0, v18
	v_and_b32_e32 v0, 0xffff, v19
	s_nop 1
	v_mov_b32_dpp v18, v0 quad_perm:[2,3,0,1] row_mask:0xf bank_mask:0xf
	s_and_saveexec_b64 s[6:7], vcc
	s_cbranch_execz .LBB0_3317
	s_waitcnt lgkmcnt(0)
	v_lshl_or_b32 v0, v18, 16, v0
	global_store_dword v[16:17], v0, off offset:96
.LBB0_3317:
	s_or_b64 exec, exec, s[6:7]
	v_rcp_f32_e32 v0, v10
	v_mov_b32_e32 v17, v1
	v_mul_f32_e32 v10, v68, v0
	v_mul_f32_e32 v10, 0x41800000, v10
	v_med3_f32 v10, v10, s72, v224
	s_nop 1
	v_mov_b32_dpp v16, v10 quad_perm:[1,0,3,2] row_mask:0xf bank_mask:0xf
	s_waitcnt lgkmcnt(0)
	v_cvt_pk_fp8_f32 v17, v10, v16
	v_and_b32_e32 v10, 0xffff, v17
	s_nop 1
	v_mov_b32_dpp v18, v10 quad_perm:[2,3,0,1] row_mask:0xf bank_mask:0xf
	v_lshlrev_b64 v[16:17], 11, v[14:15]
	v_lshl_add_u64 v[16:17], v[84:85], 0, v[16:17]
	v_lshl_add_u64 v[16:17], v[16:17], 0, s[14:15]
	s_and_saveexec_b64 s[6:7], vcc
	s_cbranch_execz .LBB0_3319
	s_waitcnt lgkmcnt(0)
	v_lshl_or_b32 v10, v18, 16, v10
	global_store_dword v[16:17], v10, off
; __device__ __forceinline__ int crow(int r, int hi) { return (r & 3) + 8 * (r >> 2) + 4 * hi; }
; template <int MODE>
; __device__ __forceinline__ void attn_block(const AttnArgs& a, const BlockRef& cur, const BlockRef& nxt, char* lds, Seam<MODE>& S, const int tid) {
;     ...
;     if (a.o8 != 0.f) {
;         unsigned char* Ob = (unsigned char*)a.O + (size_t)(orow_ + wid * QBLK) * ldo + hcol_; const float os = a.o8;
; #pragma unroll
;         for (int r = 0; r < 16; ++r) { const int orow = crow(r, hi);
; #pragma unroll
;             for (int d0 = 0; d0 < 4; ++d0) { const float v = __builtin_amdgcn_fmed3f(o[d0][r] * rli[r] * os, -448.f, 448.f);
;                 const float vn = __shfl_xor(v, 1);
;                 const int pk = __builtin_amdgcn_cvt_pk_fp8_f32(v, vn, 0, false) & 0xffff; const int pk2 = __shfl_xor(pk, 2);
;                 if ((r32 & 3) == 0) *(unsigned*)(Ob + (size_t)orow * ldo + d0 * 32 + r32) = (unsigned)pk | ((unsigned)pk2 << 16); } }
.LBB0_3319:
	s_or_b64 exec, exec, s[6:7]
	v_mul_f32_e32 v10, v52, v0
	v_mul_f32_e32 v10, 0x41800000, v10
	v_med3_f32 v10, v10, s72, v224
	s_waitcnt lgkmcnt(0)
	s_nop 1
	v_mov_b32_dpp v18, v10 quad_perm:[1,0,3,2] row_mask:0xf bank_mask:0xf
	v_mov_b32_e32 v19, v1
	s_waitcnt lgkmcnt(0)
	v_cvt_pk_fp8_f32 v19, v10, v18
	v_and_b32_e32 v10, 0xffff, v19
	s_nop 1
	v_mov_b32_dpp v18, v10 quad_perm:[2,3,0,1] row_mask:0xf bank_mask:0xf
	s_and_saveexec_b64 s[6:7], vcc
	s_cbranch_execz .LBB0_3321
	s_waitcnt lgkmcnt(0)
	v_lshl_or_b32 v10, v18, 16, v10
	global_store_dword v[16:17], v10, off offset:32
.LBB0_3321:
	s_or_b64 exec, exec, s[6:7]
	v_mul_f32_e32 v10, v36, v0
	v_mul_f32_e32 v10, 0x41800000, v10
	v_med3_f32 v10, v10, s72, v224
	s_waitcnt lgkmcnt(0)
	s_nop 1
	v_mov_b32_dpp v18, v10 quad_perm:[1,0,3,2] row_mask:0xf bank_mask:0xf
	v_mov_b32_e32 v19, v1
	s_waitcnt lgkmcnt(0)
	v_cvt_pk_fp8_f32 v19, v10, v18
	v_and_b32_e32 v10, 0xffff, v19
	s_nop 1
	v_mov_b32_dpp v18, v10 quad_perm:[2,3,0,1] row_mask:0xf bank_mask:0xf
	s_and_saveexec_b64 s[6:7], vcc
	s_cbranch_execz .LBB0_3323
	s_waitcnt lgkmcnt(0)
	v_lshl_or_b32 v10, v18, 16, v10
	global_store_dword v[16:17], v10, off offset:64
.LBB0_3323:
	s_or_b64 exec, exec, s[6:7]
	v_mul_f32_e32 v0, v20, v0
	v_mul_f32_e32 v0, 0x41800000, v0
	v_med3_f32 v0, v0, s72, v224
	s_nop 1
	v_mov_b32_dpp v10, v0 quad_perm:[1,0,3,2] row_mask:0xf bank_mask:0xf
	s_waitcnt lgkmcnt(1)
	v_mov_b32_e32 v18, v1
	s_waitcnt lgkmcnt(0)
	v_cvt_pk_fp8_f32 v18, v0, v10
	v_and_b32_e32 v0, 0xffff, v18
	s_nop 1
	v_mov_b32_dpp v10, v0 quad_perm:[2,3,0,1] row_mask:0xf bank_mask:0xf
	s_and_saveexec_b64 s[6:7], vcc
	s_cbranch_execz .LBB0_3325
	s_waitcnt lgkmcnt(0)
	v_lshl_or_b32 v0, v10, 16, v0
	global_store_dword v[16:17], v0, off offset:96
.LBB0_3325:
	s_or_b64 exec, exec, s[6:7]
	v_rcp_f32_e32 v0, v11
	v_mov_b32_e32 v16, v1
	s_waitcnt lgkmcnt(0)
	v_mul_f32_e32 v10, v69, v0
	v_mul_f32_e32 v10, 0x41800000, v10
	v_med3_f32 v10, v10, s72, v224
	s_nop 1
	v_mov_b32_dpp v11, v10 quad_perm:[1,0,3,2] row_mask:0xf bank_mask:0xf
	s_waitcnt lgkmcnt(0)
	v_cvt_pk_fp8_f32 v16, v10, v11
	v_lshlrev_b64 v[10:11], 11, v[14:15]
	v_lshl_add_u64 v[10:11], v[84:85], 0, v[10:11]
	v_lshl_add_u64 v[10:11], v[10:11], 0, s[16:17]
	v_and_b32_e32 v16, 0xffff, v16
	s_nop 1
	v_mov_b32_dpp v17, v16 quad_perm:[2,3,0,1] row_mask:0xf bank_mask:0xf
	s_and_saveexec_b64 s[6:7], vcc
	s_cbranch_execz .LBB0_3327
	s_waitcnt lgkmcnt(0)
	v_lshl_or_b32 v16, v17, 16, v16
	global_store_dword v[10:11], v16, off
.LBB0_3327:
	s_or_b64 exec, exec, s[6:7]
	v_mul_f32_e32 v16, v53, v0
	v_mul_f32_e32 v16, 0x41800000, v16
	v_med3_f32 v16, v16, s72, v224
	s_waitcnt lgkmcnt(0)
	s_nop 1
	v_mov_b32_dpp v17, v16 quad_perm:[1,0,3,2] row_mask:0xf bank_mask:0xf
	v_mov_b32_e32 v18, v1
	s_waitcnt lgkmcnt(0)
	v_cvt_pk_fp8_f32 v18, v16, v17
	v_and_b32_e32 v16, 0xffff, v18
	s_nop 1
	v_mov_b32_dpp v17, v16 quad_perm:[2,3,0,1] row_mask:0xf bank_mask:0xf
	s_and_saveexec_b64 s[6:7], vcc
	s_cbranch_execz .LBB0_3329
	s_waitcnt lgkmcnt(0)
	v_lshl_or_b32 v16, v17, 16, v16
	global_store_dword v[10:11], v16, off offset:32
.LBB0_3329:
	s_or_b64 exec, exec, s[6:7]
	v_mul_f32_e32 v16, v37, v0
	v_mul_f32_e32 v16, 0x41800000, v16
	v_med3_f32 v16, v16, s72, v224
	s_waitcnt lgkmcnt(0)
	s_nop 1
	v_mov_b32_dpp v17, v16 quad_perm:[1,0,3,2] row_mask:0xf bank_mask:0xf
	v_mov_b32_e32 v18, v1
	s_waitcnt lgkmcnt(0)
	v_cvt_pk_fp8_f32 v18, v16, v17
	v_and_b32_e32 v16, 0xffff, v18
	s_nop 1
	v_mov_b32_dpp v17, v16 quad_perm:[2,3,0,1] row_mask:0xf bank_mask:0xf
	s_and_saveexec_b64 s[6:7], vcc
	s_cbranch_execz .LBB0_3331
	s_waitcnt lgkmcnt(0)
	v_lshl_or_b32 v16, v17, 16, v16
	global_store_dword v[10:11], v16, off offset:64
.LBB0_3331:
	s_or_b64 exec, exec, s[6:7]
	v_mul_f32_e32 v0, v21, v0
	v_mul_f32_e32 v0, 0x41800000, v0
	v_med3_f32 v0, v0, s72, v224
	s_nop 1
	v_mov_b32_dpp v16, v0 quad_perm:[1,0,3,2] row_mask:0xf bank_mask:0xf
	s_waitcnt lgkmcnt(1)
	v_mov_b32_e32 v17, v1
	s_waitcnt lgkmcnt(0)
	v_cvt_pk_fp8_f32 v17, v0, v16
	v_and_b32_e32 v0, 0xffff, v17
	s_nop 1
	v_mov_b32_dpp v16, v0 quad_perm:[2,3,0,1] row_mask:0xf bank_mask:0xf
	s_and_saveexec_b64 s[6:7], vcc
	s_cbranch_execz .LBB0_3333
	s_waitcnt lgkmcnt(0)
	v_lshl_or_b32 v0, v16, 16, v0
	global_store_dword v[10:11], v0, off offset:96
.LBB0_3333:
	s_or_b64 exec, exec, s[6:7]
	v_rcp_f32_e32 v0, v12
	v_mov_b32_e32 v12, v1
	v_mul_f32_e32 v10, v70, v0
	v_mul_f32_e32 v10, 0x41800000, v10
	v_med3_f32 v10, v10, s72, v224
	s_nop 1
	v_mov_b32_dpp v11, v10 quad_perm:[1,0,3,2] row_mask:0xf bank_mask:0xf
	s_waitcnt lgkmcnt(0)
	v_cvt_pk_fp8_f32 v12, v10, v11
	v_lshlrev_b64 v[10:11], 11, v[14:15]
	v_lshl_add_u64 v[10:11], v[84:85], 0, v[10:11]
	v_lshl_add_u64 v[10:11], v[10:11], 0, s[18:19]
	v_and_b32_e32 v12, 0xffff, v12
	s_nop 1
	v_mov_b32_dpp v16, v12 quad_perm:[2,3,0,1] row_mask:0xf bank_mask:0xf
	s_and_saveexec_b64 s[6:7], vcc
	s_cbranch_execz .LBB0_3335
	s_waitcnt lgkmcnt(0)
	v_lshl_or_b32 v12, v16, 16, v12
	global_store_dword v[10:11], v12, off
.LBB0_3335:
	s_or_b64 exec, exec, s[6:7]
	v_mul_f32_e32 v12, v54, v0
	v_mul_f32_e32 v12, 0x41800000, v12
	v_med3_f32 v12, v12, s72, v224
	s_waitcnt lgkmcnt(0)
	s_nop 1
	v_mov_b32_dpp v16, v12 quad_perm:[1,0,3,2] row_mask:0xf bank_mask:0xf
	v_mov_b32_e32 v17, v1
	s_waitcnt lgkmcnt(0)
	v_cvt_pk_fp8_f32 v17, v12, v16
	v_and_b32_e32 v12, 0xffff, v17
	s_nop 1
	v_mov_b32_dpp v16, v12 quad_perm:[2,3,0,1] row_mask:0xf bank_mask:0xf
	s_and_saveexec_b64 s[6:7], vcc
	s_cbranch_execz .LBB0_3337
	s_waitcnt lgkmcnt(0)
	v_lshl_or_b32 v12, v16, 16, v12
	global_store_dword v[10:11], v12, off offset:32
; __device__ __forceinline__ int crow(int r, int hi) { return (r & 3) + 8 * (r >> 2) + 4 * hi; }
; template <int MODE>
; __device__ __forceinline__ void attn_block(const AttnArgs& a, const BlockRef& cur, const BlockRef& nxt, char* lds, Seam<MODE>& S, const int tid) {
;     ...
;     if (a.o8 != 0.f) {
;         unsigned char* Ob = (unsigned char*)a.O + (size_t)(orow_ + wid * QBLK) * ldo + hcol_; const float os = a.o8;
; #pragma unroll
;         for (int r = 0; r < 16; ++r) { const int orow = crow(r, hi);
; #pragma unroll
;             for (int d0 = 0; d0 < 4; ++d0) { const float v = __builtin_amdgcn_fmed3f(o[d0][r] * rli[r] * os, -448.f, 448.f);
;                 const float vn = __shfl_xor(v, 1);
;                 const int pk = __builtin_amdgcn_cvt_pk_fp8_f32(v, vn, 0, false) & 0xffff; const int pk2 = __shfl_xor(pk, 2);
;                 if ((r32 & 3) == 0) *(unsigned*)(Ob + (size_t)orow * ldo + d0 * 32 + r32) = (unsigned)pk | ((unsigned)pk2 << 16); } }
.LBB0_3337:
	s_or_b64 exec, exec, s[6:7]
	v_mul_f32_e32 v12, v38, v0
	v_mul_f32_e32 v12, 0x41800000, v12
	v_med3_f32 v12, v12, s72, v224
	s_waitcnt lgkmcnt(0)
	s_nop 1
	v_mov_b32_dpp v16, v12 quad_perm:[1,0,3,2] row_mask:0xf bank_mask:0xf
	v_mov_b32_e32 v17, v1
	s_waitcnt lgkmcnt(0)
	v_cvt_pk_fp8_f32 v17, v12, v16
	v_and_b32_e32 v12, 0xffff, v17
	s_nop 1
	v_mov_b32_dpp v16, v12 quad_perm:[2,3,0,1] row_mask:0xf bank_mask:0xf
	s_and_saveexec_b64 s[6:7], vcc
	s_cbranch_execz .LBB0_3339
	s_waitcnt lgkmcnt(0)
	v_lshl_or_b32 v12, v16, 16, v12
	global_store_dword v[10:11], v12, off offset:64
.LBB0_3339:
	s_or_b64 exec, exec, s[6:7]
	v_mul_f32_e32 v0, v22, v0
	v_mul_f32_e32 v0, 0x41800000, v0
	v_med3_f32 v0, v0, s72, v224
	s_nop 1
	v_mov_b32_dpp v12, v0 quad_perm:[1,0,3,2] row_mask:0xf bank_mask:0xf
	s_waitcnt lgkmcnt(1)
	v_mov_b32_e32 v16, v1
	s_waitcnt lgkmcnt(0)
	v_cvt_pk_fp8_f32 v16, v0, v12
	v_and_b32_e32 v0, 0xffff, v16
	s_nop 1
	v_mov_b32_dpp v12, v0 quad_perm:[2,3,0,1] row_mask:0xf bank_mask:0xf
	s_and_saveexec_b64 s[6:7], vcc
	s_cbranch_execz .LBB0_3341
	s_waitcnt lgkmcnt(0)
	v_lshl_or_b32 v0, v12, 16, v0
	global_store_dword v[10:11], v0, off offset:96
.LBB0_3341:
	s_or_b64 exec, exec, s[6:7]
	v_rcp_f32_e32 v0, v13
	s_waitcnt lgkmcnt(0)
	v_mov_b32_e32 v12, v1
	v_mul_f32_e32 v10, v71, v0
	v_mul_f32_e32 v10, 0x41800000, v10
	v_med3_f32 v10, v10, s72, v224
	s_nop 1
	v_mov_b32_dpp v11, v10 quad_perm:[1,0,3,2] row_mask:0xf bank_mask:0xf
	s_waitcnt lgkmcnt(0)
	v_cvt_pk_fp8_f32 v12, v10, v11
	v_lshlrev_b64 v[10:11], 11, v[14:15]
	v_lshl_add_u64 v[10:11], v[84:85], 0, v[10:11]
	v_lshl_add_u64 v[10:11], v[10:11], 0, s[20:21]
	v_and_b32_e32 v12, 0xffff, v12
	s_nop 1
	v_mov_b32_dpp v13, v12 quad_perm:[2,3,0,1] row_mask:0xf bank_mask:0xf
	s_and_saveexec_b64 s[6:7], vcc
	s_cbranch_execz .LBB0_3343
	s_waitcnt lgkmcnt(0)
	v_lshl_or_b32 v12, v13, 16, v12
	global_store_dword v[10:11], v12, off
.LBB0_3343:
	s_or_b64 exec, exec, s[6:7]
	v_mul_f32_e32 v12, v55, v0
	v_mul_f32_e32 v12, 0x41800000, v12
	v_med3_f32 v12, v12, s72, v224
	s_waitcnt lgkmcnt(0)
	s_nop 1
	v_mov_b32_dpp v13, v12 quad_perm:[1,0,3,2] row_mask:0xf bank_mask:0xf
	v_mov_b32_e32 v16, v1
	s_waitcnt lgkmcnt(0)
	v_cvt_pk_fp8_f32 v16, v12, v13
	v_and_b32_e32 v12, 0xffff, v16
	s_nop 1
	v_mov_b32_dpp v13, v12 quad_perm:[2,3,0,1] row_mask:0xf bank_mask:0xf
	s_and_saveexec_b64 s[6:7], vcc
	s_cbranch_execz .LBB0_3345
	s_waitcnt lgkmcnt(0)
	v_lshl_or_b32 v12, v13, 16, v12
	global_store_dword v[10:11], v12, off offset:32
.LBB0_3345:
	s_or_b64 exec, exec, s[6:7]
	v_mul_f32_e32 v12, v39, v0
	v_mul_f32_e32 v12, 0x41800000, v12
	v_med3_f32 v12, v12, s72, v224
	s_waitcnt lgkmcnt(0)
	s_nop 1
	v_mov_b32_dpp v13, v12 quad_perm:[1,0,3,2] row_mask:0xf bank_mask:0xf
	v_mov_b32_e32 v16, v1
	s_waitcnt lgkmcnt(0)
	v_cvt_pk_fp8_f32 v16, v12, v13
	v_and_b32_e32 v12, 0xffff, v16
	s_nop 1
	v_mov_b32_dpp v13, v12 quad_perm:[2,3,0,1] row_mask:0xf bank_mask:0xf
	s_and_saveexec_b64 s[6:7], vcc
	s_cbranch_execz .LBB0_3347
	s_waitcnt lgkmcnt(0)
	v_lshl_or_b32 v12, v13, 16, v12
	global_store_dword v[10:11], v12, off offset:64
.LBB0_3347:
	s_or_b64 exec, exec, s[6:7]
	v_mul_f32_e32 v0, v23, v0
	v_mul_f32_e32 v0, 0x41800000, v0
	v_med3_f32 v0, v0, s72, v224
	s_nop 1
	v_mov_b32_dpp v12, v0 quad_perm:[1,0,3,2] row_mask:0xf bank_mask:0xf
	s_waitcnt lgkmcnt(1)
	v_mov_b32_e32 v13, v1
	s_waitcnt lgkmcnt(0)
	v_cvt_pk_fp8_f32 v13, v0, v12
	v_and_b32_e32 v0, 0xffff, v13
	s_nop 1
	v_mov_b32_dpp v12, v0 quad_perm:[2,3,0,1] row_mask:0xf bank_mask:0xf
	s_and_saveexec_b64 s[6:7], vcc
	s_cbranch_execz .LBB0_3349
	s_waitcnt lgkmcnt(0)
	v_lshl_or_b32 v0, v12, 16, v0
	global_store_dword v[10:11], v0, off offset:96
.LBB0_3349:
	s_or_b64 exec, exec, s[6:7]
	v_rcp_f32_e32 v0, v6
	v_mov_b32_e32 v11, v1
	v_mul_f32_e32 v6, v72, v0
	v_mul_f32_e32 v6, 0x41800000, v6
	v_med3_f32 v6, v6, s72, v224
	s_nop 1
	v_mov_b32_dpp v10, v6 quad_perm:[1,0,3,2] row_mask:0xf bank_mask:0xf
	s_waitcnt lgkmcnt(0)
	v_cvt_pk_fp8_f32 v11, v6, v10
	v_and_b32_e32 v6, 0xffff, v11
	s_nop 1
	v_mov_b32_dpp v12, v6 quad_perm:[2,3,0,1] row_mask:0xf bank_mask:0xf
	v_lshlrev_b64 v[10:11], 11, v[14:15]
	v_lshl_add_u64 v[10:11], v[84:85], 0, v[10:11]
	v_lshl_add_u64 v[10:11], v[10:11], 0, s[24:25]
	s_and_saveexec_b64 s[6:7], vcc
	s_cbranch_execz .LBB0_3351
	s_waitcnt lgkmcnt(0)
	v_lshl_or_b32 v6, v12, 16, v6
	global_store_dword v[10:11], v6, off
.LBB0_3351:
	s_or_b64 exec, exec, s[6:7]
	v_mul_f32_e32 v6, v56, v0
	v_mul_f32_e32 v6, 0x41800000, v6
	v_med3_f32 v6, v6, s72, v224
	s_waitcnt lgkmcnt(0)
	s_nop 1
	v_mov_b32_dpp v12, v6 quad_perm:[1,0,3,2] row_mask:0xf bank_mask:0xf
	v_mov_b32_e32 v13, v1
	s_waitcnt lgkmcnt(0)
	v_cvt_pk_fp8_f32 v13, v6, v12
	v_and_b32_e32 v6, 0xffff, v13
	s_nop 1
	v_mov_b32_dpp v12, v6 quad_perm:[2,3,0,1] row_mask:0xf bank_mask:0xf
	s_and_saveexec_b64 s[6:7], vcc
	s_cbranch_execz .LBB0_3353
	s_waitcnt lgkmcnt(0)
	v_lshl_or_b32 v6, v12, 16, v6
	global_store_dword v[10:11], v6, off offset:32
.LBB0_3353:
	s_or_b64 exec, exec, s[6:7]
	v_mul_f32_e32 v6, v40, v0
	v_mul_f32_e32 v6, 0x41800000, v6
	v_med3_f32 v6, v6, s72, v224
	s_waitcnt lgkmcnt(0)
	s_nop 1
	v_mov_b32_dpp v12, v6 quad_perm:[1,0,3,2] row_mask:0xf bank_mask:0xf
	v_mov_b32_e32 v13, v1
	s_waitcnt lgkmcnt(0)
	v_cvt_pk_fp8_f32 v13, v6, v12
	v_and_b32_e32 v6, 0xffff, v13
	s_nop 1
	v_mov_b32_dpp v12, v6 quad_perm:[2,3,0,1] row_mask:0xf bank_mask:0xf
	s_and_saveexec_b64 s[6:7], vcc
	s_cbranch_execz .LBB0_3355
	s_waitcnt lgkmcnt(0)
	v_lshl_or_b32 v6, v12, 16, v6
	global_store_dword v[10:11], v6, off offset:64
; __device__ __forceinline__ int crow(int r, int hi) { return (r & 3) + 8 * (r >> 2) + 4 * hi; }
; template <int MODE>
; __device__ __forceinline__ void attn_block(const AttnArgs& a, const BlockRef& cur, const BlockRef& nxt, char* lds, Seam<MODE>& S, const int tid) {
;     ...
;     if (a.o8 != 0.f) {
;         unsigned char* Ob = (unsigned char*)a.O + (size_t)(orow_ + wid * QBLK) * ldo + hcol_; const float os = a.o8;
; #pragma unroll
;         for (int r = 0; r < 16; ++r) { const int orow = crow(r, hi);
; #pragma unroll
;             for (int d0 = 0; d0 < 4; ++d0) { const float v = __builtin_amdgcn_fmed3f(o[d0][r] * rli[r] * os, -448.f, 448.f);
;                 const float vn = __shfl_xor(v, 1);
;                 const int pk = __builtin_amdgcn_cvt_pk_fp8_f32(v, vn, 0, false) & 0xffff; const int pk2 = __shfl_xor(pk, 2);
;                 if ((r32 & 3) == 0) *(unsigned*)(Ob + (size_t)orow * ldo + d0 * 32 + r32) = (unsigned)pk | ((unsigned)pk2 << 16); } }
.LBB0_3355:
	s_or_b64 exec, exec, s[6:7]
	v_mul_f32_e32 v0, v24, v0
	v_mul_f32_e32 v0, 0x41800000, v0
	v_med3_f32 v0, v0, s72, v224
	s_nop 1
	v_mov_b32_dpp v6, v0 quad_perm:[1,0,3,2] row_mask:0xf bank_mask:0xf
	s_waitcnt lgkmcnt(1)
	v_mov_b32_e32 v12, v1
	s_waitcnt lgkmcnt(0)
	v_cvt_pk_fp8_f32 v12, v0, v6
	v_and_b32_e32 v0, 0xffff, v12
	s_nop 1
	v_mov_b32_dpp v6, v0 quad_perm:[2,3,0,1] row_mask:0xf bank_mask:0xf
	s_and_saveexec_b64 s[6:7], vcc
	s_cbranch_execz .LBB0_3357
	s_waitcnt lgkmcnt(0)
	v_lshl_or_b32 v0, v6, 16, v0
	global_store_dword v[10:11], v0, off offset:96
.LBB0_3357:
	s_or_b64 exec, exec, s[6:7]
	v_rcp_f32_e32 v0, v7
	v_mov_b32_e32 v10, v1
	s_waitcnt lgkmcnt(0)
	v_mul_f32_e32 v6, v73, v0
	v_mul_f32_e32 v6, 0x41800000, v6
	v_med3_f32 v6, v6, s72, v224
	s_nop 1
	v_mov_b32_dpp v7, v6 quad_perm:[1,0,3,2] row_mask:0xf bank_mask:0xf
	s_waitcnt lgkmcnt(0)
	v_cvt_pk_fp8_f32 v10, v6, v7
	v_lshlrev_b64 v[6:7], 11, v[14:15]
	v_lshl_add_u64 v[6:7], v[84:85], 0, v[6:7]
	v_lshl_add_u64 v[6:7], v[6:7], 0, s[26:27]
	v_and_b32_e32 v10, 0xffff, v10
	s_nop 1
	v_mov_b32_dpp v11, v10 quad_perm:[2,3,0,1] row_mask:0xf bank_mask:0xf
	s_and_saveexec_b64 s[6:7], vcc
	s_cbranch_execz .LBB0_3359
	s_waitcnt lgkmcnt(0)
	v_lshl_or_b32 v10, v11, 16, v10
	global_store_dword v[6:7], v10, off
.LBB0_3359:
	s_or_b64 exec, exec, s[6:7]
	v_mul_f32_e32 v10, v57, v0
	v_mul_f32_e32 v10, 0x41800000, v10
	v_med3_f32 v10, v10, s72, v224
	s_waitcnt lgkmcnt(0)
	s_nop 1
	v_mov_b32_dpp v11, v10 quad_perm:[1,0,3,2] row_mask:0xf bank_mask:0xf
	v_mov_b32_e32 v12, v1
	s_waitcnt lgkmcnt(0)
	v_cvt_pk_fp8_f32 v12, v10, v11
	v_and_b32_e32 v10, 0xffff, v12
	s_nop 1
	v_mov_b32_dpp v11, v10 quad_perm:[2,3,0,1] row_mask:0xf bank_mask:0xf
	s_and_saveexec_b64 s[6:7], vcc
	s_cbranch_execz .LBB0_3361
	s_waitcnt lgkmcnt(0)
	v_lshl_or_b32 v10, v11, 16, v10
	global_store_dword v[6:7], v10, off offset:32
.LBB0_3361:
	s_or_b64 exec, exec, s[6:7]
	v_mul_f32_e32 v10, v41, v0
	v_mul_f32_e32 v10, 0x41800000, v10
	v_med3_f32 v10, v10, s72, v224
	s_waitcnt lgkmcnt(0)
	s_nop 1
	v_mov_b32_dpp v11, v10 quad_perm:[1,0,3,2] row_mask:0xf bank_mask:0xf
	v_mov_b32_e32 v12, v1
	s_waitcnt lgkmcnt(0)
	v_cvt_pk_fp8_f32 v12, v10, v11
	v_and_b32_e32 v10, 0xffff, v12
	s_nop 1
	v_mov_b32_dpp v11, v10 quad_perm:[2,3,0,1] row_mask:0xf bank_mask:0xf
	s_and_saveexec_b64 s[6:7], vcc
	s_cbranch_execz .LBB0_3363
	s_waitcnt lgkmcnt(0)
	v_lshl_or_b32 v10, v11, 16, v10
	global_store_dword v[6:7], v10, off offset:64
.LBB0_3363:
	s_or_b64 exec, exec, s[6:7]
	v_mul_f32_e32 v0, v25, v0
	v_mul_f32_e32 v0, 0x41800000, v0
	v_med3_f32 v0, v0, s72, v224
	s_nop 1
	v_mov_b32_dpp v10, v0 quad_perm:[1,0,3,2] row_mask:0xf bank_mask:0xf
	s_waitcnt lgkmcnt(1)
	v_mov_b32_e32 v11, v1
	s_waitcnt lgkmcnt(0)
	v_cvt_pk_fp8_f32 v11, v0, v10
	v_and_b32_e32 v0, 0xffff, v11
	s_nop 1
	v_mov_b32_dpp v10, v0 quad_perm:[2,3,0,1] row_mask:0xf bank_mask:0xf
	s_and_saveexec_b64 s[6:7], vcc
	s_cbranch_execz .LBB0_3365
	s_waitcnt lgkmcnt(0)
	v_lshl_or_b32 v0, v10, 16, v0
	global_store_dword v[6:7], v0, off offset:96
.LBB0_3365:
	s_or_b64 exec, exec, s[6:7]
	v_rcp_f32_e32 v0, v8
	v_mov_b32_e32 v8, v1
	v_mul_f32_e32 v6, v74, v0
	v_mul_f32_e32 v6, 0x41800000, v6
	v_med3_f32 v6, v6, s72, v224
	s_nop 1
	v_mov_b32_dpp v7, v6 quad_perm:[1,0,3,2] row_mask:0xf bank_mask:0xf
	s_waitcnt lgkmcnt(0)
	v_cvt_pk_fp8_f32 v8, v6, v7
	v_lshlrev_b64 v[6:7], 11, v[14:15]
	v_lshl_add_u64 v[6:7], v[84:85], 0, v[6:7]
	v_lshl_add_u64 v[6:7], v[6:7], 0, s[28:29]
	v_and_b32_e32 v8, 0xffff, v8
	s_nop 1
	v_mov_b32_dpp v10, v8 quad_perm:[2,3,0,1] row_mask:0xf bank_mask:0xf
	s_and_saveexec_b64 s[6:7], vcc
	s_cbranch_execz .LBB0_3367
	s_waitcnt lgkmcnt(0)
	v_lshl_or_b32 v8, v10, 16, v8
	global_store_dword v[6:7], v8, off
.LBB0_3367:
	s_or_b64 exec, exec, s[6:7]
	v_mul_f32_e32 v8, v58, v0
	v_mul_f32_e32 v8, 0x41800000, v8
	v_med3_f32 v8, v8, s72, v224
	s_waitcnt lgkmcnt(0)
	s_nop 1
	v_mov_b32_dpp v10, v8 quad_perm:[1,0,3,2] row_mask:0xf bank_mask:0xf
	v_mov_b32_e32 v11, v1
	s_waitcnt lgkmcnt(0)
	v_cvt_pk_fp8_f32 v11, v8, v10
	v_and_b32_e32 v8, 0xffff, v11
	s_nop 1
	v_mov_b32_dpp v10, v8 quad_perm:[2,3,0,1] row_mask:0xf bank_mask:0xf
	s_and_saveexec_b64 s[6:7], vcc
	s_cbranch_execz .LBB0_3369
	s_waitcnt lgkmcnt(0)
	v_lshl_or_b32 v8, v10, 16, v8
	global_store_dword v[6:7], v8, off offset:32
.LBB0_3369:
	s_or_b64 exec, exec, s[6:7]
	v_mul_f32_e32 v8, v42, v0
	v_mul_f32_e32 v8, 0x41800000, v8
	v_med3_f32 v8, v8, s72, v224
	s_waitcnt lgkmcnt(0)
	s_nop 1
	v_mov_b32_dpp v10, v8 quad_perm:[1,0,3,2] row_mask:0xf bank_mask:0xf
	v_mov_b32_e32 v11, v1
	s_waitcnt lgkmcnt(0)
	v_cvt_pk_fp8_f32 v11, v8, v10
	v_and_b32_e32 v8, 0xffff, v11
	s_nop 1
	v_mov_b32_dpp v10, v8 quad_perm:[2,3,0,1] row_mask:0xf bank_mask:0xf
	s_and_saveexec_b64 s[6:7], vcc
	s_cbranch_execz .LBB0_3371
	s_waitcnt lgkmcnt(0)
	v_lshl_or_b32 v8, v10, 16, v8
	global_store_dword v[6:7], v8, off offset:64
.LBB0_3371:
	s_or_b64 exec, exec, s[6:7]
	v_mul_f32_e32 v0, v26, v0
	v_mul_f32_e32 v0, 0x41800000, v0
	v_med3_f32 v0, v0, s72, v224
	s_nop 1
	v_mov_b32_dpp v8, v0 quad_perm:[1,0,3,2] row_mask:0xf bank_mask:0xf
	s_waitcnt lgkmcnt(1)
	v_mov_b32_e32 v10, v1
	s_waitcnt lgkmcnt(0)
	v_cvt_pk_fp8_f32 v10, v0, v8
	v_and_b32_e32 v0, 0xffff, v10
	s_nop 1
	v_mov_b32_dpp v8, v0 quad_perm:[2,3,0,1] row_mask:0xf bank_mask:0xf
	s_and_saveexec_b64 s[6:7], vcc
	s_cbranch_execz .LBB0_3373
	s_waitcnt lgkmcnt(0)
	v_lshl_or_b32 v0, v8, 16, v0
	global_store_dword v[6:7], v0, off offset:96
; __device__ __forceinline__ int crow(int r, int hi) { return (r & 3) + 8 * (r >> 2) + 4 * hi; }
; template <int MODE>
; __device__ __forceinline__ void attn_block(const AttnArgs& a, const BlockRef& cur, const BlockRef& nxt, char* lds, Seam<MODE>& S, const int tid) {
;     ...
;     if (a.o8 != 0.f) {
;         unsigned char* Ob = (unsigned char*)a.O + (size_t)(orow_ + wid * QBLK) * ldo + hcol_; const float os = a.o8;
; #pragma unroll
;         for (int r = 0; r < 16; ++r) { const int orow = crow(r, hi);
; #pragma unroll
;             for (int d0 = 0; d0 < 4; ++d0) { const float v = __builtin_amdgcn_fmed3f(o[d0][r] * rli[r] * os, -448.f, 448.f);
;                 const float vn = __shfl_xor(v, 1);
;                 const int pk = __builtin_amdgcn_cvt_pk_fp8_f32(v, vn, 0, false) & 0xffff; const int pk2 = __shfl_xor(pk, 2);
;                 if ((r32 & 3) == 0) *(unsigned*)(Ob + (size_t)orow * ldo + d0 * 32 + r32) = (unsigned)pk | ((unsigned)pk2 << 16); } }
.LBB0_3373:
	s_or_b64 exec, exec, s[6:7]
	v_rcp_f32_e32 v0, v9
	s_waitcnt lgkmcnt(0)
	v_mov_b32_e32 v8, v1
	v_mul_f32_e32 v6, v75, v0
	v_mul_f32_e32 v6, 0x41800000, v6
	v_med3_f32 v6, v6, s72, v224
	s_nop 1
	v_mov_b32_dpp v7, v6 quad_perm:[1,0,3,2] row_mask:0xf bank_mask:0xf
	s_waitcnt lgkmcnt(0)
	v_cvt_pk_fp8_f32 v8, v6, v7
	v_lshlrev_b64 v[6:7], 11, v[14:15]
	v_lshl_add_u64 v[6:7], v[84:85], 0, v[6:7]
	v_lshl_add_u64 v[6:7], v[6:7], 0, s[30:31]
	v_and_b32_e32 v8, 0xffff, v8
	s_nop 1
	v_mov_b32_dpp v9, v8 quad_perm:[2,3,0,1] row_mask:0xf bank_mask:0xf
	s_and_saveexec_b64 s[6:7], vcc
	s_cbranch_execz .LBB0_3375
	s_waitcnt lgkmcnt(0)
	v_lshl_or_b32 v8, v9, 16, v8
	global_store_dword v[6:7], v8, off
.LBB0_3375:
	s_or_b64 exec, exec, s[6:7]
	v_mul_f32_e32 v8, v59, v0
	v_mul_f32_e32 v8, 0x41800000, v8
	v_med3_f32 v8, v8, s72, v224
	s_waitcnt lgkmcnt(0)
	s_nop 1
	v_mov_b32_dpp v9, v8 quad_perm:[1,0,3,2] row_mask:0xf bank_mask:0xf
	v_mov_b32_e32 v10, v1
	s_waitcnt lgkmcnt(0)
	v_cvt_pk_fp8_f32 v10, v8, v9
	v_and_b32_e32 v8, 0xffff, v10
	s_nop 1
	v_mov_b32_dpp v9, v8 quad_perm:[2,3,0,1] row_mask:0xf bank_mask:0xf
	s_and_saveexec_b64 s[6:7], vcc
	s_cbranch_execz .LBB0_3377
	s_waitcnt lgkmcnt(0)
	v_lshl_or_b32 v8, v9, 16, v8
	global_store_dword v[6:7], v8, off offset:32
.LBB0_3377:
	s_or_b64 exec, exec, s[6:7]
	v_mul_f32_e32 v8, v43, v0
	v_mul_f32_e32 v8, 0x41800000, v8
	v_med3_f32 v8, v8, s72, v224
	s_waitcnt lgkmcnt(0)
	s_nop 1
	v_mov_b32_dpp v9, v8 quad_perm:[1,0,3,2] row_mask:0xf bank_mask:0xf
	v_mov_b32_e32 v10, v1
	s_waitcnt lgkmcnt(0)
	v_cvt_pk_fp8_f32 v10, v8, v9
	v_and_b32_e32 v8, 0xffff, v10
	s_nop 1
	v_mov_b32_dpp v9, v8 quad_perm:[2,3,0,1] row_mask:0xf bank_mask:0xf
	s_and_saveexec_b64 s[6:7], vcc
	s_cbranch_execz .LBB0_3379
	s_waitcnt lgkmcnt(0)
	v_lshl_or_b32 v8, v9, 16, v8
	global_store_dword v[6:7], v8, off offset:64
.LBB0_3379:
	s_or_b64 exec, exec, s[6:7]
	v_mul_f32_e32 v0, v27, v0
	v_mul_f32_e32 v0, 0x41800000, v0
	v_med3_f32 v0, v0, s72, v224
	s_nop 1
	v_mov_b32_dpp v8, v0 quad_perm:[1,0,3,2] row_mask:0xf bank_mask:0xf
	s_waitcnt lgkmcnt(1)
	v_mov_b32_e32 v9, v1
	s_waitcnt lgkmcnt(0)
	v_cvt_pk_fp8_f32 v9, v0, v8
	v_and_b32_e32 v0, 0xffff, v9
	s_nop 1
	v_mov_b32_dpp v8, v0 quad_perm:[2,3,0,1] row_mask:0xf bank_mask:0xf
	s_and_saveexec_b64 s[6:7], vcc
	s_cbranch_execz .LBB0_3381
	s_waitcnt lgkmcnt(0)
	v_lshl_or_b32 v0, v8, 16, v0
	global_store_dword v[6:7], v0, off offset:96
.LBB0_3381:
	s_or_b64 exec, exec, s[6:7]
	v_rcp_f32_e32 v0, v2
	v_mov_b32_e32 v7, v1
	v_mul_f32_e32 v2, v76, v0
	v_mul_f32_e32 v2, 0x41800000, v2
	v_med3_f32 v2, v2, s72, v224
	s_nop 1
	v_mov_b32_dpp v6, v2 quad_perm:[1,0,3,2] row_mask:0xf bank_mask:0xf
	s_waitcnt lgkmcnt(0)
	v_cvt_pk_fp8_f32 v7, v2, v6
	v_and_b32_e32 v2, 0xffff, v7
	s_nop 1
	v_mov_b32_dpp v8, v2 quad_perm:[2,3,0,1] row_mask:0xf bank_mask:0xf
	v_lshlrev_b64 v[6:7], 11, v[14:15]
	v_lshl_add_u64 v[6:7], v[84:85], 0, v[6:7]
	v_lshl_add_u64 v[6:7], v[6:7], 0, s[36:37]
	s_and_saveexec_b64 s[6:7], vcc
	s_cbranch_execz .LBB0_3383
	s_waitcnt lgkmcnt(0)
	v_lshl_or_b32 v2, v8, 16, v2
	global_store_dword v[6:7], v2, off
.LBB0_3383:
	s_or_b64 exec, exec, s[6:7]
	v_mul_f32_e32 v2, v60, v0
	v_mul_f32_e32 v2, 0x41800000, v2
	v_med3_f32 v2, v2, s72, v224
	s_waitcnt lgkmcnt(0)
	s_nop 1
	v_mov_b32_dpp v8, v2 quad_perm:[1,0,3,2] row_mask:0xf bank_mask:0xf
	v_mov_b32_e32 v9, v1
	s_waitcnt lgkmcnt(0)
	v_cvt_pk_fp8_f32 v9, v2, v8
	v_and_b32_e32 v2, 0xffff, v9
	s_nop 1
	v_mov_b32_dpp v8, v2 quad_perm:[2,3,0,1] row_mask:0xf bank_mask:0xf
	s_and_saveexec_b64 s[6:7], vcc
	s_cbranch_execz .LBB0_3385
	s_waitcnt lgkmcnt(0)
	v_lshl_or_b32 v2, v8, 16, v2
	global_store_dword v[6:7], v2, off offset:32
.LBB0_3385:
	s_or_b64 exec, exec, s[6:7]
	v_mul_f32_e32 v2, v44, v0
	v_mul_f32_e32 v2, 0x41800000, v2
	v_med3_f32 v2, v2, s72, v224
	s_waitcnt lgkmcnt(0)
	s_nop 1
	v_mov_b32_dpp v8, v2 quad_perm:[1,0,3,2] row_mask:0xf bank_mask:0xf
	v_mov_b32_e32 v9, v1
	s_waitcnt lgkmcnt(0)
	v_cvt_pk_fp8_f32 v9, v2, v8
	v_and_b32_e32 v2, 0xffff, v9
	s_nop 1
	v_mov_b32_dpp v8, v2 quad_perm:[2,3,0,1] row_mask:0xf bank_mask:0xf
	s_and_saveexec_b64 s[6:7], vcc
	s_cbranch_execz .LBB0_3387
	s_waitcnt lgkmcnt(0)
	v_lshl_or_b32 v2, v8, 16, v2
	global_store_dword v[6:7], v2, off offset:64
.LBB0_3387:
	s_or_b64 exec, exec, s[6:7]
	v_mul_f32_e32 v0, v28, v0
	v_mul_f32_e32 v0, 0x41800000, v0
	v_med3_f32 v0, v0, s72, v224
	s_nop 1
	v_mov_b32_dpp v2, v0 quad_perm:[1,0,3,2] row_mask:0xf bank_mask:0xf
	s_waitcnt lgkmcnt(1)
	v_mov_b32_e32 v8, v1
	s_waitcnt lgkmcnt(0)
	v_cvt_pk_fp8_f32 v8, v0, v2
	v_and_b32_e32 v0, 0xffff, v8
	s_nop 1
	v_mov_b32_dpp v2, v0 quad_perm:[2,3,0,1] row_mask:0xf bank_mask:0xf
	s_and_saveexec_b64 s[6:7], vcc
	s_cbranch_execz .LBB0_3389
	s_waitcnt lgkmcnt(0)
	v_lshl_or_b32 v0, v2, 16, v0
	global_store_dword v[6:7], v0, off offset:96
.LBB0_3389:
	s_or_b64 exec, exec, s[6:7]
	v_rcp_f32_e32 v0, v3
	v_mov_b32_e32 v6, v1
	s_waitcnt lgkmcnt(0)
	v_mul_f32_e32 v2, v77, v0
	v_mul_f32_e32 v2, 0x41800000, v2
	v_med3_f32 v2, v2, s72, v224
	s_nop 1
	v_mov_b32_dpp v3, v2 quad_perm:[1,0,3,2] row_mask:0xf bank_mask:0xf
	s_waitcnt lgkmcnt(0)
	v_cvt_pk_fp8_f32 v6, v2, v3
	v_lshlrev_b64 v[2:3], 11, v[14:15]
	v_lshl_add_u64 v[2:3], v[84:85], 0, v[2:3]
	v_lshl_add_u64 v[2:3], v[2:3], 0, s[38:39]
	v_and_b32_e32 v6, 0xffff, v6
	s_nop 1
	v_mov_b32_dpp v7, v6 quad_perm:[2,3,0,1] row_mask:0xf bank_mask:0xf
	s_and_saveexec_b64 s[6:7], vcc
	s_cbranch_execz .LBB0_3391
	s_waitcnt lgkmcnt(0)
	v_lshl_or_b32 v6, v7, 16, v6
	global_store_dword v[2:3], v6, off
; __device__ __forceinline__ int crow(int r, int hi) { return (r & 3) + 8 * (r >> 2) + 4 * hi; }
; template <int MODE>
; __device__ __forceinline__ void attn_block(const AttnArgs& a, const BlockRef& cur, const BlockRef& nxt, char* lds, Seam<MODE>& S, const int tid) {
;     ...
;     if (a.o8 != 0.f) {
;         unsigned char* Ob = (unsigned char*)a.O + (size_t)(orow_ + wid * QBLK) * ldo + hcol_; const float os = a.o8;
; #pragma unroll
;         for (int r = 0; r < 16; ++r) { const int orow = crow(r, hi);
; #pragma unroll
;             for (int d0 = 0; d0 < 4; ++d0) { const float v = __builtin_amdgcn_fmed3f(o[d0][r] * rli[r] * os, -448.f, 448.f);
;                 const float vn = __shfl_xor(v, 1);
;                 const int pk = __builtin_amdgcn_cvt_pk_fp8_f32(v, vn, 0, false) & 0xffff; const int pk2 = __shfl_xor(pk, 2);
;                 if ((r32 & 3) == 0) *(unsigned*)(Ob + (size_t)orow * ldo + d0 * 32 + r32) = (unsigned)pk | ((unsigned)pk2 << 16); } }
.LBB0_3391:
	s_or_b64 exec, exec, s[6:7]
	v_mul_f32_e32 v6, v61, v0
	v_mul_f32_e32 v6, 0x41800000, v6
	v_med3_f32 v6, v6, s72, v224
	s_waitcnt lgkmcnt(0)
	s_nop 1
	v_mov_b32_dpp v7, v6 quad_perm:[1,0,3,2] row_mask:0xf bank_mask:0xf
	v_mov_b32_e32 v8, v1
	s_waitcnt lgkmcnt(0)
	v_cvt_pk_fp8_f32 v8, v6, v7
	v_and_b32_e32 v6, 0xffff, v8
	s_nop 1
	v_mov_b32_dpp v7, v6 quad_perm:[2,3,0,1] row_mask:0xf bank_mask:0xf
	s_and_saveexec_b64 s[6:7], vcc
	s_cbranch_execz .LBB0_3393
	s_waitcnt lgkmcnt(0)
	v_lshl_or_b32 v6, v7, 16, v6
	global_store_dword v[2:3], v6, off offset:32
.LBB0_3393:
	s_or_b64 exec, exec, s[6:7]
	v_mul_f32_e32 v6, v45, v0
	v_mul_f32_e32 v6, 0x41800000, v6
	v_med3_f32 v6, v6, s72, v224
	s_waitcnt lgkmcnt(0)
	s_nop 1
	v_mov_b32_dpp v7, v6 quad_perm:[1,0,3,2] row_mask:0xf bank_mask:0xf
	v_mov_b32_e32 v8, v1
	s_waitcnt lgkmcnt(0)
	v_cvt_pk_fp8_f32 v8, v6, v7
	v_and_b32_e32 v6, 0xffff, v8
	s_nop 1
	v_mov_b32_dpp v7, v6 quad_perm:[2,3,0,1] row_mask:0xf bank_mask:0xf
	s_and_saveexec_b64 s[6:7], vcc
	s_cbranch_execz .LBB0_3395
	s_waitcnt lgkmcnt(0)
	v_lshl_or_b32 v6, v7, 16, v6
	global_store_dword v[2:3], v6, off offset:64
.LBB0_3395:
	s_or_b64 exec, exec, s[6:7]
	v_mul_f32_e32 v0, v29, v0
	v_mul_f32_e32 v0, 0x41800000, v0
	v_med3_f32 v0, v0, s72, v224
	s_nop 1
	v_mov_b32_dpp v6, v0 quad_perm:[1,0,3,2] row_mask:0xf bank_mask:0xf
	s_waitcnt lgkmcnt(1)
	v_mov_b32_e32 v7, v1
	s_waitcnt lgkmcnt(0)
	v_cvt_pk_fp8_f32 v7, v0, v6
	v_and_b32_e32 v0, 0xffff, v7
	s_nop 1
	v_mov_b32_dpp v6, v0 quad_perm:[2,3,0,1] row_mask:0xf bank_mask:0xf
	s_and_saveexec_b64 s[6:7], vcc
	s_cbranch_execz .LBB0_3397
	s_waitcnt lgkmcnt(0)
	v_lshl_or_b32 v0, v6, 16, v0
	global_store_dword v[2:3], v0, off offset:96
.LBB0_3397:
	s_or_b64 exec, exec, s[6:7]
	v_rcp_f32_e32 v0, v4
	v_mov_b32_e32 v4, v1
	v_mul_f32_e32 v2, v78, v0
	v_mul_f32_e32 v2, 0x41800000, v2
	v_med3_f32 v2, v2, s72, v224
	s_nop 1
	v_mov_b32_dpp v3, v2 quad_perm:[1,0,3,2] row_mask:0xf bank_mask:0xf
	s_waitcnt lgkmcnt(0)
	v_cvt_pk_fp8_f32 v4, v2, v3
	v_lshlrev_b64 v[2:3], 11, v[14:15]
	v_lshl_add_u64 v[2:3], v[84:85], 0, v[2:3]
	v_lshl_add_u64 v[2:3], v[2:3], 0, s[42:43]
	v_and_b32_e32 v4, 0xffff, v4
	s_nop 1
	v_mov_b32_dpp v6, v4 quad_perm:[2,3,0,1] row_mask:0xf bank_mask:0xf
	s_and_saveexec_b64 s[6:7], vcc
	s_cbranch_execz .LBB0_3399
	s_waitcnt lgkmcnt(0)
	v_lshl_or_b32 v4, v6, 16, v4
	global_store_dword v[2:3], v4, off
.LBB0_3399:
	s_or_b64 exec, exec, s[6:7]
	v_mul_f32_e32 v4, v62, v0
	v_mul_f32_e32 v4, 0x41800000, v4
	v_med3_f32 v4, v4, s72, v224
	s_waitcnt lgkmcnt(0)
	s_nop 1
	v_mov_b32_dpp v6, v4 quad_perm:[1,0,3,2] row_mask:0xf bank_mask:0xf
	v_mov_b32_e32 v7, v1
	s_waitcnt lgkmcnt(0)
	v_cvt_pk_fp8_f32 v7, v4, v6
	v_and_b32_e32 v4, 0xffff, v7
	s_nop 1
	v_mov_b32_dpp v6, v4 quad_perm:[2,3,0,1] row_mask:0xf bank_mask:0xf
	s_and_saveexec_b64 s[6:7], vcc
	s_cbranch_execz .LBB0_3401
	s_waitcnt lgkmcnt(0)
	v_lshl_or_b32 v4, v6, 16, v4
	global_store_dword v[2:3], v4, off offset:32
.LBB0_3401:
	s_or_b64 exec, exec, s[6:7]
	v_mul_f32_e32 v4, v46, v0
	v_mul_f32_e32 v4, 0x41800000, v4
	v_med3_f32 v4, v4, s72, v224
	s_waitcnt lgkmcnt(0)
	s_nop 1
	v_mov_b32_dpp v6, v4 quad_perm:[1,0,3,2] row_mask:0xf bank_mask:0xf
	v_mov_b32_e32 v7, v1
	s_waitcnt lgkmcnt(0)
	v_cvt_pk_fp8_f32 v7, v4, v6
	v_and_b32_e32 v4, 0xffff, v7
	s_nop 1
	v_mov_b32_dpp v6, v4 quad_perm:[2,3,0,1] row_mask:0xf bank_mask:0xf
	s_and_saveexec_b64 s[6:7], vcc
	s_cbranch_execz .LBB0_3403
	s_waitcnt lgkmcnt(0)
	v_lshl_or_b32 v4, v6, 16, v4
	global_store_dword v[2:3], v4, off offset:64
.LBB0_3403:
	s_or_b64 exec, exec, s[6:7]
	v_mul_f32_e32 v0, v30, v0
	v_mul_f32_e32 v0, 0x41800000, v0
	v_med3_f32 v0, v0, s72, v224
	s_nop 1
	v_mov_b32_dpp v4, v0 quad_perm:[1,0,3,2] row_mask:0xf bank_mask:0xf
	s_waitcnt lgkmcnt(1)
	v_mov_b32_e32 v6, v1
	s_waitcnt lgkmcnt(0)
	v_cvt_pk_fp8_f32 v6, v0, v4
	v_and_b32_e32 v0, 0xffff, v6
	s_nop 1
	v_mov_b32_dpp v4, v0 quad_perm:[2,3,0,1] row_mask:0xf bank_mask:0xf
	s_and_saveexec_b64 s[6:7], vcc
	s_cbranch_execz .LBB0_3405
	s_waitcnt lgkmcnt(0)
	v_lshl_or_b32 v0, v4, 16, v0
	global_store_dword v[2:3], v0, off offset:96
.LBB0_3405:
	s_or_b64 exec, exec, s[6:7]
	v_rcp_f32_e32 v0, v5
	s_waitcnt lgkmcnt(0)
	v_mov_b32_e32 v4, v1
	v_mul_f32_e32 v2, v79, v0
	v_mul_f32_e32 v2, 0x41800000, v2
	v_med3_f32 v2, v2, s72, v224
	s_nop 1
	v_mov_b32_dpp v3, v2 quad_perm:[1,0,3,2] row_mask:0xf bank_mask:0xf
	s_waitcnt lgkmcnt(0)
	v_cvt_pk_fp8_f32 v4, v2, v3
	v_lshlrev_b64 v[2:3], 11, v[14:15]
	v_lshl_add_u64 v[2:3], v[84:85], 0, v[2:3]
	v_lshl_add_u64 v[2:3], v[2:3], 0, s[44:45]
	v_and_b32_e32 v4, 0xffff, v4
	s_nop 1
	v_mov_b32_dpp v5, v4 quad_perm:[2,3,0,1] row_mask:0xf bank_mask:0xf
	s_and_saveexec_b64 s[6:7], vcc
	s_cbranch_execz .LBB0_3407
	s_waitcnt lgkmcnt(0)
	v_lshl_or_b32 v4, v5, 16, v4
	global_store_dword v[2:3], v4, off
.LBB0_3407:
	s_or_b64 exec, exec, s[6:7]
	v_mul_f32_e32 v4, v63, v0
	v_mul_f32_e32 v4, 0x41800000, v4
	v_med3_f32 v4, v4, s72, v224
	s_waitcnt lgkmcnt(0)
	s_nop 1
	v_mov_b32_dpp v5, v4 quad_perm:[1,0,3,2] row_mask:0xf bank_mask:0xf
	v_mov_b32_e32 v6, v1
	s_waitcnt lgkmcnt(0)
	v_cvt_pk_fp8_f32 v6, v4, v5
	v_and_b32_e32 v4, 0xffff, v6
	s_nop 1
	v_mov_b32_dpp v5, v4 quad_perm:[2,3,0,1] row_mask:0xf bank_mask:0xf
	s_and_saveexec_b64 s[6:7], vcc
	s_cbranch_execz .LBB0_3409
	s_waitcnt lgkmcnt(0)
	v_lshl_or_b32 v4, v5, 16, v4
	global_store_dword v[2:3], v4, off offset:32
.LBB0_3409:
	s_or_b64 exec, exec, s[6:7]
	v_mul_f32_e32 v4, v47, v0
	v_mul_f32_e32 v4, 0x41800000, v4
	v_med3_f32 v4, v4, s72, v224
	s_waitcnt lgkmcnt(0)
	s_nop 1
	v_mov_b32_dpp v5, v4 quad_perm:[1,0,3,2] row_mask:0xf bank_mask:0xf
	v_mov_b32_e32 v6, v1
	s_waitcnt lgkmcnt(0)
	v_cvt_pk_fp8_f32 v6, v4, v5
	v_and_b32_e32 v4, 0xffff, v6
	s_nop 1
	v_mov_b32_dpp v5, v4 quad_perm:[2,3,0,1] row_mask:0xf bank_mask:0xf
	s_and_saveexec_b64 s[6:7], vcc
	s_cbranch_execz .LBB0_3411
	s_waitcnt lgkmcnt(0)
	v_lshl_or_b32 v4, v5, 16, v4
	global_store_dword v[2:3], v4, off offset:64
.LBB0_3411:
	s_or_b64 exec, exec, s[6:7]
	v_mul_f32_e32 v0, v31, v0
	v_mul_f32_e32 v0, 0x41800000, v0
	v_med3_f32 v0, v0, s72, v224
	s_nop 1
	v_mov_b32_dpp v4, v0 quad_perm:[1,0,3,2] row_mask:0xf bank_mask:0xf
	s_waitcnt lgkmcnt(1)
	v_mov_b32_e32 v5, v1
	s_waitcnt lgkmcnt(0)
	v_cvt_pk_fp8_f32 v5, v0, v4
	v_and_b32_e32 v0, 0xffff, v5
	s_nop 1
	v_mov_b32_dpp v4, v0 quad_perm:[2,3,0,1] row_mask:0xf bank_mask:0xf
	s_and_saveexec_b64 s[6:7], vcc
	s_cbranch_execz .LBB0_3413
	s_waitcnt lgkmcnt(0)
	v_lshl_or_b32 v0, v4, 16, v0
	global_store_dword v[2:3], v0, off offset:96

; #define SBAR() __builtin_amdgcn_sched_barrier(0)
; __device__ __forceinline__ int crow(int r, int hi) { return (r & 3) + 8 * (r >> 2) + 4 * hi; }
; #define SEAM_K0() do { VMWN(NQR); if constexpr (C::F8QK) { const int nb_ = ((NT & 1) == 0) ? NX3(bq) : bq; char* kb_ = KB3(nb_);     \
;                            *(bf16x8*)(kb_ + kr * K8P + kc * 16) = S.st_k0; if (kr < 32) *(bf16x8*)(kb_ + (2 * kr + (kc >> 2)) * K8P + 128 + (kc & 3) * 16) = S.st_kp; S.b0 = nb_; }  \
;                        else SWRITE_HK(0); SBAR(); } while (0)
; template <int MODE>
; __device__ __forceinline__ void attn_block(const AttnArgs& a, const BlockRef& cur, const BlockRef& nxt, char* lds, Seam<MODE>& S, const int tid) {
;     ...
;     SBAR(); SEAM_K0();
;     if constexpr (NQR < NQ) {
; #pragma unroll
;         for (int d0 = NQR; d0 < NQ; ++d0) S.qr[d0] = load8(a.Q + (size_t)(nq_ + wid * QBLK + r32) * C::DK + d0 * 16 + hi * 8);
;         SBAR(); }
;     if (hi == 0) li_l[r32] = l_reg; asm volatile("s_waitcnt lgkmcnt(0)" ::: "memory");
;     float rli[16];
; #pragma unroll
;     for (int r = 0; r < 16; ++r) rli[r] = __builtin_amdgcn_rcpf(li_l[crow(r, hi)]) * (C::F8PV ? 0.125f : 1.0f);
;     int orow_ = cur.orow, hcol_ = cur.hcol; asm volatile("" : "+s"(orow_), "+s"(hcol_));
;     if (a.o8 != 0.f) {
;         unsigned char* Ob = (unsigned char*)a.O + (size_t)(orow_ + wid * QBLK) * ldo + hcol_; const float os = a.o8;
; #pragma unroll
;         for (int r = 0; r < 16; ++r) { const int orow = crow(r, hi);
; #pragma unroll
;             for (int d0 = 0; d0 < 4; ++d0) { const float v = __builtin_amdgcn_fmed3f(o[d0][r] * rli[r] * os, -448.f, 448.f);
;                 const float vn = __shfl_xor(v, 1);
;                 const int pk = __builtin_amdgcn_cvt_pk_fp8_f32(v, vn, 0, false) & 0xffff; const int pk2 = __shfl_xor(pk, 2);
;                 if ((r32 & 3) == 0) *(unsigned*)(Ob + (size_t)orow * ldo + d0 * 32 + r32) = (unsigned)pk | ((unsigned)pk2 << 16); } }
.LBB0_3485:
	v_lshlrev_b32_e32 v18, 8, v148
	v_bitop3_b32 v17, v30, v17, s61 bitop3:0x78
	s_waitcnt vmcnt(8)
	v_add3_u32 v17, 0, v18, v17
	s_waitcnt vmcnt(9)
	ds_write_b128 v17, v[2:5] offset:32768
	s_waitcnt vmcnt(8)
	ds_write_b128 v17, v[6:9] offset:40960
	v_cmp_gt_u32_e32 vcc, 32, v15
	s_and_saveexec_b64 s[4:5], vcc
	v_lshl_add_u32 v17, v0, 2, s48
	ds_write_b32 v17, v31
	s_or_b64 exec, exec, s[4:5]
	s_waitcnt lgkmcnt(0)
	v_lshl_add_u32 v17, v14, 2, s48
	ds_read_b128 v[96:99], v17
	ds_read_b128 v[26:29], v17 offset:32
	ds_read_b128 v[22:25], v17 offset:64
	ds_read_b128 v[18:21], v17 offset:96
	v_and_b32_e32 v30, 64, v220
	s_waitcnt lgkmcnt(3)
	v_rcp_f32_e32 v102, v96
	v_xor_b32_e32 v17, 1, v220
	v_add_u32_e32 v30, 64, v30
	v_cmp_lt_i32_e32 vcc, v17, v30
	v_mul_f32_e32 v31, v80, v102
	v_mul_f32_e32 v31, 0x41800000, v31
	v_cndmask_b32_e32 v17, v220, v17, vcc
	v_lshlrev_b32_e32 v17, 2, v17
	v_med3_f32 v31, v31, s65, v221
	s_nop 1
	v_mov_b32_dpp v80, v31 quad_perm:[1,0,3,2] row_mask:0xf bank_mask:0xf
	v_mov_b32_e32 v100, v1
	s_add_i32 s4, s73, s74
	v_xor_b32_e32 v96, 2, v220
	s_waitcnt lgkmcnt(0)
	v_cvt_pk_fp8_f32 v100, v31, v80
	s_ashr_i32 s5, s4, 31
	v_cmp_lt_i32_e32 vcc, v96, v30
	s_lshl_b64 s[4:5], s[4:5], 11
	s_ashr_i32 s6, s72, 31
	v_cndmask_b32_e32 v30, v220, v96, vcc
	s_add_u32 s4, s50, s4
	v_lshlrev_b32_e32 v96, 2, v30
	v_and_b32_e32 v80, 0xffff, v100
	s_addc_u32 s5, s51, s5
	s_nop 1
	v_mov_b32_dpp v103, v80 quad_perm:[2,3,0,1] row_mask:0xf bank_mask:0xf
	s_add_u32 s4, s4, s72
	v_and_b32_e32 v15, 3, v15
	s_addc_u32 s5, s5, s6
	v_cmp_eq_u32_e32 vcc, 0, v15
	v_ashrrev_i32_e32 v15, 31, v14
	v_lshl_add_u64 v[30:31], s[4:5], 0, v[0:1]
	v_lshlrev_b64 v[100:101], 11, v[14:15]
	v_lshl_add_u64 v[100:101], v[30:31], 0, v[100:101]
	s_and_saveexec_b64 s[4:5], vcc
	s_cbranch_execz .LBB0_3489
	s_waitcnt lgkmcnt(0)
	v_lshl_or_b32 v0, v103, 16, v80
	global_store_dword v[100:101], v0, off
.LBB0_3489:
	s_or_b64 exec, exec, s[4:5]
	v_mul_f32_e32 v0, v64, v102
	v_mul_f32_e32 v0, 0x41800000, v0
	v_med3_f32 v0, v0, s65, v221
	s_nop 1
	v_mov_b32_dpp v64, v0 quad_perm:[1,0,3,2] row_mask:0xf bank_mask:0xf
	v_mov_b32_e32 v80, v1
	s_waitcnt lgkmcnt(0)
	v_cvt_pk_fp8_f32 v80, v0, v64
	v_and_b32_e32 v0, 0xffff, v80
	s_nop 1
	v_mov_b32_dpp v64, v0 quad_perm:[2,3,0,1] row_mask:0xf bank_mask:0xf
	s_and_saveexec_b64 s[4:5], vcc
	s_cbranch_execz .LBB0_3491
	s_waitcnt lgkmcnt(0)
	v_lshl_or_b32 v0, v64, 16, v0
	global_store_dword v[100:101], v0, off offset:32
.LBB0_3491:
	s_or_b64 exec, exec, s[4:5]
	v_mul_f32_e32 v0, v48, v102
	v_mul_f32_e32 v0, 0x41800000, v0
	v_med3_f32 v0, v0, s65, v221
	s_nop 1
	v_mov_b32_dpp v48, v0 quad_perm:[1,0,3,2] row_mask:0xf bank_mask:0xf
	s_waitcnt lgkmcnt(1)
	v_mov_b32_e32 v64, v1
	s_waitcnt lgkmcnt(0)
	v_cvt_pk_fp8_f32 v64, v0, v48
	v_and_b32_e32 v0, 0xffff, v64
	s_nop 1
	v_mov_b32_dpp v48, v0 quad_perm:[2,3,0,1] row_mask:0xf bank_mask:0xf
	s_and_saveexec_b64 s[4:5], vcc
	s_cbranch_execz .LBB0_3493
	s_waitcnt lgkmcnt(0)
	v_lshl_or_b32 v0, v48, 16, v0
	global_store_dword v[100:101], v0, off offset:64
.LBB0_3493:
	s_or_b64 exec, exec, s[4:5]
	v_mul_f32_e32 v0, v32, v102
	v_mul_f32_e32 v0, 0x41800000, v0
	v_med3_f32 v0, v0, s65, v221
	s_nop 1
	v_mov_b32_dpp v32, v0 quad_perm:[1,0,3,2] row_mask:0xf bank_mask:0xf
	s_waitcnt lgkmcnt(1)
	v_mov_b32_e32 v48, v1
	s_waitcnt lgkmcnt(0)
	v_cvt_pk_fp8_f32 v48, v0, v32
	v_and_b32_e32 v0, 0xffff, v48
	s_nop 1
	v_mov_b32_dpp v32, v0 quad_perm:[2,3,0,1] row_mask:0xf bank_mask:0xf
	s_and_saveexec_b64 s[4:5], vcc
	s_cbranch_execz .LBB0_3495
	s_waitcnt lgkmcnt(0)
	v_lshl_or_b32 v0, v32, 16, v0
	global_store_dword v[100:101], v0, off offset:96
.LBB0_3495:
	s_or_b64 exec, exec, s[4:5]
	v_rcp_f32_e32 v0, v97
	v_mov_b32_e32 v64, v1
	v_or_b32_e32 v80, 1, v14
	s_waitcnt lgkmcnt(0)
	v_mul_f32_e32 v32, v81, v0
	v_mul_f32_e32 v32, 0x41800000, v32
	v_med3_f32 v32, v32, s65, v221
	s_nop 1
	v_mov_b32_dpp v48, v32 quad_perm:[1,0,3,2] row_mask:0xf bank_mask:0xf
	v_ashrrev_i32_e32 v81, 31, v80
	v_lshlrev_b64 v[80:81], 11, v[80:81]
	v_lshl_add_u64 v[80:81], v[30:31], 0, v[80:81]
	s_waitcnt lgkmcnt(0)
	v_cvt_pk_fp8_f32 v64, v32, v48
	v_and_b32_e32 v32, 0xffff, v64
	s_nop 1
	v_mov_b32_dpp v48, v32 quad_perm:[2,3,0,1] row_mask:0xf bank_mask:0xf
	s_and_saveexec_b64 s[4:5], vcc
	s_cbranch_execz .LBB0_3497
	s_waitcnt lgkmcnt(0)
	v_lshl_or_b32 v32, v48, 16, v32
	global_store_dword v[80:81], v32, off
.LBB0_3497:
	s_or_b64 exec, exec, s[4:5]
	v_mul_f32_e32 v32, v65, v0
	v_mul_f32_e32 v32, 0x41800000, v32
	v_med3_f32 v32, v32, s65, v221
	s_waitcnt lgkmcnt(0)
	s_nop 1
	v_mov_b32_dpp v48, v32 quad_perm:[1,0,3,2] row_mask:0xf bank_mask:0xf
	v_mov_b32_e32 v64, v1
	s_waitcnt lgkmcnt(0)
	v_cvt_pk_fp8_f32 v64, v32, v48
	v_and_b32_e32 v32, 0xffff, v64
	s_nop 1
	v_mov_b32_dpp v48, v32 quad_perm:[2,3,0,1] row_mask:0xf bank_mask:0xf
	s_and_saveexec_b64 s[4:5], vcc
	s_cbranch_execz .LBB0_3499
	s_waitcnt lgkmcnt(0)
	v_lshl_or_b32 v32, v48, 16, v32
	global_store_dword v[80:81], v32, off offset:32
.LBB0_3499:
	s_or_b64 exec, exec, s[4:5]
	v_mul_f32_e32 v32, v49, v0
	v_mul_f32_e32 v32, 0x41800000, v32
	v_med3_f32 v32, v32, s65, v221
	s_waitcnt lgkmcnt(0)
	s_nop 1
	v_mov_b32_dpp v48, v32 quad_perm:[1,0,3,2] row_mask:0xf bank_mask:0xf
	v_mov_b32_e32 v49, v1
	s_waitcnt lgkmcnt(0)
	v_cvt_pk_fp8_f32 v49, v32, v48
	v_and_b32_e32 v32, 0xffff, v49
	s_nop 1
	v_mov_b32_dpp v48, v32 quad_perm:[2,3,0,1] row_mask:0xf bank_mask:0xf
	s_and_saveexec_b64 s[4:5], vcc
	s_cbranch_execz .LBB0_3501
	s_waitcnt lgkmcnt(0)
	v_lshl_or_b32 v32, v48, 16, v32
	global_store_dword v[80:81], v32, off offset:64
; __device__ __forceinline__ int crow(int r, int hi) { return (r & 3) + 8 * (r >> 2) + 4 * hi; }
; template <int MODE>
; __device__ __forceinline__ void attn_block(const AttnArgs& a, const BlockRef& cur, const BlockRef& nxt, char* lds, Seam<MODE>& S, const int tid) {
;     ...
;     if (a.o8 != 0.f) {
;         unsigned char* Ob = (unsigned char*)a.O + (size_t)(orow_ + wid * QBLK) * ldo + hcol_; const float os = a.o8;
; #pragma unroll
;         for (int r = 0; r < 16; ++r) { const int orow = crow(r, hi);
; #pragma unroll
;             for (int d0 = 0; d0 < 4; ++d0) { const float v = __builtin_amdgcn_fmed3f(o[d0][r] * rli[r] * os, -448.f, 448.f);
;                 const float vn = __shfl_xor(v, 1);
;                 const int pk = __builtin_amdgcn_cvt_pk_fp8_f32(v, vn, 0, false) & 0xffff; const int pk2 = __shfl_xor(pk, 2);
;                 if ((r32 & 3) == 0) *(unsigned*)(Ob + (size_t)orow * ldo + d0 * 32 + r32) = (unsigned)pk | ((unsigned)pk2 << 16); } }
.LBB0_3501:
	s_or_b64 exec, exec, s[4:5]
	v_mul_f32_e32 v0, v33, v0
	v_mul_f32_e32 v0, 0x41800000, v0
	v_med3_f32 v0, v0, s65, v221
	s_nop 1
	v_mov_b32_dpp v32, v0 quad_perm:[1,0,3,2] row_mask:0xf bank_mask:0xf
	v_mov_b32_e32 v33, v1
	s_waitcnt lgkmcnt(0)
	v_cvt_pk_fp8_f32 v33, v0, v32
	v_and_b32_e32 v0, 0xffff, v33
	s_nop 1
	v_mov_b32_dpp v32, v0 quad_perm:[2,3,0,1] row_mask:0xf bank_mask:0xf
	s_and_saveexec_b64 s[4:5], vcc
	s_cbranch_execz .LBB0_3503
	s_waitcnt lgkmcnt(0)
	v_lshl_or_b32 v0, v32, 16, v0
	global_store_dword v[80:81], v0, off offset:96
.LBB0_3503:
	s_or_b64 exec, exec, s[4:5]
	v_rcp_f32_e32 v0, v98
	v_mov_b32_e32 v48, v1
	s_waitcnt lgkmcnt(0)
	v_mul_f32_e32 v32, v82, v0
	v_mul_f32_e32 v32, 0x41800000, v32
	v_med3_f32 v32, v32, s65, v221
	s_nop 1
	v_mov_b32_dpp v33, v32 quad_perm:[1,0,3,2] row_mask:0xf bank_mask:0xf
	s_waitcnt lgkmcnt(0)
	v_cvt_pk_fp8_f32 v48, v32, v33
	v_or_b32_e32 v32, 2, v14
	v_ashrrev_i32_e32 v33, 31, v32
	v_lshlrev_b64 v[32:33], 11, v[32:33]
	v_and_b32_e32 v48, 0xffff, v48
	s_nop 1
	v_mov_b32_dpp v49, v48 quad_perm:[2,3,0,1] row_mask:0xf bank_mask:0xf
	v_lshl_add_u64 v[32:33], v[30:31], 0, v[32:33]
	s_and_saveexec_b64 s[4:5], vcc
	s_cbranch_execz .LBB0_3505
	s_waitcnt lgkmcnt(0)
	v_lshl_or_b32 v48, v49, 16, v48
	global_store_dword v[32:33], v48, off
.LBB0_3505:
	s_or_b64 exec, exec, s[4:5]
	v_mul_f32_e32 v48, v66, v0
	v_mul_f32_e32 v48, 0x41800000, v48
	v_med3_f32 v48, v48, s65, v221
	s_waitcnt lgkmcnt(0)
	s_nop 1
	v_mov_b32_dpp v49, v48 quad_perm:[1,0,3,2] row_mask:0xf bank_mask:0xf
	v_mov_b32_e32 v64, v1
	s_waitcnt lgkmcnt(0)
	v_cvt_pk_fp8_f32 v64, v48, v49
	v_and_b32_e32 v48, 0xffff, v64
	s_nop 1
	v_mov_b32_dpp v49, v48 quad_perm:[2,3,0,1] row_mask:0xf bank_mask:0xf
	s_and_saveexec_b64 s[4:5], vcc
	s_cbranch_execz .LBB0_3507
	s_waitcnt lgkmcnt(0)
	v_lshl_or_b32 v48, v49, 16, v48
	global_store_dword v[32:33], v48, off offset:32
.LBB0_3507:
	s_or_b64 exec, exec, s[4:5]
	v_mul_f32_e32 v48, v50, v0
	v_mul_f32_e32 v48, 0x41800000, v48
	v_med3_f32 v48, v48, s65, v221
	s_waitcnt lgkmcnt(0)
	s_nop 1
	v_mov_b32_dpp v49, v48 quad_perm:[1,0,3,2] row_mask:0xf bank_mask:0xf
	v_mov_b32_e32 v50, v1
	s_waitcnt lgkmcnt(0)
	v_cvt_pk_fp8_f32 v50, v48, v49
	v_and_b32_e32 v48, 0xffff, v50
	s_nop 1
	v_mov_b32_dpp v49, v48 quad_perm:[2,3,0,1] row_mask:0xf bank_mask:0xf
	s_and_saveexec_b64 s[4:5], vcc
	s_cbranch_execz .LBB0_3509
	s_waitcnt lgkmcnt(0)
	v_lshl_or_b32 v48, v49, 16, v48
	global_store_dword v[32:33], v48, off offset:64
.LBB0_3509:
	s_or_b64 exec, exec, s[4:5]
	v_mul_f32_e32 v0, v34, v0
	v_mul_f32_e32 v0, 0x41800000, v0
	v_med3_f32 v0, v0, s65, v221
	s_nop 1
	v_mov_b32_dpp v34, v0 quad_perm:[1,0,3,2] row_mask:0xf bank_mask:0xf
	v_mov_b32_e32 v48, v1
	s_waitcnt lgkmcnt(0)
	v_cvt_pk_fp8_f32 v48, v0, v34
	v_and_b32_e32 v0, 0xffff, v48
	s_nop 1
	v_mov_b32_dpp v34, v0 quad_perm:[2,3,0,1] row_mask:0xf bank_mask:0xf
	s_and_saveexec_b64 s[4:5], vcc
	s_cbranch_execz .LBB0_3511
	s_waitcnt lgkmcnt(0)
	v_lshl_or_b32 v0, v34, 16, v0
	global_store_dword v[32:33], v0, off offset:96
.LBB0_3511:
	s_or_b64 exec, exec, s[4:5]
	v_rcp_f32_e32 v0, v99
	s_waitcnt lgkmcnt(0)
	v_mov_b32_e32 v34, v1
	v_mul_f32_e32 v32, v83, v0
	v_mul_f32_e32 v32, 0x41800000, v32
	v_med3_f32 v32, v32, s65, v221
	s_nop 1
	v_mov_b32_dpp v33, v32 quad_perm:[1,0,3,2] row_mask:0xf bank_mask:0xf
	s_waitcnt lgkmcnt(0)
	v_cvt_pk_fp8_f32 v34, v32, v33
	v_or_b32_e32 v32, 3, v14
	v_ashrrev_i32_e32 v33, 31, v32
	v_lshlrev_b64 v[32:33], 11, v[32:33]
	v_and_b32_e32 v34, 0xffff, v34
	s_nop 1
	v_mov_b32_dpp v48, v34 quad_perm:[2,3,0,1] row_mask:0xf bank_mask:0xf
	v_lshl_add_u64 v[32:33], v[30:31], 0, v[32:33]
	s_and_saveexec_b64 s[4:5], vcc
	s_cbranch_execz .LBB0_3513
	s_waitcnt lgkmcnt(0)
	v_lshl_or_b32 v34, v48, 16, v34
	global_store_dword v[32:33], v34, off
.LBB0_3513:
	s_or_b64 exec, exec, s[4:5]
	v_mul_f32_e32 v34, v67, v0
	v_mul_f32_e32 v34, 0x41800000, v34
	v_med3_f32 v34, v34, s65, v221
	s_waitcnt lgkmcnt(0)
	s_nop 1
	v_mov_b32_dpp v48, v34 quad_perm:[1,0,3,2] row_mask:0xf bank_mask:0xf
	v_mov_b32_e32 v49, v1
	s_waitcnt lgkmcnt(0)
	v_cvt_pk_fp8_f32 v49, v34, v48
	v_and_b32_e32 v34, 0xffff, v49
	s_nop 1
	v_mov_b32_dpp v48, v34 quad_perm:[2,3,0,1] row_mask:0xf bank_mask:0xf
	s_and_saveexec_b64 s[4:5], vcc
	s_cbranch_execz .LBB0_3515
	s_waitcnt lgkmcnt(0)
	v_lshl_or_b32 v34, v48, 16, v34
	global_store_dword v[32:33], v34, off offset:32
.LBB0_3515:
	s_or_b64 exec, exec, s[4:5]
	v_mul_f32_e32 v34, v51, v0
	v_mul_f32_e32 v34, 0x41800000, v34
	v_med3_f32 v34, v34, s65, v221
	s_waitcnt lgkmcnt(0)
	s_nop 1
	v_mov_b32_dpp v48, v34 quad_perm:[1,0,3,2] row_mask:0xf bank_mask:0xf
	v_mov_b32_e32 v49, v1
	s_waitcnt lgkmcnt(0)
	v_cvt_pk_fp8_f32 v49, v34, v48
	v_and_b32_e32 v34, 0xffff, v49
	s_nop 1
	v_mov_b32_dpp v48, v34 quad_perm:[2,3,0,1] row_mask:0xf bank_mask:0xf
	s_and_saveexec_b64 s[4:5], vcc
	s_cbranch_execz .LBB0_3517
	s_waitcnt lgkmcnt(0)
	v_lshl_or_b32 v34, v48, 16, v34
	global_store_dword v[32:33], v34, off offset:64
.LBB0_3517:
	s_or_b64 exec, exec, s[4:5]
	v_mul_f32_e32 v0, v35, v0
	v_mul_f32_e32 v0, 0x41800000, v0
	v_med3_f32 v0, v0, s65, v221
	s_nop 1
	v_mov_b32_dpp v34, v0 quad_perm:[1,0,3,2] row_mask:0xf bank_mask:0xf
	v_mov_b32_e32 v35, v1
	s_waitcnt lgkmcnt(0)
	v_cvt_pk_fp8_f32 v35, v0, v34
	v_and_b32_e32 v0, 0xffff, v35
	s_nop 1
	v_mov_b32_dpp v34, v0 quad_perm:[2,3,0,1] row_mask:0xf bank_mask:0xf
	s_and_saveexec_b64 s[4:5], vcc
	s_cbranch_execz .LBB0_3519
	s_waitcnt lgkmcnt(0)
	v_lshl_or_b32 v0, v34, 16, v0
	global_store_dword v[32:33], v0, off offset:96
; __device__ __forceinline__ int crow(int r, int hi) { return (r & 3) + 8 * (r >> 2) + 4 * hi; }
; template <int MODE>
; __device__ __forceinline__ void attn_block(const AttnArgs& a, const BlockRef& cur, const BlockRef& nxt, char* lds, Seam<MODE>& S, const int tid) {
;     ...
;     if (a.o8 != 0.f) {
;         unsigned char* Ob = (unsigned char*)a.O + (size_t)(orow_ + wid * QBLK) * ldo + hcol_; const float os = a.o8;
; #pragma unroll
;         for (int r = 0; r < 16; ++r) { const int orow = crow(r, hi);
; #pragma unroll
;             for (int d0 = 0; d0 < 4; ++d0) { const float v = __builtin_amdgcn_fmed3f(o[d0][r] * rli[r] * os, -448.f, 448.f);
;                 const float vn = __shfl_xor(v, 1);
;                 const int pk = __builtin_amdgcn_cvt_pk_fp8_f32(v, vn, 0, false) & 0xffff; const int pk2 = __shfl_xor(pk, 2);
;                 if ((r32 & 3) == 0) *(unsigned*)(Ob + (size_t)orow * ldo + d0 * 32 + r32) = (unsigned)pk | ((unsigned)pk2 << 16); } }
.LBB0_3519:
	s_or_b64 exec, exec, s[4:5]
	v_rcp_f32_e32 v0, v26
	v_mov_b32_e32 v33, v1
	v_mul_f32_e32 v26, v84, v0
	v_mul_f32_e32 v26, 0x41800000, v26
	v_med3_f32 v26, v26, s65, v221
	s_nop 1
	v_mov_b32_dpp v32, v26 quad_perm:[1,0,3,2] row_mask:0xf bank_mask:0xf
	s_waitcnt lgkmcnt(0)
	v_cvt_pk_fp8_f32 v33, v26, v32
	v_and_b32_e32 v26, 0xffff, v33
	s_nop 1
	v_mov_b32_dpp v34, v26 quad_perm:[2,3,0,1] row_mask:0xf bank_mask:0xf
	v_lshlrev_b64 v[32:33], 11, v[14:15]
	v_lshl_add_u64 v[32:33], v[30:31], 0, v[32:33]
	v_lshl_add_u64 v[32:33], v[32:33], 0, s[14:15]
	s_and_saveexec_b64 s[4:5], vcc
	s_cbranch_execz .LBB0_3521
	s_waitcnt lgkmcnt(0)
	v_lshl_or_b32 v26, v34, 16, v26
	global_store_dword v[32:33], v26, off
.LBB0_3521:
	s_or_b64 exec, exec, s[4:5]
	v_mul_f32_e32 v26, v68, v0
	v_mul_f32_e32 v26, 0x41800000, v26
	v_med3_f32 v26, v26, s65, v221
	s_waitcnt lgkmcnt(0)
	s_nop 1
	v_mov_b32_dpp v34, v26 quad_perm:[1,0,3,2] row_mask:0xf bank_mask:0xf
	v_mov_b32_e32 v35, v1
	s_waitcnt lgkmcnt(0)
	v_cvt_pk_fp8_f32 v35, v26, v34
	v_and_b32_e32 v26, 0xffff, v35
	s_nop 1
	v_mov_b32_dpp v34, v26 quad_perm:[2,3,0,1] row_mask:0xf bank_mask:0xf
	s_and_saveexec_b64 s[4:5], vcc
	s_cbranch_execz .LBB0_3523
	s_waitcnt lgkmcnt(0)
	v_lshl_or_b32 v26, v34, 16, v26
	global_store_dword v[32:33], v26, off offset:32
.LBB0_3523:
	s_or_b64 exec, exec, s[4:5]
	v_mul_f32_e32 v26, v52, v0
	v_mul_f32_e32 v26, 0x41800000, v26
	v_med3_f32 v26, v26, s65, v221
	s_waitcnt lgkmcnt(0)
	s_nop 1
	v_mov_b32_dpp v34, v26 quad_perm:[1,0,3,2] row_mask:0xf bank_mask:0xf
	v_mov_b32_e32 v35, v1
	s_waitcnt lgkmcnt(0)
	v_cvt_pk_fp8_f32 v35, v26, v34
	v_and_b32_e32 v26, 0xffff, v35
	s_nop 1
	v_mov_b32_dpp v34, v26 quad_perm:[2,3,0,1] row_mask:0xf bank_mask:0xf
	s_and_saveexec_b64 s[4:5], vcc
	s_cbranch_execz .LBB0_3525
	s_waitcnt lgkmcnt(0)
	v_lshl_or_b32 v26, v34, 16, v26
	global_store_dword v[32:33], v26, off offset:64
.LBB0_3525:
	s_or_b64 exec, exec, s[4:5]
	v_mul_f32_e32 v0, v36, v0
	v_mul_f32_e32 v0, 0x41800000, v0
	v_med3_f32 v0, v0, s65, v221
	s_nop 1
	v_mov_b32_dpp v26, v0 quad_perm:[1,0,3,2] row_mask:0xf bank_mask:0xf
	s_waitcnt lgkmcnt(1)
	v_mov_b32_e32 v34, v1
	s_waitcnt lgkmcnt(0)
	v_cvt_pk_fp8_f32 v34, v0, v26
	v_and_b32_e32 v0, 0xffff, v34
	s_nop 1
	v_mov_b32_dpp v26, v0 quad_perm:[2,3,0,1] row_mask:0xf bank_mask:0xf
	s_and_saveexec_b64 s[4:5], vcc
	s_cbranch_execz .LBB0_3527
	s_waitcnt lgkmcnt(0)
	v_lshl_or_b32 v0, v26, 16, v0
	global_store_dword v[32:33], v0, off offset:96
.LBB0_3527:
	s_or_b64 exec, exec, s[4:5]
	v_rcp_f32_e32 v0, v27
	v_mov_b32_e32 v32, v1
	s_waitcnt lgkmcnt(0)
	v_mul_f32_e32 v26, v85, v0
	v_mul_f32_e32 v26, 0x41800000, v26
	v_med3_f32 v26, v26, s65, v221
	s_nop 1
	v_mov_b32_dpp v27, v26 quad_perm:[1,0,3,2] row_mask:0xf bank_mask:0xf
	s_waitcnt lgkmcnt(0)
	v_cvt_pk_fp8_f32 v32, v26, v27
	v_lshlrev_b64 v[26:27], 11, v[14:15]
	v_lshl_add_u64 v[26:27], v[30:31], 0, v[26:27]
	v_lshl_add_u64 v[26:27], v[26:27], 0, s[16:17]
	v_and_b32_e32 v32, 0xffff, v32
	s_nop 1
	v_mov_b32_dpp v33, v32 quad_perm:[2,3,0,1] row_mask:0xf bank_mask:0xf
	s_and_saveexec_b64 s[4:5], vcc
	s_cbranch_execz .LBB0_3529
	s_waitcnt lgkmcnt(0)
	v_lshl_or_b32 v32, v33, 16, v32
	global_store_dword v[26:27], v32, off
.LBB0_3529:
	s_or_b64 exec, exec, s[4:5]
	v_mul_f32_e32 v32, v69, v0
	v_mul_f32_e32 v32, 0x41800000, v32
	v_med3_f32 v32, v32, s65, v221
	s_waitcnt lgkmcnt(0)
	s_nop 1
	v_mov_b32_dpp v33, v32 quad_perm:[1,0,3,2] row_mask:0xf bank_mask:0xf
	v_mov_b32_e32 v34, v1
	s_waitcnt lgkmcnt(0)
	v_cvt_pk_fp8_f32 v34, v32, v33
	v_and_b32_e32 v32, 0xffff, v34
	s_nop 1
	v_mov_b32_dpp v33, v32 quad_perm:[2,3,0,1] row_mask:0xf bank_mask:0xf
	s_and_saveexec_b64 s[4:5], vcc
	s_cbranch_execz .LBB0_3531
	s_waitcnt lgkmcnt(0)
	v_lshl_or_b32 v32, v33, 16, v32
	global_store_dword v[26:27], v32, off offset:32
.LBB0_3531:
	s_or_b64 exec, exec, s[4:5]
	v_mul_f32_e32 v32, v53, v0
	v_mul_f32_e32 v32, 0x41800000, v32
	v_med3_f32 v32, v32, s65, v221
	s_waitcnt lgkmcnt(0)
	s_nop 1
	v_mov_b32_dpp v33, v32 quad_perm:[1,0,3,2] row_mask:0xf bank_mask:0xf
	v_mov_b32_e32 v34, v1
	s_waitcnt lgkmcnt(0)
	v_cvt_pk_fp8_f32 v34, v32, v33
	v_and_b32_e32 v32, 0xffff, v34
	s_nop 1
	v_mov_b32_dpp v33, v32 quad_perm:[2,3,0,1] row_mask:0xf bank_mask:0xf
	s_and_saveexec_b64 s[4:5], vcc
	s_cbranch_execz .LBB0_3533
	s_waitcnt lgkmcnt(0)
	v_lshl_or_b32 v32, v33, 16, v32
	global_store_dword v[26:27], v32, off offset:64
.LBB0_3533:
	s_or_b64 exec, exec, s[4:5]
	v_mul_f32_e32 v0, v37, v0
	v_mul_f32_e32 v0, 0x41800000, v0
	v_med3_f32 v0, v0, s65, v221
	s_nop 1
	v_mov_b32_dpp v32, v0 quad_perm:[1,0,3,2] row_mask:0xf bank_mask:0xf
	s_waitcnt lgkmcnt(1)
	v_mov_b32_e32 v33, v1
	s_waitcnt lgkmcnt(0)
	v_cvt_pk_fp8_f32 v33, v0, v32
	v_and_b32_e32 v0, 0xffff, v33
	s_nop 1
	v_mov_b32_dpp v32, v0 quad_perm:[2,3,0,1] row_mask:0xf bank_mask:0xf
	s_and_saveexec_b64 s[4:5], vcc
	s_cbranch_execz .LBB0_3535
	s_waitcnt lgkmcnt(0)
	v_lshl_or_b32 v0, v32, 16, v0
	global_store_dword v[26:27], v0, off offset:96
.LBB0_3535:
	s_or_b64 exec, exec, s[4:5]
	v_rcp_f32_e32 v0, v28
	v_mov_b32_e32 v28, v1
	v_mul_f32_e32 v26, v86, v0
	v_mul_f32_e32 v26, 0x41800000, v26
	v_med3_f32 v26, v26, s65, v221
	s_nop 1
	v_mov_b32_dpp v27, v26 quad_perm:[1,0,3,2] row_mask:0xf bank_mask:0xf
	s_waitcnt lgkmcnt(0)
	v_cvt_pk_fp8_f32 v28, v26, v27
	v_lshlrev_b64 v[26:27], 11, v[14:15]
	v_lshl_add_u64 v[26:27], v[30:31], 0, v[26:27]
	v_lshl_add_u64 v[26:27], v[26:27], 0, s[18:19]
	v_and_b32_e32 v28, 0xffff, v28
	s_nop 1
	v_mov_b32_dpp v32, v28 quad_perm:[2,3,0,1] row_mask:0xf bank_mask:0xf
	s_and_saveexec_b64 s[4:5], vcc
	s_cbranch_execz .LBB0_3537
	s_waitcnt lgkmcnt(0)
	v_lshl_or_b32 v28, v32, 16, v28
	global_store_dword v[26:27], v28, off
; __device__ __forceinline__ int crow(int r, int hi) { return (r & 3) + 8 * (r >> 2) + 4 * hi; }
; template <int MODE>
; __device__ __forceinline__ void attn_block(const AttnArgs& a, const BlockRef& cur, const BlockRef& nxt, char* lds, Seam<MODE>& S, const int tid) {
;     ...
;     if (a.o8 != 0.f) {
;         unsigned char* Ob = (unsigned char*)a.O + (size_t)(orow_ + wid * QBLK) * ldo + hcol_; const float os = a.o8;
; #pragma unroll
;         for (int r = 0; r < 16; ++r) { const int orow = crow(r, hi);
; #pragma unroll
;             for (int d0 = 0; d0 < 4; ++d0) { const float v = __builtin_amdgcn_fmed3f(o[d0][r] * rli[r] * os, -448.f, 448.f);
;                 const float vn = __shfl_xor(v, 1);
;                 const int pk = __builtin_amdgcn_cvt_pk_fp8_f32(v, vn, 0, false) & 0xffff; const int pk2 = __shfl_xor(pk, 2);
;                 if ((r32 & 3) == 0) *(unsigned*)(Ob + (size_t)orow * ldo + d0 * 32 + r32) = (unsigned)pk | ((unsigned)pk2 << 16); } }
.LBB0_3537:
	s_or_b64 exec, exec, s[4:5]
	v_mul_f32_e32 v28, v70, v0
	v_mul_f32_e32 v28, 0x41800000, v28
	v_med3_f32 v28, v28, s65, v221
	s_waitcnt lgkmcnt(0)
	s_nop 1
	v_mov_b32_dpp v32, v28 quad_perm:[1,0,3,2] row_mask:0xf bank_mask:0xf
	v_mov_b32_e32 v33, v1
	s_waitcnt lgkmcnt(0)
	v_cvt_pk_fp8_f32 v33, v28, v32
	v_and_b32_e32 v28, 0xffff, v33
	s_nop 1
	v_mov_b32_dpp v32, v28 quad_perm:[2,3,0,1] row_mask:0xf bank_mask:0xf
	s_and_saveexec_b64 s[4:5], vcc
	s_cbranch_execz .LBB0_3539
	s_waitcnt lgkmcnt(0)
	v_lshl_or_b32 v28, v32, 16, v28
	global_store_dword v[26:27], v28, off offset:32
.LBB0_3539:
	s_or_b64 exec, exec, s[4:5]
	v_mul_f32_e32 v28, v54, v0
	v_mul_f32_e32 v28, 0x41800000, v28
	v_med3_f32 v28, v28, s65, v221
	s_waitcnt lgkmcnt(0)
	s_nop 1
	v_mov_b32_dpp v32, v28 quad_perm:[1,0,3,2] row_mask:0xf bank_mask:0xf
	v_mov_b32_e32 v33, v1
	s_waitcnt lgkmcnt(0)
	v_cvt_pk_fp8_f32 v33, v28, v32
	v_and_b32_e32 v28, 0xffff, v33
	s_nop 1
	v_mov_b32_dpp v32, v28 quad_perm:[2,3,0,1] row_mask:0xf bank_mask:0xf
	s_and_saveexec_b64 s[4:5], vcc
	s_cbranch_execz .LBB0_3541
	s_waitcnt lgkmcnt(0)
	v_lshl_or_b32 v28, v32, 16, v28
	global_store_dword v[26:27], v28, off offset:64
.LBB0_3541:
	s_or_b64 exec, exec, s[4:5]
	v_mul_f32_e32 v0, v38, v0
	v_mul_f32_e32 v0, 0x41800000, v0
	v_med3_f32 v0, v0, s65, v221
	s_nop 1
	v_mov_b32_dpp v28, v0 quad_perm:[1,0,3,2] row_mask:0xf bank_mask:0xf
	s_waitcnt lgkmcnt(1)
	v_mov_b32_e32 v32, v1
	s_waitcnt lgkmcnt(0)
	v_cvt_pk_fp8_f32 v32, v0, v28
	v_and_b32_e32 v0, 0xffff, v32
	s_nop 1
	v_mov_b32_dpp v28, v0 quad_perm:[2,3,0,1] row_mask:0xf bank_mask:0xf
	s_and_saveexec_b64 s[4:5], vcc
	s_cbranch_execz .LBB0_3543
	s_waitcnt lgkmcnt(0)
	v_lshl_or_b32 v0, v28, 16, v0
	global_store_dword v[26:27], v0, off offset:96
.LBB0_3543:
	s_or_b64 exec, exec, s[4:5]
	v_rcp_f32_e32 v0, v29
	s_waitcnt lgkmcnt(0)
	v_mov_b32_e32 v28, v1
	v_mul_f32_e32 v26, v87, v0
	v_mul_f32_e32 v26, 0x41800000, v26
	v_med3_f32 v26, v26, s65, v221
	s_nop 1
	v_mov_b32_dpp v27, v26 quad_perm:[1,0,3,2] row_mask:0xf bank_mask:0xf
	s_waitcnt lgkmcnt(0)
	v_cvt_pk_fp8_f32 v28, v26, v27
	v_lshlrev_b64 v[26:27], 11, v[14:15]
	v_lshl_add_u64 v[26:27], v[30:31], 0, v[26:27]
	v_lshl_add_u64 v[26:27], v[26:27], 0, s[20:21]
	v_and_b32_e32 v28, 0xffff, v28
	s_nop 1
	v_mov_b32_dpp v29, v28 quad_perm:[2,3,0,1] row_mask:0xf bank_mask:0xf
	s_and_saveexec_b64 s[4:5], vcc
	s_cbranch_execz .LBB0_3545
	s_waitcnt lgkmcnt(0)
	v_lshl_or_b32 v28, v29, 16, v28
	global_store_dword v[26:27], v28, off
.LBB0_3545:
	s_or_b64 exec, exec, s[4:5]
	v_mul_f32_e32 v28, v71, v0
	v_mul_f32_e32 v28, 0x41800000, v28
	v_med3_f32 v28, v28, s65, v221
	s_waitcnt lgkmcnt(0)
	s_nop 1
	v_mov_b32_dpp v29, v28 quad_perm:[1,0,3,2] row_mask:0xf bank_mask:0xf
	v_mov_b32_e32 v32, v1
	s_waitcnt lgkmcnt(0)
	v_cvt_pk_fp8_f32 v32, v28, v29
	v_and_b32_e32 v28, 0xffff, v32
	s_nop 1
	v_mov_b32_dpp v29, v28 quad_perm:[2,3,0,1] row_mask:0xf bank_mask:0xf
	s_and_saveexec_b64 s[4:5], vcc
	s_cbranch_execz .LBB0_3547
	s_waitcnt lgkmcnt(0)
	v_lshl_or_b32 v28, v29, 16, v28
	global_store_dword v[26:27], v28, off offset:32
.LBB0_3547:
	s_or_b64 exec, exec, s[4:5]
	v_mul_f32_e32 v28, v55, v0
	v_mul_f32_e32 v28, 0x41800000, v28
	v_med3_f32 v28, v28, s65, v221
	s_waitcnt lgkmcnt(0)
	s_nop 1
	v_mov_b32_dpp v29, v28 quad_perm:[1,0,3,2] row_mask:0xf bank_mask:0xf
	v_mov_b32_e32 v32, v1
	s_waitcnt lgkmcnt(0)
	v_cvt_pk_fp8_f32 v32, v28, v29
	v_and_b32_e32 v28, 0xffff, v32
	s_nop 1
	v_mov_b32_dpp v29, v28 quad_perm:[2,3,0,1] row_mask:0xf bank_mask:0xf
	s_and_saveexec_b64 s[4:5], vcc
	s_cbranch_execz .LBB0_3549
	s_waitcnt lgkmcnt(0)
	v_lshl_or_b32 v28, v29, 16, v28
	global_store_dword v[26:27], v28, off offset:64
.LBB0_3549:
	s_or_b64 exec, exec, s[4:5]
	v_mul_f32_e32 v0, v39, v0
	v_mul_f32_e32 v0, 0x41800000, v0
	v_med3_f32 v0, v0, s65, v221
	s_nop 1
	v_mov_b32_dpp v28, v0 quad_perm:[1,0,3,2] row_mask:0xf bank_mask:0xf
	s_waitcnt lgkmcnt(1)
	v_mov_b32_e32 v29, v1
	s_waitcnt lgkmcnt(0)
	v_cvt_pk_fp8_f32 v29, v0, v28
	v_and_b32_e32 v0, 0xffff, v29
	s_nop 1
	v_mov_b32_dpp v28, v0 quad_perm:[2,3,0,1] row_mask:0xf bank_mask:0xf
	s_and_saveexec_b64 s[4:5], vcc
	s_cbranch_execz .LBB0_3551
	s_waitcnt lgkmcnt(0)
	v_lshl_or_b32 v0, v28, 16, v0
	global_store_dword v[26:27], v0, off offset:96
.LBB0_3551:
	s_or_b64 exec, exec, s[4:5]
	v_rcp_f32_e32 v0, v22
	v_mov_b32_e32 v27, v1
	v_mul_f32_e32 v22, v88, v0
	v_mul_f32_e32 v22, 0x41800000, v22
	v_med3_f32 v22, v22, s65, v221
	s_nop 1
	v_mov_b32_dpp v26, v22 quad_perm:[1,0,3,2] row_mask:0xf bank_mask:0xf
	s_waitcnt lgkmcnt(0)
	v_cvt_pk_fp8_f32 v27, v22, v26
	v_and_b32_e32 v22, 0xffff, v27
	s_nop 1
	v_mov_b32_dpp v28, v22 quad_perm:[2,3,0,1] row_mask:0xf bank_mask:0xf
	v_lshlrev_b64 v[26:27], 11, v[14:15]
	v_lshl_add_u64 v[26:27], v[30:31], 0, v[26:27]
	v_lshl_add_u64 v[26:27], v[26:27], 0, s[24:25]
	s_and_saveexec_b64 s[4:5], vcc
	s_cbranch_execz .LBB0_3553
	s_waitcnt lgkmcnt(0)
	v_lshl_or_b32 v22, v28, 16, v22
	global_store_dword v[26:27], v22, off
.LBB0_3553:
	s_or_b64 exec, exec, s[4:5]
	v_mul_f32_e32 v22, v72, v0
	v_mul_f32_e32 v22, 0x41800000, v22
	v_med3_f32 v22, v22, s65, v221
	s_waitcnt lgkmcnt(0)
	s_nop 1
	v_mov_b32_dpp v28, v22 quad_perm:[1,0,3,2] row_mask:0xf bank_mask:0xf
	v_mov_b32_e32 v29, v1
	s_waitcnt lgkmcnt(0)
	v_cvt_pk_fp8_f32 v29, v22, v28
	v_and_b32_e32 v22, 0xffff, v29
	s_nop 1
	v_mov_b32_dpp v28, v22 quad_perm:[2,3,0,1] row_mask:0xf bank_mask:0xf
	s_and_saveexec_b64 s[4:5], vcc
	s_cbranch_execz .LBB0_3555
	s_waitcnt lgkmcnt(0)
	v_lshl_or_b32 v22, v28, 16, v22
	global_store_dword v[26:27], v22, off offset:32
; __device__ __forceinline__ int crow(int r, int hi) { return (r & 3) + 8 * (r >> 2) + 4 * hi; }
; template <int MODE>
; __device__ __forceinline__ void attn_block(const AttnArgs& a, const BlockRef& cur, const BlockRef& nxt, char* lds, Seam<MODE>& S, const int tid) {
;     ...
;     for (int r = 0; r < 16; ++r) rli[r] = __builtin_amdgcn_rcpf(li_l[crow(r, hi)]) * (C::F8PV ? 0.125f : 1.0f);
;     int orow_ = cur.orow, hcol_ = cur.hcol; asm volatile("" : "+s"(orow_), "+s"(hcol_));
;     if (a.o8 != 0.f) {
;         unsigned char* Ob = (unsigned char*)a.O + (size_t)(orow_ + wid * QBLK) * ldo + hcol_; const float os = a.o8;
; #pragma unroll
;         for (int r = 0; r < 16; ++r) { const int orow = crow(r, hi);
; #pragma unroll
;             for (int d0 = 0; d0 < 4; ++d0) { const float v = __builtin_amdgcn_fmed3f(o[d0][r] * rli[r] * os, -448.f, 448.f);
;                 const float vn = __shfl_xor(v, 1);
;                 const int pk = __builtin_amdgcn_cvt_pk_fp8_f32(v, vn, 0, false) & 0xffff; const int pk2 = __shfl_xor(pk, 2);
;                 if ((r32 & 3) == 0) *(unsigned*)(Ob + (size_t)orow * ldo + d0 * 32 + r32) = (unsigned)pk | ((unsigned)pk2 << 16); } }
.LBB0_3555:
	s_or_b64 exec, exec, s[4:5]
	v_mul_f32_e32 v22, v56, v0
	v_mul_f32_e32 v22, 0x41800000, v22
	v_med3_f32 v22, v22, s65, v221
	s_waitcnt lgkmcnt(0)
	s_nop 1
	v_mov_b32_dpp v28, v22 quad_perm:[1,0,3,2] row_mask:0xf bank_mask:0xf
	v_mov_b32_e32 v29, v1
	s_waitcnt lgkmcnt(0)
	v_cvt_pk_fp8_f32 v29, v22, v28
	v_and_b32_e32 v22, 0xffff, v29
	s_nop 1
	v_mov_b32_dpp v28, v22 quad_perm:[2,3,0,1] row_mask:0xf bank_mask:0xf
	s_and_saveexec_b64 s[4:5], vcc
	s_cbranch_execz .LBB0_3557
	s_waitcnt lgkmcnt(0)
	v_lshl_or_b32 v22, v28, 16, v22
	global_store_dword v[26:27], v22, off offset:64
.LBB0_3557:
	s_or_b64 exec, exec, s[4:5]
	v_mul_f32_e32 v0, v40, v0
	v_mul_f32_e32 v0, 0x41800000, v0
	v_med3_f32 v0, v0, s65, v221
	s_nop 1
	v_mov_b32_dpp v22, v0 quad_perm:[1,0,3,2] row_mask:0xf bank_mask:0xf
	s_waitcnt lgkmcnt(1)
	v_mov_b32_e32 v28, v1
	s_waitcnt lgkmcnt(0)
	v_cvt_pk_fp8_f32 v28, v0, v22
	v_and_b32_e32 v0, 0xffff, v28
	s_nop 1
	v_mov_b32_dpp v22, v0 quad_perm:[2,3,0,1] row_mask:0xf bank_mask:0xf
	s_and_saveexec_b64 s[4:5], vcc
	s_cbranch_execz .LBB0_3559
	s_waitcnt lgkmcnt(0)
	v_lshl_or_b32 v0, v22, 16, v0
	global_store_dword v[26:27], v0, off offset:96
.LBB0_3559:
	s_or_b64 exec, exec, s[4:5]
	v_rcp_f32_e32 v0, v23
	v_mov_b32_e32 v26, v1
	s_waitcnt lgkmcnt(0)
	v_mul_f32_e32 v22, v89, v0
	v_mul_f32_e32 v22, 0x41800000, v22
	v_med3_f32 v22, v22, s65, v221
	s_nop 1
	v_mov_b32_dpp v23, v22 quad_perm:[1,0,3,2] row_mask:0xf bank_mask:0xf
	s_waitcnt lgkmcnt(0)
	v_cvt_pk_fp8_f32 v26, v22, v23
	v_lshlrev_b64 v[22:23], 11, v[14:15]
	v_lshl_add_u64 v[22:23], v[30:31], 0, v[22:23]
	v_lshl_add_u64 v[22:23], v[22:23], 0, s[26:27]
	v_and_b32_e32 v26, 0xffff, v26
	s_nop 1
	v_mov_b32_dpp v27, v26 quad_perm:[2,3,0,1] row_mask:0xf bank_mask:0xf
	s_and_saveexec_b64 s[4:5], vcc
	s_cbranch_execz .LBB0_3561
	s_waitcnt lgkmcnt(0)
	v_lshl_or_b32 v26, v27, 16, v26
	global_store_dword v[22:23], v26, off
.LBB0_3561:
	s_or_b64 exec, exec, s[4:5]
	v_mul_f32_e32 v26, v73, v0
	v_mul_f32_e32 v26, 0x41800000, v26
	v_med3_f32 v26, v26, s65, v221
	s_waitcnt lgkmcnt(0)
	s_nop 1
	v_mov_b32_dpp v27, v26 quad_perm:[1,0,3,2] row_mask:0xf bank_mask:0xf
	v_mov_b32_e32 v28, v1
	s_waitcnt lgkmcnt(0)
	v_cvt_pk_fp8_f32 v28, v26, v27
	v_and_b32_e32 v26, 0xffff, v28
	s_nop 1
	v_mov_b32_dpp v27, v26 quad_perm:[2,3,0,1] row_mask:0xf bank_mask:0xf
	s_and_saveexec_b64 s[4:5], vcc
	s_cbranch_execz .LBB0_3563
	s_waitcnt lgkmcnt(0)
	v_lshl_or_b32 v26, v27, 16, v26
	global_store_dword v[22:23], v26, off offset:32
.LBB0_3563:
	s_or_b64 exec, exec, s[4:5]
	v_mul_f32_e32 v26, v57, v0
	v_mul_f32_e32 v26, 0x41800000, v26
	v_med3_f32 v26, v26, s65, v221
	s_waitcnt lgkmcnt(0)
	s_nop 1
	v_mov_b32_dpp v27, v26 quad_perm:[1,0,3,2] row_mask:0xf bank_mask:0xf
	v_mov_b32_e32 v28, v1
	s_waitcnt lgkmcnt(0)
	v_cvt_pk_fp8_f32 v28, v26, v27
	v_and_b32_e32 v26, 0xffff, v28
	s_nop 1
	v_mov_b32_dpp v27, v26 quad_perm:[2,3,0,1] row_mask:0xf bank_mask:0xf
	s_and_saveexec_b64 s[4:5], vcc
	s_cbranch_execz .LBB0_3565
	s_waitcnt lgkmcnt(0)
	v_lshl_or_b32 v26, v27, 16, v26
	global_store_dword v[22:23], v26, off offset:64
.LBB0_3565:
	s_or_b64 exec, exec, s[4:5]
	v_mul_f32_e32 v0, v41, v0
	v_mul_f32_e32 v0, 0x41800000, v0
	v_med3_f32 v0, v0, s65, v221
	s_nop 1
	v_mov_b32_dpp v26, v0 quad_perm:[1,0,3,2] row_mask:0xf bank_mask:0xf
	s_waitcnt lgkmcnt(1)
	v_mov_b32_e32 v27, v1
	s_waitcnt lgkmcnt(0)
	v_cvt_pk_fp8_f32 v27, v0, v26
	v_and_b32_e32 v0, 0xffff, v27
	s_nop 1
	v_mov_b32_dpp v26, v0 quad_perm:[2,3,0,1] row_mask:0xf bank_mask:0xf
	s_and_saveexec_b64 s[4:5], vcc
	s_cbranch_execz .LBB0_3567
	s_waitcnt lgkmcnt(0)
	v_lshl_or_b32 v0, v26, 16, v0
	global_store_dword v[22:23], v0, off offset:96
.LBB0_3567:
	s_or_b64 exec, exec, s[4:5]
	v_rcp_f32_e32 v0, v24
	v_mov_b32_e32 v24, v1
	v_mul_f32_e32 v22, v90, v0
	v_mul_f32_e32 v22, 0x41800000, v22
	v_med3_f32 v22, v22, s65, v221
	s_nop 1
	v_mov_b32_dpp v23, v22 quad_perm:[1,0,3,2] row_mask:0xf bank_mask:0xf
	s_waitcnt lgkmcnt(0)
	v_cvt_pk_fp8_f32 v24, v22, v23
	v_lshlrev_b64 v[22:23], 11, v[14:15]
	v_lshl_add_u64 v[22:23], v[30:31], 0, v[22:23]
	v_lshl_add_u64 v[22:23], v[22:23], 0, s[28:29]
	v_and_b32_e32 v24, 0xffff, v24
	s_nop 1
	v_mov_b32_dpp v26, v24 quad_perm:[2,3,0,1] row_mask:0xf bank_mask:0xf
	s_and_saveexec_b64 s[4:5], vcc
	s_cbranch_execz .LBB0_3569
	s_waitcnt lgkmcnt(0)
	v_lshl_or_b32 v24, v26, 16, v24
	global_store_dword v[22:23], v24, off
.LBB0_3569:
	s_or_b64 exec, exec, s[4:5]
	v_mul_f32_e32 v24, v74, v0
	v_mul_f32_e32 v24, 0x41800000, v24
	v_med3_f32 v24, v24, s65, v221
	s_waitcnt lgkmcnt(0)
	s_nop 1
	v_mov_b32_dpp v26, v24 quad_perm:[1,0,3,2] row_mask:0xf bank_mask:0xf
	v_mov_b32_e32 v27, v1
	s_waitcnt lgkmcnt(0)
	v_cvt_pk_fp8_f32 v27, v24, v26
	v_and_b32_e32 v24, 0xffff, v27
	s_nop 1
	v_mov_b32_dpp v26, v24 quad_perm:[2,3,0,1] row_mask:0xf bank_mask:0xf
	s_and_saveexec_b64 s[4:5], vcc
	s_cbranch_execz .LBB0_3571
	s_waitcnt lgkmcnt(0)
	v_lshl_or_b32 v24, v26, 16, v24
	global_store_dword v[22:23], v24, off offset:32
.LBB0_3571:
	s_or_b64 exec, exec, s[4:5]
	v_mul_f32_e32 v24, v58, v0
	v_mul_f32_e32 v24, 0x41800000, v24
	v_med3_f32 v24, v24, s65, v221
	s_waitcnt lgkmcnt(0)
	s_nop 1
	v_mov_b32_dpp v26, v24 quad_perm:[1,0,3,2] row_mask:0xf bank_mask:0xf
	v_mov_b32_e32 v27, v1
	s_waitcnt lgkmcnt(0)
	v_cvt_pk_fp8_f32 v27, v24, v26
	v_and_b32_e32 v24, 0xffff, v27
	s_nop 1
	v_mov_b32_dpp v26, v24 quad_perm:[2,3,0,1] row_mask:0xf bank_mask:0xf
	s_and_saveexec_b64 s[4:5], vcc
	s_cbranch_execz .LBB0_3573
	s_waitcnt lgkmcnt(0)
	v_lshl_or_b32 v24, v26, 16, v24
	global_store_dword v[22:23], v24, off offset:64
; __device__ __forceinline__ int crow(int r, int hi) { return (r & 3) + 8 * (r >> 2) + 4 * hi; }
; template <int MODE>
; __device__ __forceinline__ void attn_block(const AttnArgs& a, const BlockRef& cur, const BlockRef& nxt, char* lds, Seam<MODE>& S, const int tid) {
;     ...
;     for (int r = 0; r < 16; ++r) rli[r] = __builtin_amdgcn_rcpf(li_l[crow(r, hi)]) * (C::F8PV ? 0.125f : 1.0f);
;     int orow_ = cur.orow, hcol_ = cur.hcol; asm volatile("" : "+s"(orow_), "+s"(hcol_));
;     if (a.o8 != 0.f) {
;         unsigned char* Ob = (unsigned char*)a.O + (size_t)(orow_ + wid * QBLK) * ldo + hcol_; const float os = a.o8;
; #pragma unroll
;         for (int r = 0; r < 16; ++r) { const int orow = crow(r, hi);
; #pragma unroll
;             for (int d0 = 0; d0 < 4; ++d0) { const float v = __builtin_amdgcn_fmed3f(o[d0][r] * rli[r] * os, -448.f, 448.f);
;                 const float vn = __shfl_xor(v, 1);
;                 const int pk = __builtin_amdgcn_cvt_pk_fp8_f32(v, vn, 0, false) & 0xffff; const int pk2 = __shfl_xor(pk, 2);
;                 if ((r32 & 3) == 0) *(unsigned*)(Ob + (size_t)orow * ldo + d0 * 32 + r32) = (unsigned)pk | ((unsigned)pk2 << 16); } }
.LBB0_3573:
	s_or_b64 exec, exec, s[4:5]
	v_mul_f32_e32 v0, v42, v0
	v_mul_f32_e32 v0, 0x41800000, v0
	v_med3_f32 v0, v0, s65, v221
	s_nop 1
	v_mov_b32_dpp v24, v0 quad_perm:[1,0,3,2] row_mask:0xf bank_mask:0xf
	s_waitcnt lgkmcnt(1)
	v_mov_b32_e32 v26, v1
	s_waitcnt lgkmcnt(0)
	v_cvt_pk_fp8_f32 v26, v0, v24
	v_and_b32_e32 v0, 0xffff, v26
	s_nop 1
	v_mov_b32_dpp v24, v0 quad_perm:[2,3,0,1] row_mask:0xf bank_mask:0xf
	s_and_saveexec_b64 s[4:5], vcc
	s_cbranch_execz .LBB0_3575
	s_waitcnt lgkmcnt(0)
	v_lshl_or_b32 v0, v24, 16, v0
	global_store_dword v[22:23], v0, off offset:96
.LBB0_3575:
	s_or_b64 exec, exec, s[4:5]
	v_rcp_f32_e32 v0, v25
	s_waitcnt lgkmcnt(0)
	v_mov_b32_e32 v24, v1
	v_mul_f32_e32 v22, v91, v0
	v_mul_f32_e32 v22, 0x41800000, v22
	v_med3_f32 v22, v22, s65, v221
	s_nop 1
	v_mov_b32_dpp v23, v22 quad_perm:[1,0,3,2] row_mask:0xf bank_mask:0xf
	s_waitcnt lgkmcnt(0)
	v_cvt_pk_fp8_f32 v24, v22, v23
	v_lshlrev_b64 v[22:23], 11, v[14:15]
	v_lshl_add_u64 v[22:23], v[30:31], 0, v[22:23]
	v_lshl_add_u64 v[22:23], v[22:23], 0, s[30:31]
	v_and_b32_e32 v24, 0xffff, v24
	s_nop 1
	v_mov_b32_dpp v25, v24 quad_perm:[2,3,0,1] row_mask:0xf bank_mask:0xf
	s_and_saveexec_b64 s[4:5], vcc
	s_cbranch_execz .LBB0_3577
	s_waitcnt lgkmcnt(0)
	v_lshl_or_b32 v24, v25, 16, v24
	global_store_dword v[22:23], v24, off
.LBB0_3577:
	s_or_b64 exec, exec, s[4:5]
	v_mul_f32_e32 v24, v75, v0
	v_mul_f32_e32 v24, 0x41800000, v24
	v_med3_f32 v24, v24, s65, v221
	s_waitcnt lgkmcnt(0)
	s_nop 1
	v_mov_b32_dpp v25, v24 quad_perm:[1,0,3,2] row_mask:0xf bank_mask:0xf
	v_mov_b32_e32 v26, v1
	s_waitcnt lgkmcnt(0)
	v_cvt_pk_fp8_f32 v26, v24, v25
	v_and_b32_e32 v24, 0xffff, v26
	s_nop 1
	v_mov_b32_dpp v25, v24 quad_perm:[2,3,0,1] row_mask:0xf bank_mask:0xf
	s_and_saveexec_b64 s[4:5], vcc
	s_cbranch_execz .LBB0_3579
	s_waitcnt lgkmcnt(0)
	v_lshl_or_b32 v24, v25, 16, v24
	global_store_dword v[22:23], v24, off offset:32
.LBB0_3579:
	s_or_b64 exec, exec, s[4:5]
	v_mul_f32_e32 v24, v59, v0
	v_mul_f32_e32 v24, 0x41800000, v24
	v_med3_f32 v24, v24, s65, v221
	s_waitcnt lgkmcnt(0)
	s_nop 1
	v_mov_b32_dpp v25, v24 quad_perm:[1,0,3,2] row_mask:0xf bank_mask:0xf
	v_mov_b32_e32 v26, v1
	s_waitcnt lgkmcnt(0)
	v_cvt_pk_fp8_f32 v26, v24, v25
	v_and_b32_e32 v24, 0xffff, v26
	s_nop 1
	v_mov_b32_dpp v25, v24 quad_perm:[2,3,0,1] row_mask:0xf bank_mask:0xf
	s_and_saveexec_b64 s[4:5], vcc
	s_cbranch_execz .LBB0_3581
	s_waitcnt lgkmcnt(0)
	v_lshl_or_b32 v24, v25, 16, v24
	global_store_dword v[22:23], v24, off offset:64
.LBB0_3581:
	s_or_b64 exec, exec, s[4:5]
	v_mul_f32_e32 v0, v43, v0
	v_mul_f32_e32 v0, 0x41800000, v0
	v_med3_f32 v0, v0, s65, v221
	s_nop 1
	v_mov_b32_dpp v24, v0 quad_perm:[1,0,3,2] row_mask:0xf bank_mask:0xf
	s_waitcnt lgkmcnt(1)
	v_mov_b32_e32 v25, v1
	s_waitcnt lgkmcnt(0)
	v_cvt_pk_fp8_f32 v25, v0, v24
	v_and_b32_e32 v0, 0xffff, v25
	s_nop 1
	v_mov_b32_dpp v24, v0 quad_perm:[2,3,0,1] row_mask:0xf bank_mask:0xf
	s_and_saveexec_b64 s[4:5], vcc
	s_cbranch_execz .LBB0_3583
	s_waitcnt lgkmcnt(0)
	v_lshl_or_b32 v0, v24, 16, v0
	global_store_dword v[22:23], v0, off offset:96
.LBB0_3583:
	s_or_b64 exec, exec, s[4:5]
	v_rcp_f32_e32 v0, v18
	v_mov_b32_e32 v23, v1
	v_mul_f32_e32 v18, v92, v0
	v_mul_f32_e32 v18, 0x41800000, v18
	v_med3_f32 v18, v18, s65, v221
	s_nop 1
	v_mov_b32_dpp v22, v18 quad_perm:[1,0,3,2] row_mask:0xf bank_mask:0xf
	s_waitcnt lgkmcnt(0)
	v_cvt_pk_fp8_f32 v23, v18, v22
	v_and_b32_e32 v18, 0xffff, v23
	s_nop 1
	v_mov_b32_dpp v24, v18 quad_perm:[2,3,0,1] row_mask:0xf bank_mask:0xf
	v_lshlrev_b64 v[22:23], 11, v[14:15]
	v_lshl_add_u64 v[22:23], v[30:31], 0, v[22:23]
	v_lshl_add_u64 v[22:23], v[22:23], 0, s[36:37]
	s_and_saveexec_b64 s[4:5], vcc
	s_cbranch_execz .LBB0_3585
	s_waitcnt lgkmcnt(0)
	v_lshl_or_b32 v18, v24, 16, v18
	global_store_dword v[22:23], v18, off
.LBB0_3585:
	s_or_b64 exec, exec, s[4:5]
	v_mul_f32_e32 v18, v76, v0
	v_mul_f32_e32 v18, 0x41800000, v18
	v_med3_f32 v18, v18, s65, v221
	s_waitcnt lgkmcnt(0)
	s_nop 1
	v_mov_b32_dpp v24, v18 quad_perm:[1,0,3,2] row_mask:0xf bank_mask:0xf
	v_mov_b32_e32 v25, v1
	s_waitcnt lgkmcnt(0)
	v_cvt_pk_fp8_f32 v25, v18, v24
	v_and_b32_e32 v18, 0xffff, v25
	s_nop 1
	v_mov_b32_dpp v24, v18 quad_perm:[2,3,0,1] row_mask:0xf bank_mask:0xf
	s_and_saveexec_b64 s[4:5], vcc
	s_cbranch_execz .LBB0_3587
	s_waitcnt lgkmcnt(0)
	v_lshl_or_b32 v18, v24, 16, v18
	global_store_dword v[22:23], v18, off offset:32
.LBB0_3587:
	s_or_b64 exec, exec, s[4:5]
	v_mul_f32_e32 v18, v60, v0
	v_mul_f32_e32 v18, 0x41800000, v18
	v_med3_f32 v18, v18, s65, v221
	s_waitcnt lgkmcnt(0)
	s_nop 1
	v_mov_b32_dpp v24, v18 quad_perm:[1,0,3,2] row_mask:0xf bank_mask:0xf
	v_mov_b32_e32 v25, v1
	s_waitcnt lgkmcnt(0)
	v_cvt_pk_fp8_f32 v25, v18, v24
	v_and_b32_e32 v18, 0xffff, v25
	s_nop 1
	v_mov_b32_dpp v24, v18 quad_perm:[2,3,0,1] row_mask:0xf bank_mask:0xf
	s_and_saveexec_b64 s[4:5], vcc
	s_cbranch_execz .LBB0_3589
	s_waitcnt lgkmcnt(0)
	v_lshl_or_b32 v18, v24, 16, v18
	global_store_dword v[22:23], v18, off offset:64
.LBB0_3589:
	s_or_b64 exec, exec, s[4:5]
	v_mul_f32_e32 v0, v44, v0
	v_mul_f32_e32 v0, 0x41800000, v0
	v_med3_f32 v0, v0, s65, v221
	s_nop 1
	v_mov_b32_dpp v18, v0 quad_perm:[1,0,3,2] row_mask:0xf bank_mask:0xf
	s_waitcnt lgkmcnt(1)
	v_mov_b32_e32 v24, v1
	s_waitcnt lgkmcnt(0)
	v_cvt_pk_fp8_f32 v24, v0, v18
	v_and_b32_e32 v0, 0xffff, v24
	s_nop 1
	v_mov_b32_dpp v18, v0 quad_perm:[2,3,0,1] row_mask:0xf bank_mask:0xf
	s_and_saveexec_b64 s[4:5], vcc
	s_cbranch_execz .LBB0_3591
	s_waitcnt lgkmcnt(0)
	v_lshl_or_b32 v0, v18, 16, v0
	global_store_dword v[22:23], v0, off offset:96
; __device__ __forceinline__ int crow(int r, int hi) { return (r & 3) + 8 * (r >> 2) + 4 * hi; }
; template <int MODE>
; __device__ __forceinline__ void attn_block(const AttnArgs& a, const BlockRef& cur, const BlockRef& nxt, char* lds, Seam<MODE>& S, const int tid) {
;     ...
;     for (int r = 0; r < 16; ++r) rli[r] = __builtin_amdgcn_rcpf(li_l[crow(r, hi)]) * (C::F8PV ? 0.125f : 1.0f);
;     int orow_ = cur.orow, hcol_ = cur.hcol; asm volatile("" : "+s"(orow_), "+s"(hcol_));
;     if (a.o8 != 0.f) {
;         unsigned char* Ob = (unsigned char*)a.O + (size_t)(orow_ + wid * QBLK) * ldo + hcol_; const float os = a.o8;
; #pragma unroll
;         for (int r = 0; r < 16; ++r) { const int orow = crow(r, hi);
; #pragma unroll
;             for (int d0 = 0; d0 < 4; ++d0) { const float v = __builtin_amdgcn_fmed3f(o[d0][r] * rli[r] * os, -448.f, 448.f);
;                 const float vn = __shfl_xor(v, 1);
;                 const int pk = __builtin_amdgcn_cvt_pk_fp8_f32(v, vn, 0, false) & 0xffff; const int pk2 = __shfl_xor(pk, 2);
;                 if ((r32 & 3) == 0) *(unsigned*)(Ob + (size_t)orow * ldo + d0 * 32 + r32) = (unsigned)pk | ((unsigned)pk2 << 16); } }
.LBB0_3591:
	s_or_b64 exec, exec, s[4:5]
	v_rcp_f32_e32 v0, v19
	v_mov_b32_e32 v22, v1
	s_waitcnt lgkmcnt(0)
	v_mul_f32_e32 v18, v93, v0
	v_mul_f32_e32 v18, 0x41800000, v18
	v_med3_f32 v18, v18, s65, v221
	s_nop 1
	v_mov_b32_dpp v19, v18 quad_perm:[1,0,3,2] row_mask:0xf bank_mask:0xf
	s_waitcnt lgkmcnt(0)
	v_cvt_pk_fp8_f32 v22, v18, v19
	v_lshlrev_b64 v[18:19], 11, v[14:15]
	v_lshl_add_u64 v[18:19], v[30:31], 0, v[18:19]
	v_lshl_add_u64 v[18:19], v[18:19], 0, s[38:39]
	v_and_b32_e32 v22, 0xffff, v22
	s_nop 1
	v_mov_b32_dpp v23, v22 quad_perm:[2,3,0,1] row_mask:0xf bank_mask:0xf
	s_and_saveexec_b64 s[4:5], vcc
	s_cbranch_execz .LBB0_3593
	s_waitcnt lgkmcnt(0)
	v_lshl_or_b32 v22, v23, 16, v22
	global_store_dword v[18:19], v22, off
.LBB0_3593:
	s_or_b64 exec, exec, s[4:5]
	v_mul_f32_e32 v22, v77, v0
	v_mul_f32_e32 v22, 0x41800000, v22
	v_med3_f32 v22, v22, s65, v221
	s_waitcnt lgkmcnt(0)
	s_nop 1
	v_mov_b32_dpp v23, v22 quad_perm:[1,0,3,2] row_mask:0xf bank_mask:0xf
	v_mov_b32_e32 v24, v1
	s_waitcnt lgkmcnt(0)
	v_cvt_pk_fp8_f32 v24, v22, v23
	v_and_b32_e32 v22, 0xffff, v24
	s_nop 1
	v_mov_b32_dpp v23, v22 quad_perm:[2,3,0,1] row_mask:0xf bank_mask:0xf
	s_and_saveexec_b64 s[4:5], vcc
	s_cbranch_execz .LBB0_3595
	s_waitcnt lgkmcnt(0)
	v_lshl_or_b32 v22, v23, 16, v22
	global_store_dword v[18:19], v22, off offset:32
.LBB0_3595:
	s_or_b64 exec, exec, s[4:5]
	v_mul_f32_e32 v22, v61, v0
	v_mul_f32_e32 v22, 0x41800000, v22
	v_med3_f32 v22, v22, s65, v221
	s_waitcnt lgkmcnt(0)
	s_nop 1
	v_mov_b32_dpp v23, v22 quad_perm:[1,0,3,2] row_mask:0xf bank_mask:0xf
	v_mov_b32_e32 v24, v1
	s_waitcnt lgkmcnt(0)
	v_cvt_pk_fp8_f32 v24, v22, v23
	v_and_b32_e32 v22, 0xffff, v24
	s_nop 1
	v_mov_b32_dpp v23, v22 quad_perm:[2,3,0,1] row_mask:0xf bank_mask:0xf
	s_and_saveexec_b64 s[4:5], vcc
	s_cbranch_execz .LBB0_3597
	s_waitcnt lgkmcnt(0)
	v_lshl_or_b32 v22, v23, 16, v22
	global_store_dword v[18:19], v22, off offset:64
.LBB0_3597:
	s_or_b64 exec, exec, s[4:5]
	v_mul_f32_e32 v0, v45, v0
	v_mul_f32_e32 v0, 0x41800000, v0
	v_med3_f32 v0, v0, s65, v221
	s_nop 1
	v_mov_b32_dpp v22, v0 quad_perm:[1,0,3,2] row_mask:0xf bank_mask:0xf
	s_waitcnt lgkmcnt(1)
	v_mov_b32_e32 v23, v1
	s_waitcnt lgkmcnt(0)
	v_cvt_pk_fp8_f32 v23, v0, v22
	v_and_b32_e32 v0, 0xffff, v23
	s_nop 1
	v_mov_b32_dpp v22, v0 quad_perm:[2,3,0,1] row_mask:0xf bank_mask:0xf
	s_and_saveexec_b64 s[4:5], vcc
	s_cbranch_execz .LBB0_3599
	s_waitcnt lgkmcnt(0)
	v_lshl_or_b32 v0, v22, 16, v0
	global_store_dword v[18:19], v0, off offset:96
.LBB0_3599:
	s_or_b64 exec, exec, s[4:5]
	v_rcp_f32_e32 v0, v20
	v_mov_b32_e32 v20, v1
	v_mul_f32_e32 v18, v94, v0
	v_mul_f32_e32 v18, 0x41800000, v18
	v_med3_f32 v18, v18, s65, v221
	s_nop 1
	v_mov_b32_dpp v19, v18 quad_perm:[1,0,3,2] row_mask:0xf bank_mask:0xf
	s_waitcnt lgkmcnt(0)
	v_cvt_pk_fp8_f32 v20, v18, v19
	v_lshlrev_b64 v[18:19], 11, v[14:15]
	v_lshl_add_u64 v[18:19], v[30:31], 0, v[18:19]
	v_lshl_add_u64 v[18:19], v[18:19], 0, s[40:41]
	v_and_b32_e32 v20, 0xffff, v20
	s_nop 1
	v_mov_b32_dpp v22, v20 quad_perm:[2,3,0,1] row_mask:0xf bank_mask:0xf
	s_and_saveexec_b64 s[4:5], vcc
	s_cbranch_execz .LBB0_3601
	s_waitcnt lgkmcnt(0)
	v_lshl_or_b32 v20, v22, 16, v20
	global_store_dword v[18:19], v20, off
.LBB0_3601:
	s_or_b64 exec, exec, s[4:5]
	v_mul_f32_e32 v20, v78, v0
	v_mul_f32_e32 v20, 0x41800000, v20
	v_med3_f32 v20, v20, s65, v221
	s_waitcnt lgkmcnt(0)
	s_nop 1
	v_mov_b32_dpp v22, v20 quad_perm:[1,0,3,2] row_mask:0xf bank_mask:0xf
	v_mov_b32_e32 v23, v1
	s_waitcnt lgkmcnt(0)
	v_cvt_pk_fp8_f32 v23, v20, v22
	v_and_b32_e32 v20, 0xffff, v23
	s_nop 1
	v_mov_b32_dpp v22, v20 quad_perm:[2,3,0,1] row_mask:0xf bank_mask:0xf
	s_and_saveexec_b64 s[4:5], vcc
	s_cbranch_execz .LBB0_3603
	s_waitcnt lgkmcnt(0)
	v_lshl_or_b32 v20, v22, 16, v20
	global_store_dword v[18:19], v20, off offset:32
; __device__ __forceinline__ int crow(int r, int hi) { return (r & 3) + 8 * (r >> 2) + 4 * hi; }
; template <int MODE>
; __device__ __forceinline__ void attn_block(const AttnArgs& a, const BlockRef& cur, const BlockRef& nxt, char* lds, Seam<MODE>& S, const int tid) {
;     ...
;     for (int r = 0; r < 16; ++r) rli[r] = __builtin_amdgcn_rcpf(li_l[crow(r, hi)]) * (C::F8PV ? 0.125f : 1.0f);
;     int orow_ = cur.orow, hcol_ = cur.hcol; asm volatile("" : "+s"(orow_), "+s"(hcol_));
;     if (a.o8 != 0.f) {
;         unsigned char* Ob = (unsigned char*)a.O + (size_t)(orow_ + wid * QBLK) * ldo + hcol_; const float os = a.o8;
; #pragma unroll
;         for (int r = 0; r < 16; ++r) { const int orow = crow(r, hi);
; #pragma unroll
;             for (int d0 = 0; d0 < 4; ++d0) { const float v = __builtin_amdgcn_fmed3f(o[d0][r] * rli[r] * os, -448.f, 448.f);
;                 const float vn = __shfl_xor(v, 1);
;                 const int pk = __builtin_amdgcn_cvt_pk_fp8_f32(v, vn, 0, false) & 0xffff; const int pk2 = __shfl_xor(pk, 2);
;                 if ((r32 & 3) == 0) *(unsigned*)(Ob + (size_t)orow * ldo + d0 * 32 + r32) = (unsigned)pk | ((unsigned)pk2 << 16); } }
.LBB0_3603:
	s_or_b64 exec, exec, s[4:5]
	v_mul_f32_e32 v20, v62, v0
	v_mul_f32_e32 v20, 0x41800000, v20
	v_med3_f32 v20, v20, s65, v221
	s_waitcnt lgkmcnt(0)
	s_nop 1
	v_mov_b32_dpp v22, v20 quad_perm:[1,0,3,2] row_mask:0xf bank_mask:0xf
	v_mov_b32_e32 v23, v1
	s_waitcnt lgkmcnt(0)
	v_cvt_pk_fp8_f32 v23, v20, v22
	v_and_b32_e32 v20, 0xffff, v23
	s_nop 1
	v_mov_b32_dpp v22, v20 quad_perm:[2,3,0,1] row_mask:0xf bank_mask:0xf
	s_and_saveexec_b64 s[4:5], vcc
	s_cbranch_execz .LBB0_3605
	s_waitcnt lgkmcnt(0)
	v_lshl_or_b32 v20, v22, 16, v20
	global_store_dword v[18:19], v20, off offset:64
.LBB0_3605:
	s_or_b64 exec, exec, s[4:5]
	v_mul_f32_e32 v0, v46, v0
	v_mul_f32_e32 v0, 0x41800000, v0
	v_med3_f32 v0, v0, s65, v221
	s_nop 1
	v_mov_b32_dpp v20, v0 quad_perm:[1,0,3,2] row_mask:0xf bank_mask:0xf
	s_waitcnt lgkmcnt(1)
	v_mov_b32_e32 v22, v1
	s_waitcnt lgkmcnt(0)
	v_cvt_pk_fp8_f32 v22, v0, v20
	v_and_b32_e32 v0, 0xffff, v22
	s_nop 1
	v_mov_b32_dpp v20, v0 quad_perm:[2,3,0,1] row_mask:0xf bank_mask:0xf
	s_and_saveexec_b64 s[4:5], vcc
	s_cbranch_execz .LBB0_3607
	s_waitcnt lgkmcnt(0)
	v_lshl_or_b32 v0, v20, 16, v0
	global_store_dword v[18:19], v0, off offset:96
.LBB0_3607:
	s_or_b64 exec, exec, s[4:5]
	v_rcp_f32_e32 v0, v21
	s_waitcnt lgkmcnt(0)
	v_mov_b32_e32 v20, v1
	v_lshlrev_b64 v[14:15], 11, v[14:15]
	v_lshl_add_u64 v[14:15], v[30:31], 0, v[14:15]
	v_mul_f32_e32 v18, v95, v0
	v_mul_f32_e32 v18, 0x41800000, v18
	v_med3_f32 v18, v18, s65, v221
	s_nop 1
	v_mov_b32_dpp v19, v18 quad_perm:[1,0,3,2] row_mask:0xf bank_mask:0xf
	v_lshl_add_u64 v[14:15], v[14:15], 0, s[42:43]
	s_waitcnt lgkmcnt(0)
	v_cvt_pk_fp8_f32 v20, v18, v19
	v_and_b32_e32 v18, 0xffff, v20
	s_nop 1
	v_mov_b32_dpp v19, v18 quad_perm:[2,3,0,1] row_mask:0xf bank_mask:0xf
	s_and_saveexec_b64 s[4:5], vcc
	s_cbranch_execz .LBB0_3609
	s_waitcnt lgkmcnt(0)
	v_lshl_or_b32 v18, v19, 16, v18
	global_store_dword v[14:15], v18, off
.LBB0_3609:
	s_or_b64 exec, exec, s[4:5]
	v_mul_f32_e32 v18, v79, v0
	v_mul_f32_e32 v18, 0x41800000, v18
	v_med3_f32 v18, v18, s65, v221
	s_waitcnt lgkmcnt(0)
	s_nop 1
	v_mov_b32_dpp v19, v18 quad_perm:[1,0,3,2] row_mask:0xf bank_mask:0xf
	v_mov_b32_e32 v20, v1
	s_waitcnt lgkmcnt(0)
	v_cvt_pk_fp8_f32 v20, v18, v19
	v_and_b32_e32 v18, 0xffff, v20
	s_nop 1
	v_mov_b32_dpp v19, v18 quad_perm:[2,3,0,1] row_mask:0xf bank_mask:0xf
	s_and_saveexec_b64 s[4:5], vcc
	s_cbranch_execz .LBB0_3611
	s_waitcnt lgkmcnt(0)
	v_lshl_or_b32 v18, v19, 16, v18
	global_store_dword v[14:15], v18, off offset:32
.LBB0_3611:
	s_or_b64 exec, exec, s[4:5]
	v_mul_f32_e32 v18, v63, v0
	v_mul_f32_e32 v18, 0x41800000, v18
	v_med3_f32 v18, v18, s65, v221
	s_waitcnt lgkmcnt(0)
	s_nop 1
	v_mov_b32_dpp v19, v18 quad_perm:[1,0,3,2] row_mask:0xf bank_mask:0xf
	v_mov_b32_e32 v20, v1
	s_waitcnt lgkmcnt(0)
	v_cvt_pk_fp8_f32 v20, v18, v19
	v_and_b32_e32 v18, 0xffff, v20
	s_nop 1
	v_mov_b32_dpp v19, v18 quad_perm:[2,3,0,1] row_mask:0xf bank_mask:0xf
	s_and_saveexec_b64 s[4:5], vcc
	s_cbranch_execz .LBB0_3613
	s_waitcnt lgkmcnt(0)
	v_lshl_or_b32 v18, v19, 16, v18
	global_store_dword v[14:15], v18, off offset:64
.LBB0_3613:
	s_or_b64 exec, exec, s[4:5]
	v_mul_f32_e32 v0, v47, v0
	v_mul_f32_e32 v0, 0x41800000, v0
	v_med3_f32 v0, v0, s65, v221
	s_nop 1
	v_mov_b32_dpp v17, v0 quad_perm:[1,0,3,2] row_mask:0xf bank_mask:0xf
	v_mov_b32_e32 v18, v1
	s_waitcnt lgkmcnt(0)
	v_cvt_pk_fp8_f32 v18, v0, v17
	v_and_b32_e32 v0, 0xffff, v18
	s_nop 1
	v_mov_b32_dpp v17, v0 quad_perm:[2,3,0,1] row_mask:0xf bank_mask:0xf
	s_and_saveexec_b64 s[4:5], vcc
	s_cbranch_execz .LBB0_3417
	s_waitcnt lgkmcnt(0)
	v_lshl_or_b32 v0, v17, 16, v0
	global_store_dword v[14:15], v0, off offset:96
	s_branch .LBB0_3417

; #define SBAR() __builtin_amdgcn_sched_barrier(0)
; __device__ __forceinline__ int crow(int r, int hi) { return (r & 3) + 8 * (r >> 2) + 4 * hi; }
; #define SEAM_K0() do { VMWN(NQR); if constexpr (C::F8QK) { const int nb_ = ((NT & 1) == 0) ? NX3(bq) : bq; char* kb_ = KB3(nb_);     \
;                            *(bf16x8*)(kb_ + kr * K8P + kc * 16) = S.st_k0; if (kr < 32) *(bf16x8*)(kb_ + (2 * kr + (kc >> 2)) * K8P + 128 + (kc & 3) * 16) = S.st_kp; S.b0 = nb_; }  \
;                        else SWRITE_HK(0); SBAR(); } while (0)
; template <int MODE>
; __device__ __forceinline__ void attn_block(const AttnArgs& a, const BlockRef& cur, const BlockRef& nxt, char* lds, Seam<MODE>& S, const int tid) {
;     ...
;     if constexpr (C::F8PV) asm volatile("s_nop 15\n\ts_nop 15" : "+v"(o[0]), "+v"(o[1]), "+v"(o[2]), "+v"(o[3]));
;     SBAR(); SEAM_K0();
;     if constexpr (NQR < NQ) {
; #pragma unroll
;         for (int d0 = NQR; d0 < NQ; ++d0) S.qr[d0] = load8(a.Q + (size_t)(nq_ + wid * QBLK + r32) * C::DK + d0 * 16 + hi * 8);
;         SBAR(); }
;     if (hi == 0) li_l[r32] = l_reg; asm volatile("s_waitcnt lgkmcnt(0)" ::: "memory");
;     float rli[16];
; #pragma unroll
;     for (int r = 0; r < 16; ++r) rli[r] = __builtin_amdgcn_rcpf(li_l[crow(r, hi)]) * (C::F8PV ? 0.125f : 1.0f);
;     int orow_ = cur.orow, hcol_ = cur.hcol; asm volatile("" : "+s"(orow_), "+s"(hcol_));
;     if (a.o8 != 0.f) {
;         unsigned char* Ob = (unsigned char*)a.O + (size_t)(orow_ + wid * QBLK) * ldo + hcol_; const float os = a.o8;
; #pragma unroll
;         for (int r = 0; r < 16; ++r) { const int orow = crow(r, hi);
; #pragma unroll
;             for (int d0 = 0; d0 < 4; ++d0) { const float v = __builtin_amdgcn_fmed3f(o[d0][r] * rli[r] * os, -448.f, 448.f);
;                 const float vn = __shfl_xor(v, 1);
;                 const int pk = __builtin_amdgcn_cvt_pk_fp8_f32(v, vn, 0, false) & 0xffff; const int pk2 = __shfl_xor(pk, 2);
;                 if ((r32 & 3) == 0) *(unsigned*)(Ob + (size_t)orow * ldo + d0 * 32 + r32) = (unsigned)pk | ((unsigned)pk2 << 16); } }
.LBB0_4297:
	s_nop 0
	s_nop 15
	s_nop 15
	s_add_i32 s30, s92, 1
	s_cmp_lg_u32 s92, 2
	s_cselect_b32 s30, s30, 0
	s_and_b64 s[28:29], s[28:29], exec
	s_cselect_b32 s92, s92, s30
	s_cmp_eq_u32 s92, 1
	s_cselect_b32 s28, s77, 0x15000
	s_cmp_lg_u32 s92, 0
	s_waitcnt vmcnt(6)
	s_cselect_b32 s28, s28, 0x8000
	s_add_i32 s30, s28, 0
	v_mul_lo_u32 v80, v154, s73
	v_add3_u32 v80, s30, v80, v150
	s_waitcnt vmcnt(6)
	ds_write_b128 v80, v[132:135]
	s_and_saveexec_b64 s[28:29], s[6:7]
	v_mul_lo_u32 v80, v148, s73
	v_add3_u32 v0, s30, v80, v0
	ds_write_b128 v0, v[168:171] offset:128
	s_or_b64 exec, exec, s[28:29]
	global_load_dwordx4 v[100:103], v[152:153], off offset:192
	global_load_dwordx4 v[96:99], v[152:153], off offset:224
	global_load_dwordx4 v[92:95], v[152:153], off offset:256
	global_load_dwordx4 v[88:91], v[152:153], off offset:288
	global_load_dwordx4 v[84:87], v[152:153], off offset:320
	global_load_dwordx4 v[80:83], v[152:153], off offset:352
	v_cmp_gt_u32_e32 vcc, 32, v15
	s_and_saveexec_b64 s[6:7], vcc
	v_lshl_add_u32 v0, v180, 2, s62
	ds_write_b32 v0, v112
	s_or_b64 exec, exec, s[6:7]
	s_waitcnt lgkmcnt(0)
	v_lshl_add_u32 v0, v14, 2, s62
	ds_read_b128 v[116:119], v0
	ds_read_b128 v[112:115], v0 offset:32
	ds_read_b128 v[108:111], v0 offset:64
	ds_read_b128 v[104:107], v0 offset:96
	v_xor_b32_e32 v120, 2, v197
	s_waitcnt lgkmcnt(3)
	v_rcp_f32_e32 v0, v116
	v_and_b32_e32 v116, 64, v197
	v_add_u32_e32 v116, 64, v116
	v_mul_f32_e32 v124, 0x3e000000, v0
	v_xor_b32_e32 v0, 1, v197
	v_cmp_lt_i32_e32 vcc, v0, v116
	v_mul_f32_e32 v64, v64, v124
	v_mul_f32_e32 v64, 0x41800000, v64
	v_cndmask_b32_e32 v0, v197, v0, vcc
	v_lshlrev_b32_e32 v0, 2, v0
	v_med3_f32 v64, v64, s79, v198
	s_nop 1
	v_mov_b32_dpp v121, v64 quad_perm:[1,0,3,2] row_mask:0xf bank_mask:0xf
	v_cmp_lt_i32_e32 vcc, v120, v116
	s_add_i32 s6, s88, s64
	s_ashr_i32 s7, s6, 31
	v_cndmask_b32_e32 v116, v197, v120, vcc
	v_mov_b32_e32 v120, v1
	s_waitcnt lgkmcnt(0)
	v_cvt_pk_fp8_f32 v120, v64, v121
	s_lshl_b64 s[6:7], s[6:7], 11
	s_ashr_i32 s28, s89, 31
	s_add_u32 s6, s74, s6
	v_lshlrev_b32_e32 v116, 2, v116
	v_and_b32_e32 v64, 0xffff, v120
	s_addc_u32 s7, s75, s7
	s_nop 1
	v_mov_b32_dpp v125, v64 quad_perm:[2,3,0,1] row_mask:0xf bank_mask:0xf
	s_add_u32 s6, s6, s89
	v_and_b32_e32 v15, 3, v15
	s_addc_u32 s7, s7, s28
	v_cmp_eq_u32_e32 vcc, 0, v15
	v_mov_b32_e32 v181, v1
	v_ashrrev_i32_e32 v15, 31, v14
	v_lshl_add_u64 v[120:121], s[6:7], 0, v[180:181]
	v_lshlrev_b64 v[122:123], 11, v[14:15]
	v_lshl_add_u64 v[122:123], v[120:121], 0, v[122:123]
	s_and_saveexec_b64 s[6:7], vcc
	s_cbranch_execz .LBB0_4303
	s_waitcnt lgkmcnt(0)
	v_lshl_or_b32 v64, v125, 16, v64
	global_store_dword v[122:123], v64, off
.LBB0_4303:
	s_or_b64 exec, exec, s[6:7]
	v_mul_f32_e32 v48, v48, v124
	v_mul_f32_e32 v48, 0x41800000, v48
	v_med3_f32 v48, v48, s79, v198
	s_nop 1
	v_mov_b32_dpp v64, v48 quad_perm:[1,0,3,2] row_mask:0xf bank_mask:0xf
	s_waitcnt lgkmcnt(1)
	v_mov_b32_e32 v125, v1
	s_waitcnt lgkmcnt(0)
	v_cvt_pk_fp8_f32 v125, v48, v64
	v_and_b32_e32 v48, 0xffff, v125
	s_nop 1
	v_mov_b32_dpp v64, v48 quad_perm:[2,3,0,1] row_mask:0xf bank_mask:0xf
	s_and_saveexec_b64 s[6:7], vcc
	s_cbranch_execz .LBB0_4305
	s_waitcnt lgkmcnt(0)
	v_lshl_or_b32 v48, v64, 16, v48
	global_store_dword v[122:123], v48, off offset:32
.LBB0_4305:
	s_or_b64 exec, exec, s[6:7]
	v_mul_f32_e32 v32, v32, v124
	v_mul_f32_e32 v32, 0x41800000, v32
	v_med3_f32 v32, v32, s79, v198
	s_nop 1
	v_mov_b32_dpp v48, v32 quad_perm:[1,0,3,2] row_mask:0xf bank_mask:0xf
	s_waitcnt lgkmcnt(1)
	v_mov_b32_e32 v64, v1
	s_waitcnt lgkmcnt(0)
	v_cvt_pk_fp8_f32 v64, v32, v48
	v_and_b32_e32 v32, 0xffff, v64
	s_nop 1
	v_mov_b32_dpp v48, v32 quad_perm:[2,3,0,1] row_mask:0xf bank_mask:0xf
	s_and_saveexec_b64 s[6:7], vcc
	s_cbranch_execz .LBB0_4307
	s_waitcnt lgkmcnt(0)
	v_lshl_or_b32 v32, v48, 16, v32
	global_store_dword v[122:123], v32, off offset:64
.LBB0_4307:
	s_or_b64 exec, exec, s[6:7]
	v_mul_f32_e32 v16, v16, v124
	v_mul_f32_e32 v16, 0x41800000, v16
	v_med3_f32 v16, v16, s79, v198
	s_nop 1
	v_mov_b32_dpp v32, v16 quad_perm:[1,0,3,2] row_mask:0xf bank_mask:0xf
	s_waitcnt lgkmcnt(1)
	v_mov_b32_e32 v48, v1
	s_waitcnt lgkmcnt(0)
	v_cvt_pk_fp8_f32 v48, v16, v32
	v_and_b32_e32 v16, 0xffff, v48
	s_nop 1
	v_mov_b32_dpp v32, v16 quad_perm:[2,3,0,1] row_mask:0xf bank_mask:0xf
	s_and_saveexec_b64 s[6:7], vcc
	s_cbranch_execz .LBB0_4309
	s_waitcnt lgkmcnt(0)
	v_lshl_or_b32 v16, v32, 16, v16
	global_store_dword v[122:123], v16, off offset:96
.LBB0_4309:
	s_or_b64 exec, exec, s[6:7]
	v_rcp_f32_e32 v16, v117
	v_mov_b32_e32 v64, v1
	v_mul_f32_e32 v16, 0x3e000000, v16
	s_waitcnt lgkmcnt(0)
	v_mul_f32_e32 v32, v65, v16
	v_mul_f32_e32 v32, 0x41800000, v32
	v_med3_f32 v32, v32, s79, v198
	s_nop 1
	v_mov_b32_dpp v48, v32 quad_perm:[1,0,3,2] row_mask:0xf bank_mask:0xf
	s_waitcnt lgkmcnt(0)
	v_cvt_pk_fp8_f32 v64, v32, v48
	v_and_b32_e32 v32, 0xffff, v64
	s_nop 1
	v_mov_b32_dpp v48, v32 quad_perm:[2,3,0,1] row_mask:0xf bank_mask:0xf
	v_or_b32_e32 v64, 1, v14
	v_ashrrev_i32_e32 v65, 31, v64
	v_lshlrev_b64 v[64:65], 11, v[64:65]
	v_lshl_add_u64 v[64:65], v[120:121], 0, v[64:65]
	s_and_saveexec_b64 s[6:7], vcc
	s_cbranch_execz .LBB0_4311
	s_waitcnt lgkmcnt(0)
	v_lshl_or_b32 v32, v48, 16, v32
	global_store_dword v[64:65], v32, off
.LBB0_4311:
	s_or_b64 exec, exec, s[6:7]
	v_mul_f32_e32 v32, v49, v16
	v_mul_f32_e32 v32, 0x41800000, v32
	v_med3_f32 v32, v32, s79, v198
	s_waitcnt lgkmcnt(0)
	s_nop 1
	v_mov_b32_dpp v48, v32 quad_perm:[1,0,3,2] row_mask:0xf bank_mask:0xf
	v_mov_b32_e32 v49, v1
	s_waitcnt lgkmcnt(0)
	v_cvt_pk_fp8_f32 v49, v32, v48
	v_and_b32_e32 v32, 0xffff, v49
	s_nop 1
	v_mov_b32_dpp v48, v32 quad_perm:[2,3,0,1] row_mask:0xf bank_mask:0xf
	s_and_saveexec_b64 s[6:7], vcc
	s_cbranch_execz .LBB0_4313
	s_waitcnt lgkmcnt(0)
	v_lshl_or_b32 v32, v48, 16, v32
	global_store_dword v[64:65], v32, off offset:32
; __device__ __forceinline__ int crow(int r, int hi) { return (r & 3) + 8 * (r >> 2) + 4 * hi; }
; template <int MODE>
; __device__ __forceinline__ void attn_block(const AttnArgs& a, const BlockRef& cur, const BlockRef& nxt, char* lds, Seam<MODE>& S, const int tid) {
;     ...
;     if (a.o8 != 0.f) {
;         unsigned char* Ob = (unsigned char*)a.O + (size_t)(orow_ + wid * QBLK) * ldo + hcol_; const float os = a.o8;
; #pragma unroll
;         for (int r = 0; r < 16; ++r) { const int orow = crow(r, hi);
; #pragma unroll
;             for (int d0 = 0; d0 < 4; ++d0) { const float v = __builtin_amdgcn_fmed3f(o[d0][r] * rli[r] * os, -448.f, 448.f);
;                 const float vn = __shfl_xor(v, 1);
;                 const int pk = __builtin_amdgcn_cvt_pk_fp8_f32(v, vn, 0, false) & 0xffff; const int pk2 = __shfl_xor(pk, 2);
;                 if ((r32 & 3) == 0) *(unsigned*)(Ob + (size_t)orow * ldo + d0 * 32 + r32) = (unsigned)pk | ((unsigned)pk2 << 16); } }
.LBB0_4313:
	s_or_b64 exec, exec, s[6:7]
	v_mul_f32_e32 v32, v33, v16
	v_mul_f32_e32 v32, 0x41800000, v32
	v_med3_f32 v32, v32, s79, v198
	s_nop 1
	v_mov_b32_dpp v33, v32 quad_perm:[1,0,3,2] row_mask:0xf bank_mask:0xf
	s_waitcnt lgkmcnt(1)
	v_mov_b32_e32 v48, v1
	s_waitcnt lgkmcnt(0)
	v_cvt_pk_fp8_f32 v48, v32, v33
	v_and_b32_e32 v32, 0xffff, v48
	s_nop 1
	v_mov_b32_dpp v33, v32 quad_perm:[2,3,0,1] row_mask:0xf bank_mask:0xf
	s_and_saveexec_b64 s[6:7], vcc
	s_cbranch_execz .LBB0_4315
	s_waitcnt lgkmcnt(0)
	v_lshl_or_b32 v32, v33, 16, v32
	global_store_dword v[64:65], v32, off offset:64
.LBB0_4315:
	s_or_b64 exec, exec, s[6:7]
	v_mul_f32_e32 v16, v17, v16
	v_mul_f32_e32 v16, 0x41800000, v16
	v_med3_f32 v16, v16, s79, v198
	s_nop 1
	v_mov_b32_dpp v17, v16 quad_perm:[1,0,3,2] row_mask:0xf bank_mask:0xf
	v_mov_b32_e32 v32, v1
	s_waitcnt lgkmcnt(0)
	v_cvt_pk_fp8_f32 v32, v16, v17
	v_and_b32_e32 v16, 0xffff, v32
	s_nop 1
	v_mov_b32_dpp v17, v16 quad_perm:[2,3,0,1] row_mask:0xf bank_mask:0xf
	s_and_saveexec_b64 s[6:7], vcc
	s_cbranch_execz .LBB0_4317
	s_waitcnt lgkmcnt(0)
	v_lshl_or_b32 v16, v17, 16, v16
	global_store_dword v[64:65], v16, off offset:96
.LBB0_4317:
	s_or_b64 exec, exec, s[6:7]
	v_rcp_f32_e32 v16, v118
	v_mov_b32_e32 v33, v1
	v_mul_f32_e32 v32, 0x3e000000, v16
	v_mul_f32_e32 v16, v66, v32
	v_mul_f32_e32 v16, 0x41800000, v16
	v_med3_f32 v16, v16, s79, v198
	s_waitcnt lgkmcnt(0)
	s_nop 1
	v_mov_b32_dpp v17, v16 quad_perm:[1,0,3,2] row_mask:0xf bank_mask:0xf
	s_waitcnt lgkmcnt(0)
	v_cvt_pk_fp8_f32 v33, v16, v17
	v_or_b32_e32 v16, 2, v14
	v_ashrrev_i32_e32 v17, 31, v16
	v_lshlrev_b64 v[16:17], 11, v[16:17]
	v_and_b32_e32 v33, 0xffff, v33
	s_nop 1
	v_mov_b32_dpp v48, v33 quad_perm:[2,3,0,1] row_mask:0xf bank_mask:0xf
	v_lshl_add_u64 v[16:17], v[120:121], 0, v[16:17]
	s_and_saveexec_b64 s[6:7], vcc
	s_cbranch_execz .LBB0_4319
	s_waitcnt lgkmcnt(0)
	v_lshl_or_b32 v33, v48, 16, v33
	global_store_dword v[16:17], v33, off
.LBB0_4319:
	s_or_b64 exec, exec, s[6:7]
	v_mul_f32_e32 v33, v50, v32
	v_mul_f32_e32 v33, 0x41800000, v33
	v_med3_f32 v33, v33, s79, v198
	s_waitcnt lgkmcnt(0)
	s_nop 1
	v_mov_b32_dpp v48, v33 quad_perm:[1,0,3,2] row_mask:0xf bank_mask:0xf
	v_mov_b32_e32 v49, v1
	s_waitcnt lgkmcnt(0)
	v_cvt_pk_fp8_f32 v49, v33, v48
	v_and_b32_e32 v33, 0xffff, v49
	s_nop 1
	v_mov_b32_dpp v48, v33 quad_perm:[2,3,0,1] row_mask:0xf bank_mask:0xf
	s_and_saveexec_b64 s[6:7], vcc
	s_cbranch_execz .LBB0_4321
	s_waitcnt lgkmcnt(0)
	v_lshl_or_b32 v33, v48, 16, v33
	global_store_dword v[16:17], v33, off offset:32
.LBB0_4321:
	s_or_b64 exec, exec, s[6:7]
	v_mul_f32_e32 v33, v34, v32
	v_mul_f32_e32 v33, 0x41800000, v33
	v_med3_f32 v33, v33, s79, v198
	s_nop 1
	v_mov_b32_dpp v34, v33 quad_perm:[1,0,3,2] row_mask:0xf bank_mask:0xf
	s_waitcnt lgkmcnt(1)
	v_mov_b32_e32 v48, v1
	s_waitcnt lgkmcnt(0)
	v_cvt_pk_fp8_f32 v48, v33, v34
	v_and_b32_e32 v33, 0xffff, v48
	s_nop 1
	v_mov_b32_dpp v34, v33 quad_perm:[2,3,0,1] row_mask:0xf bank_mask:0xf
	s_and_saveexec_b64 s[6:7], vcc
	s_cbranch_execz .LBB0_4323
	s_waitcnt lgkmcnt(0)
	v_lshl_or_b32 v33, v34, 16, v33
	global_store_dword v[16:17], v33, off offset:64
.LBB0_4323:
	s_or_b64 exec, exec, s[6:7]
	v_mul_f32_e32 v18, v18, v32
	v_mul_f32_e32 v18, 0x41800000, v18
	v_med3_f32 v18, v18, s79, v198
	s_nop 1
	v_mov_b32_dpp v32, v18 quad_perm:[1,0,3,2] row_mask:0xf bank_mask:0xf
	v_mov_b32_e32 v33, v1
	s_waitcnt lgkmcnt(0)
	v_cvt_pk_fp8_f32 v33, v18, v32
	v_and_b32_e32 v18, 0xffff, v33
	s_nop 1
	v_mov_b32_dpp v32, v18 quad_perm:[2,3,0,1] row_mask:0xf bank_mask:0xf
	s_and_saveexec_b64 s[6:7], vcc
	s_cbranch_execz .LBB0_4325
	s_waitcnt lgkmcnt(0)
	v_lshl_or_b32 v18, v32, 16, v18
	global_store_dword v[16:17], v18, off offset:96
.LBB0_4325:
	s_or_b64 exec, exec, s[6:7]
	v_rcp_f32_e32 v16, v119
	s_waitcnt lgkmcnt(0)
	v_mov_b32_e32 v32, v1
	v_mul_f32_e32 v18, 0x3e000000, v16
	v_mul_f32_e32 v16, v67, v18
	v_mul_f32_e32 v16, 0x41800000, v16
	v_med3_f32 v16, v16, s79, v198
	s_nop 1
	v_mov_b32_dpp v17, v16 quad_perm:[1,0,3,2] row_mask:0xf bank_mask:0xf
	s_waitcnt lgkmcnt(0)
	v_cvt_pk_fp8_f32 v32, v16, v17
	v_or_b32_e32 v16, 3, v14
	v_ashrrev_i32_e32 v17, 31, v16
	v_lshlrev_b64 v[16:17], 11, v[16:17]
	v_and_b32_e32 v32, 0xffff, v32
	s_nop 1
	v_mov_b32_dpp v33, v32 quad_perm:[2,3,0,1] row_mask:0xf bank_mask:0xf
	v_lshl_add_u64 v[16:17], v[120:121], 0, v[16:17]
	s_and_saveexec_b64 s[6:7], vcc
	s_cbranch_execz .LBB0_4327
	s_waitcnt lgkmcnt(0)
	v_lshl_or_b32 v32, v33, 16, v32
	global_store_dword v[16:17], v32, off
.LBB0_4327:
	s_or_b64 exec, exec, s[6:7]
	v_mul_f32_e32 v32, v51, v18
	v_mul_f32_e32 v32, 0x41800000, v32
	v_med3_f32 v32, v32, s79, v198
	s_waitcnt lgkmcnt(0)
	s_nop 1
	v_mov_b32_dpp v33, v32 quad_perm:[1,0,3,2] row_mask:0xf bank_mask:0xf
	v_mov_b32_e32 v34, v1
	s_waitcnt lgkmcnt(0)
	v_cvt_pk_fp8_f32 v34, v32, v33
	v_and_b32_e32 v32, 0xffff, v34
	s_nop 1
	v_mov_b32_dpp v33, v32 quad_perm:[2,3,0,1] row_mask:0xf bank_mask:0xf
	s_and_saveexec_b64 s[6:7], vcc
	s_cbranch_execz .LBB0_4329
	s_waitcnt lgkmcnt(0)
	v_lshl_or_b32 v32, v33, 16, v32
	global_store_dword v[16:17], v32, off offset:32
.LBB0_4329:
	s_or_b64 exec, exec, s[6:7]
	v_mul_f32_e32 v32, v35, v18
	v_mul_f32_e32 v32, 0x41800000, v32
	v_med3_f32 v32, v32, s79, v198
	s_waitcnt lgkmcnt(0)
	s_nop 1
	v_mov_b32_dpp v33, v32 quad_perm:[1,0,3,2] row_mask:0xf bank_mask:0xf
	v_mov_b32_e32 v34, v1
	s_waitcnt lgkmcnt(0)
	v_cvt_pk_fp8_f32 v34, v32, v33
	v_and_b32_e32 v32, 0xffff, v34
	s_nop 1
	v_mov_b32_dpp v33, v32 quad_perm:[2,3,0,1] row_mask:0xf bank_mask:0xf
	s_and_saveexec_b64 s[6:7], vcc
	s_cbranch_execz .LBB0_4331
	s_waitcnt lgkmcnt(0)
	v_lshl_or_b32 v32, v33, 16, v32
	global_store_dword v[16:17], v32, off offset:64
; __device__ __forceinline__ int crow(int r, int hi) { return (r & 3) + 8 * (r >> 2) + 4 * hi; }
; template <int MODE>
; __device__ __forceinline__ void attn_block(const AttnArgs& a, const BlockRef& cur, const BlockRef& nxt, char* lds, Seam<MODE>& S, const int tid) {
;     ...
;     if (a.o8 != 0.f) {
;         unsigned char* Ob = (unsigned char*)a.O + (size_t)(orow_ + wid * QBLK) * ldo + hcol_; const float os = a.o8;
; #pragma unroll
;         for (int r = 0; r < 16; ++r) { const int orow = crow(r, hi);
; #pragma unroll
;             for (int d0 = 0; d0 < 4; ++d0) { const float v = __builtin_amdgcn_fmed3f(o[d0][r] * rli[r] * os, -448.f, 448.f);
;                 const float vn = __shfl_xor(v, 1);
;                 const int pk = __builtin_amdgcn_cvt_pk_fp8_f32(v, vn, 0, false) & 0xffff; const int pk2 = __shfl_xor(pk, 2);
;                 if ((r32 & 3) == 0) *(unsigned*)(Ob + (size_t)orow * ldo + d0 * 32 + r32) = (unsigned)pk | ((unsigned)pk2 << 16); } }
.LBB0_4331:
	s_or_b64 exec, exec, s[6:7]
	v_mul_f32_e32 v18, v19, v18
	v_mul_f32_e32 v18, 0x41800000, v18
	v_med3_f32 v18, v18, s79, v198
	s_nop 1
	v_mov_b32_dpp v19, v18 quad_perm:[1,0,3,2] row_mask:0xf bank_mask:0xf
	v_mov_b32_e32 v32, v1
	s_waitcnt lgkmcnt(0)
	v_cvt_pk_fp8_f32 v32, v18, v19
	v_and_b32_e32 v18, 0xffff, v32
	s_nop 1
	v_mov_b32_dpp v19, v18 quad_perm:[2,3,0,1] row_mask:0xf bank_mask:0xf
	s_and_saveexec_b64 s[6:7], vcc
	s_cbranch_execz .LBB0_4333
	s_waitcnt lgkmcnt(0)
	v_lshl_or_b32 v18, v19, 16, v18
	global_store_dword v[16:17], v18, off offset:96
.LBB0_4333:
	s_or_b64 exec, exec, s[6:7]
	v_rcp_f32_e32 v16, v112
	s_waitcnt lgkmcnt(0)
	v_mov_b32_e32 v19, v1
	s_mov_b64 s[6:7], 0x4000
	v_mul_f32_e32 v18, 0x3e000000, v16
	v_mul_f32_e32 v16, v68, v18
	v_mul_f32_e32 v16, 0x41800000, v16
	v_med3_f32 v16, v16, s79, v198
	s_nop 1
	v_mov_b32_dpp v17, v16 quad_perm:[1,0,3,2] row_mask:0xf bank_mask:0xf
	s_waitcnt lgkmcnt(0)
	v_cvt_pk_fp8_f32 v19, v16, v17
	v_lshlrev_b64 v[16:17], 11, v[14:15]
	v_lshl_add_u64 v[16:17], v[120:121], 0, v[16:17]
	v_lshl_add_u64 v[16:17], v[16:17], 0, s[6:7]
	v_and_b32_e32 v19, 0xffff, v19
	s_nop 1
	v_mov_b32_dpp v32, v19 quad_perm:[2,3,0,1] row_mask:0xf bank_mask:0xf
	s_and_saveexec_b64 s[6:7], vcc
	s_cbranch_execz .LBB0_4335
	s_waitcnt lgkmcnt(0)
	v_lshl_or_b32 v19, v32, 16, v19
	global_store_dword v[16:17], v19, off
.LBB0_4335:
	s_or_b64 exec, exec, s[6:7]
	v_mul_f32_e32 v19, v52, v18
	v_mul_f32_e32 v19, 0x41800000, v19
	v_med3_f32 v19, v19, s79, v198
	s_waitcnt lgkmcnt(0)
	s_nop 1
	v_mov_b32_dpp v32, v19 quad_perm:[1,0,3,2] row_mask:0xf bank_mask:0xf
	v_mov_b32_e32 v33, v1
	s_waitcnt lgkmcnt(0)
	v_cvt_pk_fp8_f32 v33, v19, v32
	v_and_b32_e32 v19, 0xffff, v33
	s_nop 1
	v_mov_b32_dpp v32, v19 quad_perm:[2,3,0,1] row_mask:0xf bank_mask:0xf
	s_and_saveexec_b64 s[6:7], vcc
	s_cbranch_execz .LBB0_4337
	s_waitcnt lgkmcnt(0)
	v_lshl_or_b32 v19, v32, 16, v19
	global_store_dword v[16:17], v19, off offset:32
.LBB0_4337:
	s_or_b64 exec, exec, s[6:7]
	v_mul_f32_e32 v19, v36, v18
	v_mul_f32_e32 v19, 0x41800000, v19
	v_med3_f32 v19, v19, s79, v198
	s_waitcnt lgkmcnt(0)
	s_nop 1
	v_mov_b32_dpp v32, v19 quad_perm:[1,0,3,2] row_mask:0xf bank_mask:0xf
	v_mov_b32_e32 v33, v1
	s_waitcnt lgkmcnt(0)
	v_cvt_pk_fp8_f32 v33, v19, v32
	v_and_b32_e32 v19, 0xffff, v33
	s_nop 1
	v_mov_b32_dpp v32, v19 quad_perm:[2,3,0,1] row_mask:0xf bank_mask:0xf
	s_and_saveexec_b64 s[6:7], vcc
	s_cbranch_execz .LBB0_4339
	s_waitcnt lgkmcnt(0)
	v_lshl_or_b32 v19, v32, 16, v19
	global_store_dword v[16:17], v19, off offset:64
.LBB0_4339:
	s_or_b64 exec, exec, s[6:7]
	v_mul_f32_e32 v18, v20, v18
	v_mul_f32_e32 v18, 0x41800000, v18
	v_med3_f32 v18, v18, s79, v198
	s_nop 1
	v_mov_b32_dpp v19, v18 quad_perm:[1,0,3,2] row_mask:0xf bank_mask:0xf
	v_mov_b32_e32 v20, v1
	s_waitcnt lgkmcnt(0)
	v_cvt_pk_fp8_f32 v20, v18, v19
	v_and_b32_e32 v18, 0xffff, v20
	s_nop 1
	v_mov_b32_dpp v19, v18 quad_perm:[2,3,0,1] row_mask:0xf bank_mask:0xf
	s_and_saveexec_b64 s[6:7], vcc
	s_cbranch_execz .LBB0_4341
	s_waitcnt lgkmcnt(0)
	v_lshl_or_b32 v18, v19, 16, v18
	global_store_dword v[16:17], v18, off offset:96
.LBB0_4341:
	s_or_b64 exec, exec, s[6:7]
	v_rcp_f32_e32 v16, v113
	s_waitcnt lgkmcnt(0)
	v_mov_b32_e32 v19, v1
	s_mov_b64 s[6:7], 0x4800
	v_mul_f32_e32 v18, 0x3e000000, v16
	v_mul_f32_e32 v16, v69, v18
	v_mul_f32_e32 v16, 0x41800000, v16
	v_med3_f32 v16, v16, s79, v198
	s_nop 1
	v_mov_b32_dpp v17, v16 quad_perm:[1,0,3,2] row_mask:0xf bank_mask:0xf
	s_waitcnt lgkmcnt(0)
	v_cvt_pk_fp8_f32 v19, v16, v17
	v_lshlrev_b64 v[16:17], 11, v[14:15]
	v_lshl_add_u64 v[16:17], v[120:121], 0, v[16:17]
	v_lshl_add_u64 v[16:17], v[16:17], 0, s[6:7]
	v_and_b32_e32 v19, 0xffff, v19
	s_nop 1
	v_mov_b32_dpp v20, v19 quad_perm:[2,3,0,1] row_mask:0xf bank_mask:0xf
	s_and_saveexec_b64 s[6:7], vcc
	s_cbranch_execz .LBB0_4343
	s_waitcnt lgkmcnt(0)
	v_lshl_or_b32 v19, v20, 16, v19
	global_store_dword v[16:17], v19, off
.LBB0_4343:
	s_or_b64 exec, exec, s[6:7]
	v_mul_f32_e32 v19, v53, v18
	v_mul_f32_e32 v19, 0x41800000, v19
	v_med3_f32 v19, v19, s79, v198
	s_waitcnt lgkmcnt(0)
	s_nop 1
	v_mov_b32_dpp v20, v19 quad_perm:[1,0,3,2] row_mask:0xf bank_mask:0xf
	v_mov_b32_e32 v32, v1
	s_waitcnt lgkmcnt(0)
	v_cvt_pk_fp8_f32 v32, v19, v20
	v_and_b32_e32 v19, 0xffff, v32
	s_nop 1
	v_mov_b32_dpp v20, v19 quad_perm:[2,3,0,1] row_mask:0xf bank_mask:0xf
	s_and_saveexec_b64 s[6:7], vcc
	s_cbranch_execz .LBB0_4345
	s_waitcnt lgkmcnt(0)
	v_lshl_or_b32 v19, v20, 16, v19
	global_store_dword v[16:17], v19, off offset:32
.LBB0_4345:
	s_or_b64 exec, exec, s[6:7]
	v_mul_f32_e32 v19, v37, v18
	v_mul_f32_e32 v19, 0x41800000, v19
	v_med3_f32 v19, v19, s79, v198
	s_waitcnt lgkmcnt(0)
	s_nop 1
	v_mov_b32_dpp v20, v19 quad_perm:[1,0,3,2] row_mask:0xf bank_mask:0xf
	v_mov_b32_e32 v32, v1
	s_waitcnt lgkmcnt(0)
	v_cvt_pk_fp8_f32 v32, v19, v20
	v_and_b32_e32 v19, 0xffff, v32
	s_nop 1
	v_mov_b32_dpp v20, v19 quad_perm:[2,3,0,1] row_mask:0xf bank_mask:0xf
	s_and_saveexec_b64 s[6:7], vcc
	s_cbranch_execz .LBB0_4347
	s_waitcnt lgkmcnt(0)
	v_lshl_or_b32 v19, v20, 16, v19
	global_store_dword v[16:17], v19, off offset:64
.LBB0_4347:
	s_or_b64 exec, exec, s[6:7]
	v_mul_f32_e32 v18, v21, v18
	v_mul_f32_e32 v18, 0x41800000, v18
	v_med3_f32 v18, v18, s79, v198
	s_nop 1
	v_mov_b32_dpp v19, v18 quad_perm:[1,0,3,2] row_mask:0xf bank_mask:0xf
	s_waitcnt lgkmcnt(1)
	v_mov_b32_e32 v20, v1
	s_waitcnt lgkmcnt(0)
	v_cvt_pk_fp8_f32 v20, v18, v19
	v_and_b32_e32 v18, 0xffff, v20
	s_nop 1
	v_mov_b32_dpp v19, v18 quad_perm:[2,3,0,1] row_mask:0xf bank_mask:0xf
	s_and_saveexec_b64 s[6:7], vcc
	s_cbranch_execz .LBB0_4349
	s_waitcnt lgkmcnt(0)
	v_lshl_or_b32 v18, v19, 16, v18
	global_store_dword v[16:17], v18, off offset:96
; __device__ __forceinline__ int crow(int r, int hi) { return (r & 3) + 8 * (r >> 2) + 4 * hi; }
; template <int MODE>
; __device__ __forceinline__ void attn_block(const AttnArgs& a, const BlockRef& cur, const BlockRef& nxt, char* lds, Seam<MODE>& S, const int tid) {
;     ...
;     if (a.o8 != 0.f) {
;         unsigned char* Ob = (unsigned char*)a.O + (size_t)(orow_ + wid * QBLK) * ldo + hcol_; const float os = a.o8;
; #pragma unroll
;         for (int r = 0; r < 16; ++r) { const int orow = crow(r, hi);
; #pragma unroll
;             for (int d0 = 0; d0 < 4; ++d0) { const float v = __builtin_amdgcn_fmed3f(o[d0][r] * rli[r] * os, -448.f, 448.f);
;                 const float vn = __shfl_xor(v, 1);
;                 const int pk = __builtin_amdgcn_cvt_pk_fp8_f32(v, vn, 0, false) & 0xffff; const int pk2 = __shfl_xor(pk, 2);
;                 if ((r32 & 3) == 0) *(unsigned*)(Ob + (size_t)orow * ldo + d0 * 32 + r32) = (unsigned)pk | ((unsigned)pk2 << 16); } }
.LBB0_4349:
	s_or_b64 exec, exec, s[6:7]
	v_rcp_f32_e32 v16, v114
	s_waitcnt lgkmcnt(0)
	v_mov_b32_e32 v19, v1
	s_mov_b64 s[6:7], 0x5000
	v_mul_f32_e32 v18, 0x3e000000, v16
	v_mul_f32_e32 v16, v70, v18
	v_mul_f32_e32 v16, 0x41800000, v16
	v_med3_f32 v16, v16, s79, v198
	s_nop 1
	v_mov_b32_dpp v17, v16 quad_perm:[1,0,3,2] row_mask:0xf bank_mask:0xf
	s_waitcnt lgkmcnt(0)
	v_cvt_pk_fp8_f32 v19, v16, v17
	v_lshlrev_b64 v[16:17], 11, v[14:15]
	v_lshl_add_u64 v[16:17], v[120:121], 0, v[16:17]
	v_lshl_add_u64 v[16:17], v[16:17], 0, s[6:7]
	v_and_b32_e32 v19, 0xffff, v19
	s_nop 1
	v_mov_b32_dpp v20, v19 quad_perm:[2,3,0,1] row_mask:0xf bank_mask:0xf
	s_and_saveexec_b64 s[6:7], vcc
	s_cbranch_execz .LBB0_4351
	s_waitcnt lgkmcnt(0)
	v_lshl_or_b32 v19, v20, 16, v19
	global_store_dword v[16:17], v19, off
.LBB0_4351:
	s_or_b64 exec, exec, s[6:7]
	v_mul_f32_e32 v19, v54, v18
	v_mul_f32_e32 v19, 0x41800000, v19
	v_med3_f32 v19, v19, s79, v198
	s_waitcnt lgkmcnt(0)
	s_nop 1
	v_mov_b32_dpp v20, v19 quad_perm:[1,0,3,2] row_mask:0xf bank_mask:0xf
	v_mov_b32_e32 v21, v1
	s_waitcnt lgkmcnt(0)
	v_cvt_pk_fp8_f32 v21, v19, v20
	v_and_b32_e32 v19, 0xffff, v21
	s_nop 1
	v_mov_b32_dpp v20, v19 quad_perm:[2,3,0,1] row_mask:0xf bank_mask:0xf
	s_and_saveexec_b64 s[6:7], vcc
	s_cbranch_execz .LBB0_4353
	s_waitcnt lgkmcnt(0)
	v_lshl_or_b32 v19, v20, 16, v19
	global_store_dword v[16:17], v19, off offset:32
.LBB0_4353:
	s_or_b64 exec, exec, s[6:7]
	v_mul_f32_e32 v19, v38, v18
	v_mul_f32_e32 v19, 0x41800000, v19
	v_med3_f32 v19, v19, s79, v198
	s_waitcnt lgkmcnt(0)
	s_nop 1
	v_mov_b32_dpp v20, v19 quad_perm:[1,0,3,2] row_mask:0xf bank_mask:0xf
	v_mov_b32_e32 v21, v1
	s_waitcnt lgkmcnt(0)
	v_cvt_pk_fp8_f32 v21, v19, v20
	v_and_b32_e32 v19, 0xffff, v21
	s_nop 1
	v_mov_b32_dpp v20, v19 quad_perm:[2,3,0,1] row_mask:0xf bank_mask:0xf
	s_and_saveexec_b64 s[6:7], vcc
	s_cbranch_execz .LBB0_4355
	s_waitcnt lgkmcnt(0)
	v_lshl_or_b32 v19, v20, 16, v19
	global_store_dword v[16:17], v19, off offset:64
.LBB0_4355:
	s_or_b64 exec, exec, s[6:7]
	v_mul_f32_e32 v18, v22, v18
	v_mul_f32_e32 v18, 0x41800000, v18
	v_med3_f32 v18, v18, s79, v198
	s_nop 1
	v_mov_b32_dpp v19, v18 quad_perm:[1,0,3,2] row_mask:0xf bank_mask:0xf
	s_waitcnt lgkmcnt(1)
	v_mov_b32_e32 v20, v1
	s_waitcnt lgkmcnt(0)
	v_cvt_pk_fp8_f32 v20, v18, v19
	v_and_b32_e32 v18, 0xffff, v20
	s_nop 1
	v_mov_b32_dpp v19, v18 quad_perm:[2,3,0,1] row_mask:0xf bank_mask:0xf
	s_and_saveexec_b64 s[6:7], vcc
	s_cbranch_execz .LBB0_4357
	s_waitcnt lgkmcnt(0)
	v_lshl_or_b32 v18, v19, 16, v18
	global_store_dword v[16:17], v18, off offset:96
.LBB0_4357:
	s_or_b64 exec, exec, s[6:7]
	v_rcp_f32_e32 v16, v115
	s_waitcnt lgkmcnt(0)
	v_mov_b32_e32 v19, v1
	s_mov_b64 s[6:7], 0x5800
	v_mul_f32_e32 v18, 0x3e000000, v16
	v_mul_f32_e32 v16, v71, v18
	v_mul_f32_e32 v16, 0x41800000, v16
	v_med3_f32 v16, v16, s79, v198
	s_nop 1
	v_mov_b32_dpp v17, v16 quad_perm:[1,0,3,2] row_mask:0xf bank_mask:0xf
	s_waitcnt lgkmcnt(0)
	v_cvt_pk_fp8_f32 v19, v16, v17
	v_lshlrev_b64 v[16:17], 11, v[14:15]
	v_lshl_add_u64 v[16:17], v[120:121], 0, v[16:17]
	v_lshl_add_u64 v[16:17], v[16:17], 0, s[6:7]
	v_and_b32_e32 v19, 0xffff, v19
	s_nop 1
	v_mov_b32_dpp v20, v19 quad_perm:[2,3,0,1] row_mask:0xf bank_mask:0xf
	s_and_saveexec_b64 s[6:7], vcc
	s_cbranch_execz .LBB0_4359
	s_waitcnt lgkmcnt(0)
	v_lshl_or_b32 v19, v20, 16, v19
	global_store_dword v[16:17], v19, off
.LBB0_4359:
	s_or_b64 exec, exec, s[6:7]
	v_mul_f32_e32 v19, v55, v18
	v_mul_f32_e32 v19, 0x41800000, v19
	v_med3_f32 v19, v19, s79, v198
	s_waitcnt lgkmcnt(0)
	s_nop 1
	v_mov_b32_dpp v20, v19 quad_perm:[1,0,3,2] row_mask:0xf bank_mask:0xf
	v_mov_b32_e32 v21, v1
	s_waitcnt lgkmcnt(0)
	v_cvt_pk_fp8_f32 v21, v19, v20
	v_and_b32_e32 v19, 0xffff, v21
	s_nop 1
	v_mov_b32_dpp v20, v19 quad_perm:[2,3,0,1] row_mask:0xf bank_mask:0xf
	s_and_saveexec_b64 s[6:7], vcc
	s_cbranch_execz .LBB0_4361
	s_waitcnt lgkmcnt(0)
	v_lshl_or_b32 v19, v20, 16, v19
	global_store_dword v[16:17], v19, off offset:32
.LBB0_4361:
	s_or_b64 exec, exec, s[6:7]
	v_mul_f32_e32 v19, v39, v18
	v_mul_f32_e32 v19, 0x41800000, v19
	v_med3_f32 v19, v19, s79, v198
	s_waitcnt lgkmcnt(0)
	s_nop 1
	v_mov_b32_dpp v20, v19 quad_perm:[1,0,3,2] row_mask:0xf bank_mask:0xf
	v_mov_b32_e32 v21, v1
	s_waitcnt lgkmcnt(0)
	v_cvt_pk_fp8_f32 v21, v19, v20
	v_and_b32_e32 v19, 0xffff, v21
	s_nop 1
	v_mov_b32_dpp v20, v19 quad_perm:[2,3,0,1] row_mask:0xf bank_mask:0xf
	s_and_saveexec_b64 s[6:7], vcc
	s_cbranch_execz .LBB0_4363
	s_waitcnt lgkmcnt(0)
	v_lshl_or_b32 v19, v20, 16, v19
	global_store_dword v[16:17], v19, off offset:64
.LBB0_4363:
	s_or_b64 exec, exec, s[6:7]
	v_mul_f32_e32 v18, v23, v18
	v_mul_f32_e32 v18, 0x41800000, v18
	v_med3_f32 v18, v18, s79, v198
	s_nop 1
	v_mov_b32_dpp v19, v18 quad_perm:[1,0,3,2] row_mask:0xf bank_mask:0xf
	s_waitcnt lgkmcnt(1)
	v_mov_b32_e32 v20, v1
	s_waitcnt lgkmcnt(0)
	v_cvt_pk_fp8_f32 v20, v18, v19
	v_and_b32_e32 v18, 0xffff, v20
	s_nop 1
	v_mov_b32_dpp v19, v18 quad_perm:[2,3,0,1] row_mask:0xf bank_mask:0xf
	s_and_saveexec_b64 s[6:7], vcc
	s_cbranch_execz .LBB0_4365
	s_waitcnt lgkmcnt(0)
	v_lshl_or_b32 v18, v19, 16, v18
	global_store_dword v[16:17], v18, off offset:96
.LBB0_4365:
	s_or_b64 exec, exec, s[6:7]
	v_rcp_f32_e32 v16, v108
	s_waitcnt lgkmcnt(0)
	v_mov_b32_e32 v19, v1
	s_mov_b64 s[6:7], 0x8000
	v_mul_f32_e32 v18, 0x3e000000, v16
	v_mul_f32_e32 v16, v72, v18
	v_mul_f32_e32 v16, 0x41800000, v16
	v_med3_f32 v16, v16, s79, v198
	s_nop 1
	v_mov_b32_dpp v17, v16 quad_perm:[1,0,3,2] row_mask:0xf bank_mask:0xf
	s_waitcnt lgkmcnt(0)
	v_cvt_pk_fp8_f32 v19, v16, v17
	v_lshlrev_b64 v[16:17], 11, v[14:15]
	v_lshl_add_u64 v[16:17], v[120:121], 0, v[16:17]
	v_lshl_add_u64 v[16:17], v[16:17], 0, s[6:7]
	v_and_b32_e32 v19, 0xffff, v19
	s_nop 1
	v_mov_b32_dpp v20, v19 quad_perm:[2,3,0,1] row_mask:0xf bank_mask:0xf
	s_and_saveexec_b64 s[6:7], vcc
	s_cbranch_execz .LBB0_4367
	s_waitcnt lgkmcnt(0)
	v_lshl_or_b32 v19, v20, 16, v19
	global_store_dword v[16:17], v19, off
; __device__ __forceinline__ int crow(int r, int hi) { return (r & 3) + 8 * (r >> 2) + 4 * hi; }
; template <int MODE>
; __device__ __forceinline__ void attn_block(const AttnArgs& a, const BlockRef& cur, const BlockRef& nxt, char* lds, Seam<MODE>& S, const int tid) {
;     ...
;     if (a.o8 != 0.f) {
;         unsigned char* Ob = (unsigned char*)a.O + (size_t)(orow_ + wid * QBLK) * ldo + hcol_; const float os = a.o8;
; #pragma unroll
;         for (int r = 0; r < 16; ++r) { const int orow = crow(r, hi);
; #pragma unroll
;             for (int d0 = 0; d0 < 4; ++d0) { const float v = __builtin_amdgcn_fmed3f(o[d0][r] * rli[r] * os, -448.f, 448.f);
;                 const float vn = __shfl_xor(v, 1);
;                 const int pk = __builtin_amdgcn_cvt_pk_fp8_f32(v, vn, 0, false) & 0xffff; const int pk2 = __shfl_xor(pk, 2);
;                 if ((r32 & 3) == 0) *(unsigned*)(Ob + (size_t)orow * ldo + d0 * 32 + r32) = (unsigned)pk | ((unsigned)pk2 << 16); } }
.LBB0_4367:
	s_or_b64 exec, exec, s[6:7]
	v_mul_f32_e32 v19, v56, v18
	v_mul_f32_e32 v19, 0x41800000, v19
	v_med3_f32 v19, v19, s79, v198
	s_waitcnt lgkmcnt(0)
	s_nop 1
	v_mov_b32_dpp v20, v19 quad_perm:[1,0,3,2] row_mask:0xf bank_mask:0xf
	v_mov_b32_e32 v21, v1
	s_waitcnt lgkmcnt(0)
	v_cvt_pk_fp8_f32 v21, v19, v20
	v_and_b32_e32 v19, 0xffff, v21
	s_nop 1
	v_mov_b32_dpp v20, v19 quad_perm:[2,3,0,1] row_mask:0xf bank_mask:0xf
	s_and_saveexec_b64 s[6:7], vcc
	s_cbranch_execz .LBB0_4369
	s_waitcnt lgkmcnt(0)
	v_lshl_or_b32 v19, v20, 16, v19
	global_store_dword v[16:17], v19, off offset:32
.LBB0_4369:
	s_or_b64 exec, exec, s[6:7]
	v_mul_f32_e32 v19, v40, v18
	v_mul_f32_e32 v19, 0x41800000, v19
	v_med3_f32 v19, v19, s79, v198
	s_waitcnt lgkmcnt(0)
	s_nop 1
	v_mov_b32_dpp v20, v19 quad_perm:[1,0,3,2] row_mask:0xf bank_mask:0xf
	v_mov_b32_e32 v21, v1
	s_waitcnt lgkmcnt(0)
	v_cvt_pk_fp8_f32 v21, v19, v20
	v_and_b32_e32 v19, 0xffff, v21
	s_nop 1
	v_mov_b32_dpp v20, v19 quad_perm:[2,3,0,1] row_mask:0xf bank_mask:0xf
	s_and_saveexec_b64 s[6:7], vcc
	s_cbranch_execz .LBB0_4371
	s_waitcnt lgkmcnt(0)
	v_lshl_or_b32 v19, v20, 16, v19
	global_store_dword v[16:17], v19, off offset:64
.LBB0_4371:
	s_or_b64 exec, exec, s[6:7]
	v_mul_f32_e32 v18, v24, v18
	v_mul_f32_e32 v18, 0x41800000, v18
	v_med3_f32 v18, v18, s79, v198
	s_nop 1
	v_mov_b32_dpp v19, v18 quad_perm:[1,0,3,2] row_mask:0xf bank_mask:0xf
	s_waitcnt lgkmcnt(1)
	v_mov_b32_e32 v20, v1
	s_waitcnt lgkmcnt(0)
	v_cvt_pk_fp8_f32 v20, v18, v19
	v_and_b32_e32 v18, 0xffff, v20
	s_nop 1
	v_mov_b32_dpp v19, v18 quad_perm:[2,3,0,1] row_mask:0xf bank_mask:0xf
	s_and_saveexec_b64 s[6:7], vcc
	s_cbranch_execz .LBB0_4373
	s_waitcnt lgkmcnt(0)
	v_lshl_or_b32 v18, v19, 16, v18
	global_store_dword v[16:17], v18, off offset:96
.LBB0_4373:
	s_or_b64 exec, exec, s[6:7]
	v_rcp_f32_e32 v16, v109
	s_waitcnt lgkmcnt(0)
	v_mov_b32_e32 v19, v1
	s_mov_b64 s[6:7], 0x8800
	v_mul_f32_e32 v18, 0x3e000000, v16
	v_mul_f32_e32 v16, v73, v18
	v_mul_f32_e32 v16, 0x41800000, v16
	v_med3_f32 v16, v16, s79, v198
	s_nop 1
	v_mov_b32_dpp v17, v16 quad_perm:[1,0,3,2] row_mask:0xf bank_mask:0xf
	s_waitcnt lgkmcnt(0)
	v_cvt_pk_fp8_f32 v19, v16, v17
	v_lshlrev_b64 v[16:17], 11, v[14:15]
	v_lshl_add_u64 v[16:17], v[120:121], 0, v[16:17]
	v_lshl_add_u64 v[16:17], v[16:17], 0, s[6:7]
	v_and_b32_e32 v19, 0xffff, v19
	s_nop 1
	v_mov_b32_dpp v20, v19 quad_perm:[2,3,0,1] row_mask:0xf bank_mask:0xf
	s_and_saveexec_b64 s[6:7], vcc
	s_cbranch_execz .LBB0_4375
	s_waitcnt lgkmcnt(0)
	v_lshl_or_b32 v19, v20, 16, v19
	global_store_dword v[16:17], v19, off
.LBB0_4375:
	s_or_b64 exec, exec, s[6:7]
	v_mul_f32_e32 v19, v57, v18
	v_mul_f32_e32 v19, 0x41800000, v19
	v_med3_f32 v19, v19, s79, v198
	s_waitcnt lgkmcnt(0)
	s_nop 1
	v_mov_b32_dpp v20, v19 quad_perm:[1,0,3,2] row_mask:0xf bank_mask:0xf
	v_mov_b32_e32 v21, v1
	s_waitcnt lgkmcnt(0)
	v_cvt_pk_fp8_f32 v21, v19, v20
	v_and_b32_e32 v19, 0xffff, v21
	s_nop 1
	v_mov_b32_dpp v20, v19 quad_perm:[2,3,0,1] row_mask:0xf bank_mask:0xf
	s_and_saveexec_b64 s[6:7], vcc
	s_cbranch_execz .LBB0_4377
	s_waitcnt lgkmcnt(0)
	v_lshl_or_b32 v19, v20, 16, v19
	global_store_dword v[16:17], v19, off offset:32
.LBB0_4377:
	s_or_b64 exec, exec, s[6:7]
	v_mul_f32_e32 v19, v41, v18
	v_mul_f32_e32 v19, 0x41800000, v19
	v_med3_f32 v19, v19, s79, v198
	s_waitcnt lgkmcnt(0)
	s_nop 1
	v_mov_b32_dpp v20, v19 quad_perm:[1,0,3,2] row_mask:0xf bank_mask:0xf
	v_mov_b32_e32 v21, v1
	s_waitcnt lgkmcnt(0)
	v_cvt_pk_fp8_f32 v21, v19, v20
	v_and_b32_e32 v19, 0xffff, v21
	s_nop 1
	v_mov_b32_dpp v20, v19 quad_perm:[2,3,0,1] row_mask:0xf bank_mask:0xf
	s_and_saveexec_b64 s[6:7], vcc
	s_cbranch_execz .LBB0_4379
	s_waitcnt lgkmcnt(0)
	v_lshl_or_b32 v19, v20, 16, v19
	global_store_dword v[16:17], v19, off offset:64
.LBB0_4379:
	s_or_b64 exec, exec, s[6:7]
	v_mul_f32_e32 v18, v25, v18
	v_mul_f32_e32 v18, 0x41800000, v18
	v_med3_f32 v18, v18, s79, v198
	s_nop 1
	v_mov_b32_dpp v19, v18 quad_perm:[1,0,3,2] row_mask:0xf bank_mask:0xf
	s_waitcnt lgkmcnt(1)
	v_mov_b32_e32 v20, v1
	s_waitcnt lgkmcnt(0)
	v_cvt_pk_fp8_f32 v20, v18, v19
	v_and_b32_e32 v18, 0xffff, v20
	s_nop 1
	v_mov_b32_dpp v19, v18 quad_perm:[2,3,0,1] row_mask:0xf bank_mask:0xf
	s_and_saveexec_b64 s[6:7], vcc
	s_cbranch_execz .LBB0_4381
	s_waitcnt lgkmcnt(0)
	v_lshl_or_b32 v18, v19, 16, v18
	global_store_dword v[16:17], v18, off offset:96
.LBB0_4381:
	s_or_b64 exec, exec, s[6:7]
	v_rcp_f32_e32 v16, v110
	s_waitcnt lgkmcnt(0)
	v_mov_b32_e32 v19, v1
	v_mul_f32_e32 v18, 0x3e000000, v16
	v_mul_f32_e32 v16, v74, v18
	v_mul_f32_e32 v16, 0x41800000, v16
	v_med3_f32 v16, v16, s79, v198
	s_nop 1
	v_mov_b32_dpp v17, v16 quad_perm:[1,0,3,2] row_mask:0xf bank_mask:0xf
	s_waitcnt lgkmcnt(0)
	v_cvt_pk_fp8_f32 v19, v16, v17
	v_lshlrev_b64 v[16:17], 11, v[14:15]
	v_lshl_add_u64 v[16:17], v[120:121], 0, v[16:17]
	v_lshl_add_u64 v[16:17], v[16:17], 0, s[10:11]
	v_and_b32_e32 v19, 0xffff, v19
	s_nop 1
	v_mov_b32_dpp v20, v19 quad_perm:[2,3,0,1] row_mask:0xf bank_mask:0xf
	s_and_saveexec_b64 s[6:7], vcc
	s_cbranch_execz .LBB0_4383
	s_waitcnt lgkmcnt(0)
	v_lshl_or_b32 v19, v20, 16, v19
	global_store_dword v[16:17], v19, off
.LBB0_4383:
	s_or_b64 exec, exec, s[6:7]
	v_mul_f32_e32 v19, v58, v18
	v_mul_f32_e32 v19, 0x41800000, v19
	v_med3_f32 v19, v19, s79, v198
	s_waitcnt lgkmcnt(0)
	s_nop 1
	v_mov_b32_dpp v20, v19 quad_perm:[1,0,3,2] row_mask:0xf bank_mask:0xf
	v_mov_b32_e32 v21, v1
	s_waitcnt lgkmcnt(0)
	v_cvt_pk_fp8_f32 v21, v19, v20
	v_and_b32_e32 v19, 0xffff, v21
	s_nop 1
	v_mov_b32_dpp v20, v19 quad_perm:[2,3,0,1] row_mask:0xf bank_mask:0xf
	s_and_saveexec_b64 s[6:7], vcc
	s_cbranch_execz .LBB0_4385
	s_waitcnt lgkmcnt(0)
	v_lshl_or_b32 v19, v20, 16, v19
	global_store_dword v[16:17], v19, off offset:32
; __device__ __forceinline__ int crow(int r, int hi) { return (r & 3) + 8 * (r >> 2) + 4 * hi; }
; template <int MODE>
; __device__ __forceinline__ void attn_block(const AttnArgs& a, const BlockRef& cur, const BlockRef& nxt, char* lds, Seam<MODE>& S, const int tid) {
;     ...
;     if (a.o8 != 0.f) {
;         unsigned char* Ob = (unsigned char*)a.O + (size_t)(orow_ + wid * QBLK) * ldo + hcol_; const float os = a.o8;
; #pragma unroll
;         for (int r = 0; r < 16; ++r) { const int orow = crow(r, hi);
; #pragma unroll
;             for (int d0 = 0; d0 < 4; ++d0) { const float v = __builtin_amdgcn_fmed3f(o[d0][r] * rli[r] * os, -448.f, 448.f);
;                 const float vn = __shfl_xor(v, 1);
;                 const int pk = __builtin_amdgcn_cvt_pk_fp8_f32(v, vn, 0, false) & 0xffff; const int pk2 = __shfl_xor(pk, 2);
;                 if ((r32 & 3) == 0) *(unsigned*)(Ob + (size_t)orow * ldo + d0 * 32 + r32) = (unsigned)pk | ((unsigned)pk2 << 16); } }
.LBB0_4385:
	s_or_b64 exec, exec, s[6:7]
	v_mul_f32_e32 v19, v42, v18
	v_mul_f32_e32 v19, 0x41800000, v19
	v_med3_f32 v19, v19, s79, v198
	s_waitcnt lgkmcnt(0)
	s_nop 1
	v_mov_b32_dpp v20, v19 quad_perm:[1,0,3,2] row_mask:0xf bank_mask:0xf
	v_mov_b32_e32 v21, v1
	s_waitcnt lgkmcnt(0)
	v_cvt_pk_fp8_f32 v21, v19, v20
	v_and_b32_e32 v19, 0xffff, v21
	s_nop 1
	v_mov_b32_dpp v20, v19 quad_perm:[2,3,0,1] row_mask:0xf bank_mask:0xf
	s_and_saveexec_b64 s[6:7], vcc
	s_cbranch_execz .LBB0_4387
	s_waitcnt lgkmcnt(0)
	v_lshl_or_b32 v19, v20, 16, v19
	global_store_dword v[16:17], v19, off offset:64
.LBB0_4387:
	s_or_b64 exec, exec, s[6:7]
	v_mul_f32_e32 v18, v26, v18
	v_mul_f32_e32 v18, 0x41800000, v18
	v_med3_f32 v18, v18, s79, v198
	s_nop 1
	v_mov_b32_dpp v19, v18 quad_perm:[1,0,3,2] row_mask:0xf bank_mask:0xf
	s_waitcnt lgkmcnt(1)
	v_mov_b32_e32 v20, v1
	s_waitcnt lgkmcnt(0)
	v_cvt_pk_fp8_f32 v20, v18, v19
	v_and_b32_e32 v18, 0xffff, v20
	s_nop 1
	v_mov_b32_dpp v19, v18 quad_perm:[2,3,0,1] row_mask:0xf bank_mask:0xf
	s_and_saveexec_b64 s[6:7], vcc
	s_cbranch_execz .LBB0_4389
	s_waitcnt lgkmcnt(0)
	v_lshl_or_b32 v18, v19, 16, v18
	global_store_dword v[16:17], v18, off offset:96
.LBB0_4389:
	s_or_b64 exec, exec, s[6:7]
	v_rcp_f32_e32 v16, v111
	s_waitcnt lgkmcnt(0)
	v_mov_b32_e32 v19, v1
	v_mul_f32_e32 v18, 0x3e000000, v16
	v_mul_f32_e32 v16, v75, v18
	v_mul_f32_e32 v16, 0x41800000, v16
	v_med3_f32 v16, v16, s79, v198
	s_nop 1
	v_mov_b32_dpp v17, v16 quad_perm:[1,0,3,2] row_mask:0xf bank_mask:0xf
	s_waitcnt lgkmcnt(0)
	v_cvt_pk_fp8_f32 v19, v16, v17
	v_lshlrev_b64 v[16:17], 11, v[14:15]
	v_lshl_add_u64 v[16:17], v[120:121], 0, v[16:17]
	v_lshl_add_u64 v[16:17], v[16:17], 0, s[14:15]
	v_and_b32_e32 v19, 0xffff, v19
	s_nop 1
	v_mov_b32_dpp v20, v19 quad_perm:[2,3,0,1] row_mask:0xf bank_mask:0xf
	s_and_saveexec_b64 s[6:7], vcc
	s_cbranch_execz .LBB0_4391
	s_waitcnt lgkmcnt(0)
	v_lshl_or_b32 v19, v20, 16, v19
	global_store_dword v[16:17], v19, off
.LBB0_4391:
	s_or_b64 exec, exec, s[6:7]
	v_mul_f32_e32 v19, v59, v18
	v_mul_f32_e32 v19, 0x41800000, v19
	v_med3_f32 v19, v19, s79, v198
	s_waitcnt lgkmcnt(0)
	s_nop 1
	v_mov_b32_dpp v20, v19 quad_perm:[1,0,3,2] row_mask:0xf bank_mask:0xf
	v_mov_b32_e32 v21, v1
	s_waitcnt lgkmcnt(0)
	v_cvt_pk_fp8_f32 v21, v19, v20
	v_and_b32_e32 v19, 0xffff, v21
	s_nop 1
	v_mov_b32_dpp v20, v19 quad_perm:[2,3,0,1] row_mask:0xf bank_mask:0xf
	s_and_saveexec_b64 s[6:7], vcc
	s_cbranch_execz .LBB0_4393
	s_waitcnt lgkmcnt(0)
	v_lshl_or_b32 v19, v20, 16, v19
	global_store_dword v[16:17], v19, off offset:32
.LBB0_4393:
	s_or_b64 exec, exec, s[6:7]
	v_mul_f32_e32 v19, v43, v18
	v_mul_f32_e32 v19, 0x41800000, v19
	v_med3_f32 v19, v19, s79, v198
	s_waitcnt lgkmcnt(0)
	s_nop 1
	v_mov_b32_dpp v20, v19 quad_perm:[1,0,3,2] row_mask:0xf bank_mask:0xf
	v_mov_b32_e32 v21, v1
	s_waitcnt lgkmcnt(0)
	v_cvt_pk_fp8_f32 v21, v19, v20
	v_and_b32_e32 v19, 0xffff, v21
	s_nop 1
	v_mov_b32_dpp v20, v19 quad_perm:[2,3,0,1] row_mask:0xf bank_mask:0xf
	s_and_saveexec_b64 s[6:7], vcc
	s_cbranch_execz .LBB0_4395
	s_waitcnt lgkmcnt(0)
	v_lshl_or_b32 v19, v20, 16, v19
	global_store_dword v[16:17], v19, off offset:64
.LBB0_4395:
	s_or_b64 exec, exec, s[6:7]
	v_mul_f32_e32 v18, v27, v18
	v_mul_f32_e32 v18, 0x41800000, v18
	v_med3_f32 v18, v18, s79, v198
	s_nop 1
	v_mov_b32_dpp v19, v18 quad_perm:[1,0,3,2] row_mask:0xf bank_mask:0xf
	s_waitcnt lgkmcnt(1)
	v_mov_b32_e32 v20, v1
	s_waitcnt lgkmcnt(0)
	v_cvt_pk_fp8_f32 v20, v18, v19
	v_and_b32_e32 v18, 0xffff, v20
	s_nop 1
	v_mov_b32_dpp v19, v18 quad_perm:[2,3,0,1] row_mask:0xf bank_mask:0xf
	s_and_saveexec_b64 s[6:7], vcc
	s_cbranch_execz .LBB0_4397
	s_waitcnt lgkmcnt(0)
	v_lshl_or_b32 v18, v19, 16, v18
	global_store_dword v[16:17], v18, off offset:96
.LBB0_4397:
	s_or_b64 exec, exec, s[6:7]
	v_rcp_f32_e32 v16, v104
	s_waitcnt lgkmcnt(0)
	v_mov_b32_e32 v19, v1
	v_mul_f32_e32 v18, 0x3e000000, v16
	v_mul_f32_e32 v16, v76, v18
	v_mul_f32_e32 v16, 0x41800000, v16
	v_med3_f32 v16, v16, s79, v198
	s_nop 1
	v_mov_b32_dpp v17, v16 quad_perm:[1,0,3,2] row_mask:0xf bank_mask:0xf
	s_waitcnt lgkmcnt(0)
	v_cvt_pk_fp8_f32 v19, v16, v17
	v_lshlrev_b64 v[16:17], 11, v[14:15]
	v_lshl_add_u64 v[16:17], v[120:121], 0, v[16:17]
	v_lshl_add_u64 v[16:17], v[16:17], 0, s[16:17]
	v_and_b32_e32 v19, 0xffff, v19
	s_nop 1
	v_mov_b32_dpp v20, v19 quad_perm:[2,3,0,1] row_mask:0xf bank_mask:0xf
	s_and_saveexec_b64 s[6:7], vcc
	s_cbranch_execz .LBB0_4399
	s_waitcnt lgkmcnt(0)
	v_lshl_or_b32 v19, v20, 16, v19
	global_store_dword v[16:17], v19, off
.LBB0_4399:
	s_or_b64 exec, exec, s[6:7]
	v_mul_f32_e32 v19, v60, v18
	v_mul_f32_e32 v19, 0x41800000, v19
	v_med3_f32 v19, v19, s79, v198
	s_waitcnt lgkmcnt(0)
	s_nop 1
	v_mov_b32_dpp v20, v19 quad_perm:[1,0,3,2] row_mask:0xf bank_mask:0xf
	v_mov_b32_e32 v21, v1
	s_waitcnt lgkmcnt(0)
	v_cvt_pk_fp8_f32 v21, v19, v20
	v_and_b32_e32 v19, 0xffff, v21
	s_nop 1
	v_mov_b32_dpp v20, v19 quad_perm:[2,3,0,1] row_mask:0xf bank_mask:0xf
	s_and_saveexec_b64 s[6:7], vcc
	s_cbranch_execz .LBB0_4401
	s_waitcnt lgkmcnt(0)
	v_lshl_or_b32 v19, v20, 16, v19
	global_store_dword v[16:17], v19, off offset:32
.LBB0_4401:
	s_or_b64 exec, exec, s[6:7]
	v_mul_f32_e32 v19, v44, v18
	v_mul_f32_e32 v19, 0x41800000, v19
	v_med3_f32 v19, v19, s79, v198
	s_waitcnt lgkmcnt(0)
	s_nop 1
	v_mov_b32_dpp v20, v19 quad_perm:[1,0,3,2] row_mask:0xf bank_mask:0xf
	v_mov_b32_e32 v21, v1
	s_waitcnt lgkmcnt(0)
	v_cvt_pk_fp8_f32 v21, v19, v20
	v_and_b32_e32 v19, 0xffff, v21
	s_nop 1
	v_mov_b32_dpp v20, v19 quad_perm:[2,3,0,1] row_mask:0xf bank_mask:0xf
	s_and_saveexec_b64 s[6:7], vcc
	s_cbranch_execz .LBB0_4403
	s_waitcnt lgkmcnt(0)
	v_lshl_or_b32 v19, v20, 16, v19
	global_store_dword v[16:17], v19, off offset:64
; __device__ __forceinline__ int crow(int r, int hi) { return (r & 3) + 8 * (r >> 2) + 4 * hi; }
; template <int MODE>
; __device__ __forceinline__ void attn_block(const AttnArgs& a, const BlockRef& cur, const BlockRef& nxt, char* lds, Seam<MODE>& S, const int tid) {
;     ...
;     if (a.o8 != 0.f) {
;         unsigned char* Ob = (unsigned char*)a.O + (size_t)(orow_ + wid * QBLK) * ldo + hcol_; const float os = a.o8;
; #pragma unroll
;         for (int r = 0; r < 16; ++r) { const int orow = crow(r, hi);
; #pragma unroll
;             for (int d0 = 0; d0 < 4; ++d0) { const float v = __builtin_amdgcn_fmed3f(o[d0][r] * rli[r] * os, -448.f, 448.f);
;                 const float vn = __shfl_xor(v, 1);
;                 const int pk = __builtin_amdgcn_cvt_pk_fp8_f32(v, vn, 0, false) & 0xffff; const int pk2 = __shfl_xor(pk, 2);
;                 if ((r32 & 3) == 0) *(unsigned*)(Ob + (size_t)orow * ldo + d0 * 32 + r32) = (unsigned)pk | ((unsigned)pk2 << 16); } }
.LBB0_4403:
	s_or_b64 exec, exec, s[6:7]
	v_mul_f32_e32 v18, v28, v18
	v_mul_f32_e32 v18, 0x41800000, v18
	v_med3_f32 v18, v18, s79, v198
	s_nop 1
	v_mov_b32_dpp v19, v18 quad_perm:[1,0,3,2] row_mask:0xf bank_mask:0xf
	s_waitcnt lgkmcnt(1)
	v_mov_b32_e32 v20, v1
	s_waitcnt lgkmcnt(0)
	v_cvt_pk_fp8_f32 v20, v18, v19
	v_and_b32_e32 v18, 0xffff, v20
	s_nop 1
	v_mov_b32_dpp v19, v18 quad_perm:[2,3,0,1] row_mask:0xf bank_mask:0xf
	s_and_saveexec_b64 s[6:7], vcc
	s_cbranch_execz .LBB0_4405
	s_waitcnt lgkmcnt(0)
	v_lshl_or_b32 v18, v19, 16, v18
	global_store_dword v[16:17], v18, off offset:96
.LBB0_4405:
	s_or_b64 exec, exec, s[6:7]
	v_rcp_f32_e32 v16, v105
	s_waitcnt lgkmcnt(0)
	v_mov_b32_e32 v19, v1
	v_mul_f32_e32 v18, 0x3e000000, v16
	v_mul_f32_e32 v16, v77, v18
	v_mul_f32_e32 v16, 0x41800000, v16
	v_med3_f32 v16, v16, s79, v198
	s_nop 1
	v_mov_b32_dpp v17, v16 quad_perm:[1,0,3,2] row_mask:0xf bank_mask:0xf
	s_waitcnt lgkmcnt(0)
	v_cvt_pk_fp8_f32 v19, v16, v17
	v_lshlrev_b64 v[16:17], 11, v[14:15]
	v_lshl_add_u64 v[16:17], v[120:121], 0, v[16:17]
	v_lshl_add_u64 v[16:17], v[16:17], 0, s[18:19]
	v_and_b32_e32 v19, 0xffff, v19
	s_nop 1
	v_mov_b32_dpp v20, v19 quad_perm:[2,3,0,1] row_mask:0xf bank_mask:0xf
	s_and_saveexec_b64 s[6:7], vcc
	s_cbranch_execz .LBB0_4407
	s_waitcnt lgkmcnt(0)
	v_lshl_or_b32 v19, v20, 16, v19
	global_store_dword v[16:17], v19, off
.LBB0_4407:
	s_or_b64 exec, exec, s[6:7]
	v_mul_f32_e32 v19, v61, v18
	v_mul_f32_e32 v19, 0x41800000, v19
	v_med3_f32 v19, v19, s79, v198
	s_waitcnt lgkmcnt(0)
	s_nop 1
	v_mov_b32_dpp v20, v19 quad_perm:[1,0,3,2] row_mask:0xf bank_mask:0xf
	v_mov_b32_e32 v21, v1
	s_waitcnt lgkmcnt(0)
	v_cvt_pk_fp8_f32 v21, v19, v20
	v_and_b32_e32 v19, 0xffff, v21
	s_nop 1
	v_mov_b32_dpp v20, v19 quad_perm:[2,3,0,1] row_mask:0xf bank_mask:0xf
	s_and_saveexec_b64 s[6:7], vcc
	s_cbranch_execz .LBB0_4409
	s_waitcnt lgkmcnt(0)
	v_lshl_or_b32 v19, v20, 16, v19
	global_store_dword v[16:17], v19, off offset:32
.LBB0_4409:
	s_or_b64 exec, exec, s[6:7]
	v_mul_f32_e32 v19, v45, v18
	v_mul_f32_e32 v19, 0x41800000, v19
	v_med3_f32 v19, v19, s79, v198
	s_waitcnt lgkmcnt(0)
	s_nop 1
	v_mov_b32_dpp v20, v19 quad_perm:[1,0,3,2] row_mask:0xf bank_mask:0xf
	v_mov_b32_e32 v21, v1
	s_waitcnt lgkmcnt(0)
	v_cvt_pk_fp8_f32 v21, v19, v20
	v_and_b32_e32 v19, 0xffff, v21
	s_nop 1
	v_mov_b32_dpp v20, v19 quad_perm:[2,3,0,1] row_mask:0xf bank_mask:0xf
	s_and_saveexec_b64 s[6:7], vcc
	s_cbranch_execz .LBB0_4411
	s_waitcnt lgkmcnt(0)
	v_lshl_or_b32 v19, v20, 16, v19
	global_store_dword v[16:17], v19, off offset:64
.LBB0_4411:
	s_or_b64 exec, exec, s[6:7]
	v_mul_f32_e32 v18, v29, v18
	v_mul_f32_e32 v18, 0x41800000, v18
	v_med3_f32 v18, v18, s79, v198
	s_nop 1
	v_mov_b32_dpp v19, v18 quad_perm:[1,0,3,2] row_mask:0xf bank_mask:0xf
	s_waitcnt lgkmcnt(1)
	v_mov_b32_e32 v20, v1
	s_waitcnt lgkmcnt(0)
	v_cvt_pk_fp8_f32 v20, v18, v19
	v_and_b32_e32 v18, 0xffff, v20
	s_nop 1
	v_mov_b32_dpp v19, v18 quad_perm:[2,3,0,1] row_mask:0xf bank_mask:0xf
	s_and_saveexec_b64 s[6:7], vcc
	s_cbranch_execz .LBB0_4413
	s_waitcnt lgkmcnt(0)
	v_lshl_or_b32 v18, v19, 16, v18
	global_store_dword v[16:17], v18, off offset:96
.LBB0_4413:
	s_or_b64 exec, exec, s[6:7]
	v_rcp_f32_e32 v16, v106
	s_waitcnt lgkmcnt(0)
	v_mov_b32_e32 v19, v1
	v_mul_f32_e32 v18, 0x3e000000, v16
	v_mul_f32_e32 v16, v78, v18
	v_mul_f32_e32 v16, 0x41800000, v16
	v_med3_f32 v16, v16, s79, v198
	s_nop 1
	v_mov_b32_dpp v17, v16 quad_perm:[1,0,3,2] row_mask:0xf bank_mask:0xf
	s_waitcnt lgkmcnt(0)
	v_cvt_pk_fp8_f32 v19, v16, v17
	v_lshlrev_b64 v[16:17], 11, v[14:15]
	v_lshl_add_u64 v[16:17], v[120:121], 0, v[16:17]
	v_lshl_add_u64 v[16:17], v[16:17], 0, s[20:21]
	v_and_b32_e32 v19, 0xffff, v19
	s_nop 1
	v_mov_b32_dpp v20, v19 quad_perm:[2,3,0,1] row_mask:0xf bank_mask:0xf
	s_and_saveexec_b64 s[6:7], vcc
	s_cbranch_execz .LBB0_4415
	s_waitcnt lgkmcnt(0)
	v_lshl_or_b32 v19, v20, 16, v19
	global_store_dword v[16:17], v19, off
; __device__ __forceinline__ int crow(int r, int hi) { return (r & 3) + 8 * (r >> 2) + 4 * hi; }
; template <int MODE>
; __device__ __forceinline__ void attn_block(const AttnArgs& a, const BlockRef& cur, const BlockRef& nxt, char* lds, Seam<MODE>& S, const int tid) {
;     ...
;     if (a.o8 != 0.f) {
;         unsigned char* Ob = (unsigned char*)a.O + (size_t)(orow_ + wid * QBLK) * ldo + hcol_; const float os = a.o8;
; #pragma unroll
;         for (int r = 0; r < 16; ++r) { const int orow = crow(r, hi);
; #pragma unroll
;             for (int d0 = 0; d0 < 4; ++d0) { const float v = __builtin_amdgcn_fmed3f(o[d0][r] * rli[r] * os, -448.f, 448.f);
;                 const float vn = __shfl_xor(v, 1);
;                 const int pk = __builtin_amdgcn_cvt_pk_fp8_f32(v, vn, 0, false) & 0xffff; const int pk2 = __shfl_xor(pk, 2);
;                 if ((r32 & 3) == 0) *(unsigned*)(Ob + (size_t)orow * ldo + d0 * 32 + r32) = (unsigned)pk | ((unsigned)pk2 << 16); } }
.LBB0_4415:
	s_or_b64 exec, exec, s[6:7]
	v_mul_f32_e32 v19, v62, v18
	v_mul_f32_e32 v19, 0x41800000, v19
	v_med3_f32 v19, v19, s79, v198
	s_waitcnt lgkmcnt(0)
	s_nop 1
	v_mov_b32_dpp v20, v19 quad_perm:[1,0,3,2] row_mask:0xf bank_mask:0xf
	v_mov_b32_e32 v21, v1
	s_waitcnt lgkmcnt(0)
	v_cvt_pk_fp8_f32 v21, v19, v20
	v_and_b32_e32 v19, 0xffff, v21
	s_nop 1
	v_mov_b32_dpp v20, v19 quad_perm:[2,3,0,1] row_mask:0xf bank_mask:0xf
	s_and_saveexec_b64 s[6:7], vcc
	s_cbranch_execz .LBB0_4417
	s_waitcnt lgkmcnt(0)
	v_lshl_or_b32 v19, v20, 16, v19
	global_store_dword v[16:17], v19, off offset:32
.LBB0_4417:
	s_or_b64 exec, exec, s[6:7]
	v_mul_f32_e32 v19, v46, v18
	v_mul_f32_e32 v19, 0x41800000, v19
	v_med3_f32 v19, v19, s79, v198
	s_waitcnt lgkmcnt(0)
	s_nop 1
	v_mov_b32_dpp v20, v19 quad_perm:[1,0,3,2] row_mask:0xf bank_mask:0xf
	v_mov_b32_e32 v21, v1
	s_waitcnt lgkmcnt(0)
	v_cvt_pk_fp8_f32 v21, v19, v20
	v_and_b32_e32 v19, 0xffff, v21
	s_nop 1
	v_mov_b32_dpp v20, v19 quad_perm:[2,3,0,1] row_mask:0xf bank_mask:0xf
	s_and_saveexec_b64 s[6:7], vcc
	s_cbranch_execz .LBB0_4419
	s_waitcnt lgkmcnt(0)
	v_lshl_or_b32 v19, v20, 16, v19
	global_store_dword v[16:17], v19, off offset:64
.LBB0_4419:
	s_or_b64 exec, exec, s[6:7]
	v_mul_f32_e32 v18, v30, v18
	v_mul_f32_e32 v18, 0x41800000, v18
	v_med3_f32 v18, v18, s79, v198
	s_nop 1
	v_mov_b32_dpp v19, v18 quad_perm:[1,0,3,2] row_mask:0xf bank_mask:0xf
	s_waitcnt lgkmcnt(1)
	v_mov_b32_e32 v20, v1
	s_waitcnt lgkmcnt(0)
	v_cvt_pk_fp8_f32 v20, v18, v19
	v_and_b32_e32 v18, 0xffff, v20
	s_nop 1
	v_mov_b32_dpp v19, v18 quad_perm:[2,3,0,1] row_mask:0xf bank_mask:0xf
	s_and_saveexec_b64 s[6:7], vcc
	s_cbranch_execz .LBB0_4421
	s_waitcnt lgkmcnt(0)
	v_lshl_or_b32 v18, v19, 16, v18
	global_store_dword v[16:17], v18, off offset:96
.LBB0_4421:
	s_or_b64 exec, exec, s[6:7]
	v_rcp_f32_e32 v16, v107
	s_waitcnt lgkmcnt(0)
	v_mov_b32_e32 v19, v1
	v_lshlrev_b64 v[14:15], 11, v[14:15]
	v_lshl_add_u64 v[14:15], v[120:121], 0, v[14:15]
	v_mul_f32_e32 v16, 0x3e000000, v16
	v_mul_f32_e32 v17, v79, v16
	v_mul_f32_e32 v17, 0x41800000, v17
	v_med3_f32 v17, v17, s79, v198
	s_nop 1
	v_mov_b32_dpp v18, v17 quad_perm:[1,0,3,2] row_mask:0xf bank_mask:0xf
	v_lshl_add_u64 v[14:15], v[14:15], 0, s[24:25]
	s_waitcnt lgkmcnt(0)
	v_cvt_pk_fp8_f32 v19, v17, v18
	v_and_b32_e32 v17, 0xffff, v19
	s_nop 1
	v_mov_b32_dpp v18, v17 quad_perm:[2,3,0,1] row_mask:0xf bank_mask:0xf
	s_and_saveexec_b64 s[6:7], vcc
	s_cbranch_execz .LBB0_4423
	s_waitcnt lgkmcnt(0)
	v_lshl_or_b32 v17, v18, 16, v17
	global_store_dword v[14:15], v17, off
.LBB0_4423:
	s_or_b64 exec, exec, s[6:7]
	v_mul_f32_e32 v17, v63, v16
	v_mul_f32_e32 v17, 0x41800000, v17
	v_med3_f32 v17, v17, s79, v198
	s_waitcnt lgkmcnt(0)
	s_nop 1
	v_mov_b32_dpp v18, v17 quad_perm:[1,0,3,2] row_mask:0xf bank_mask:0xf
	v_mov_b32_e32 v19, v1
	s_waitcnt lgkmcnt(0)
	v_cvt_pk_fp8_f32 v19, v17, v18
	v_and_b32_e32 v17, 0xffff, v19
	s_nop 1
	v_mov_b32_dpp v18, v17 quad_perm:[2,3,0,1] row_mask:0xf bank_mask:0xf
	s_and_saveexec_b64 s[6:7], vcc
	s_cbranch_execz .LBB0_4425
	s_waitcnt lgkmcnt(0)
	v_lshl_or_b32 v17, v18, 16, v17
	global_store_dword v[14:15], v17, off offset:32
.LBB0_4425:
	s_or_b64 exec, exec, s[6:7]
	v_mul_f32_e32 v17, v47, v16
	v_mul_f32_e32 v17, 0x41800000, v17
	v_med3_f32 v17, v17, s79, v198
	s_waitcnt lgkmcnt(0)
	s_nop 1
	v_mov_b32_dpp v18, v17 quad_perm:[1,0,3,2] row_mask:0xf bank_mask:0xf
	v_mov_b32_e32 v19, v1
	s_waitcnt lgkmcnt(0)
	v_cvt_pk_fp8_f32 v19, v17, v18
	v_and_b32_e32 v17, 0xffff, v19
	s_nop 1
	v_mov_b32_dpp v18, v17 quad_perm:[2,3,0,1] row_mask:0xf bank_mask:0xf
	s_and_saveexec_b64 s[6:7], vcc
	s_cbranch_execz .LBB0_4427
	s_waitcnt lgkmcnt(0)
	v_lshl_or_b32 v17, v18, 16, v17
	global_store_dword v[14:15], v17, off offset:64
.LBB0_4427:
	s_or_b64 exec, exec, s[6:7]
	v_mul_f32_e32 v16, v31, v16
	v_mul_f32_e32 v16, 0x41800000, v16
	v_med3_f32 v16, v16, s79, v198
	s_nop 1
	v_mov_b32_dpp v0, v16 quad_perm:[1,0,3,2] row_mask:0xf bank_mask:0xf
	v_mov_b32_e32 v17, v1
	s_waitcnt lgkmcnt(0)
	v_cvt_pk_fp8_f32 v17, v16, v0
	v_and_b32_e32 v0, 0xffff, v17
	s_nop 1
	v_mov_b32_dpp v16, v0 quad_perm:[2,3,0,1] row_mask:0xf bank_mask:0xf
	s_and_saveexec_b64 s[6:7], vcc
	s_cbranch_execz .LBB0_4230
	s_waitcnt lgkmcnt(0)
	v_lshl_or_b32 v0, v16, 16, v0
	global_store_dword v[14:15], v0, off offset:96
	s_branch .LBB0_4230
